# pair GEMM loops: read-phase priority 3 + per-fragment-row counted LDS waits (MFMAs start as soon as their operands land)
# speedup vs baseline: 1.0153x; 1.0003x over previous
.Lfin3_loop:
	s_setprio 3
	v_add_u32_e32 v234, s22, v232
	v_add_u32_e32 v236, s28, v232
	v_add_u32_e32 v235, s22, v233
	v_add_u32_e32 v237, s28, v233
	ds_read_b128 v[136:139], v234
	ds_read_b128 v[188:191], v236
	ds_read_b128 v[196:199], v236 offset:2048
	ds_read_b128 v[200:203], v236 offset:4096
	ds_read_b128 v[204:207], v236 offset:6144
	ds_read_b128 v[140:143], v234 offset:2048
	ds_read_b128 v[144:147], v234 offset:4096
	ds_read_b128 v[148:151], v234 offset:6144
	ds_read_b128 v[172:175], v235
	ds_read_b128 v[212:215], v237
	ds_read_b128 v[216:219], v237 offset:2048
	ds_read_b128 v[220:223], v237 offset:4096
	ds_read_b128 v[224:227], v237 offset:6144
	ds_read_b128 v[176:179], v235 offset:2048
	ds_read_b128 v[180:183], v235 offset:4096
	ds_read_b128 v[184:187], v235 offset:6144
	s_add_i32 m0, s51, 0xc000
	s_nop 0
	global_load_lds_dwordx4 v228, s[44:45]
	s_add_i32 m0, s51, 0xc400
	s_nop 0
	global_load_lds_dwordx4 v230, s[44:45]
	s_add_i32 m0, s51, 0xe000
	s_nop 0
	global_load_lds_dwordx4 v229, s[44:45]
	s_add_i32 m0, s51, 0xe400
	s_nop 0
	global_load_lds_dwordx4 v231, s[44:45]
	s_add_i32 m0, s51, 0x10000
	s_nop 0
	global_load_lds_dwordx4 v228, s[46:47]
	s_add_i32 m0, s51, 0x10400
	s_nop 0
	global_load_lds_dwordx4 v230, s[46:47]
	s_waitcnt lgkmcnt(11)
	s_setprio 1
	v_mfma_f32_16x16x32_bf16 v[2:5], v[136:139], v[188:191], v[2:5]
	v_mfma_f32_16x16x32_bf16 v[6:9], v[136:139], v[196:199], v[6:9]
	v_mfma_f32_16x16x32_bf16 v[10:13], v[136:139], v[200:203], v[10:13]
	v_mfma_f32_16x16x32_bf16 v[14:17], v[136:139], v[204:207], v[14:17]
	s_waitcnt lgkmcnt(10)
	v_mfma_f32_16x16x32_bf16 v[18:21], v[140:143], v[188:191], v[18:21]
	v_mfma_f32_16x16x32_bf16 v[22:25], v[140:143], v[196:199], v[22:25]
	v_mfma_f32_16x16x32_bf16 v[26:29], v[140:143], v[200:203], v[26:29]
	v_mfma_f32_16x16x32_bf16 v[30:33], v[140:143], v[204:207], v[30:33]
	s_waitcnt lgkmcnt(9)
	v_mfma_f32_16x16x32_bf16 v[34:37], v[144:147], v[188:191], v[34:37]
	v_mfma_f32_16x16x32_bf16 v[38:41], v[144:147], v[196:199], v[38:41]
	v_mfma_f32_16x16x32_bf16 v[42:45], v[144:147], v[200:203], v[42:45]
	v_mfma_f32_16x16x32_bf16 v[46:49], v[144:147], v[204:207], v[46:49]
	s_waitcnt lgkmcnt(8)
	v_mfma_f32_16x16x32_bf16 v[50:53], v[148:151], v[188:191], v[50:53]
	v_mfma_f32_16x16x32_bf16 v[54:57], v[148:151], v[196:199], v[54:57]
	v_mfma_f32_16x16x32_bf16 v[58:61], v[148:151], v[200:203], v[58:61]
	v_mfma_f32_16x16x32_bf16 v[62:65], v[148:151], v[204:207], v[62:65]
	s_waitcnt lgkmcnt(3)
	v_mfma_f32_16x16x32_bf16 v[2:5], v[172:175], v[212:215], v[2:5]
	v_mfma_f32_16x16x32_bf16 v[6:9], v[172:175], v[216:219], v[6:9]
	v_mfma_f32_16x16x32_bf16 v[10:13], v[172:175], v[220:223], v[10:13]
	v_mfma_f32_16x16x32_bf16 v[14:17], v[172:175], v[224:227], v[14:17]
	s_waitcnt lgkmcnt(2)
	v_mfma_f32_16x16x32_bf16 v[18:21], v[176:179], v[212:215], v[18:21]
	v_mfma_f32_16x16x32_bf16 v[22:25], v[176:179], v[216:219], v[22:25]
	v_mfma_f32_16x16x32_bf16 v[26:29], v[176:179], v[220:223], v[26:29]
	v_mfma_f32_16x16x32_bf16 v[30:33], v[176:179], v[224:227], v[30:33]
	s_waitcnt lgkmcnt(1)
	v_mfma_f32_16x16x32_bf16 v[34:37], v[180:183], v[212:215], v[34:37]
	v_mfma_f32_16x16x32_bf16 v[38:41], v[180:183], v[216:219], v[38:41]
	v_mfma_f32_16x16x32_bf16 v[42:45], v[180:183], v[220:223], v[42:45]
	v_mfma_f32_16x16x32_bf16 v[46:49], v[180:183], v[224:227], v[46:49]
	s_waitcnt lgkmcnt(0)
	v_mfma_f32_16x16x32_bf16 v[50:53], v[184:187], v[212:215], v[50:53]
	v_mfma_f32_16x16x32_bf16 v[54:57], v[184:187], v[216:219], v[54:57]
	v_mfma_f32_16x16x32_bf16 v[58:61], v[184:187], v[220:223], v[58:61]
	v_mfma_f32_16x16x32_bf16 v[62:65], v[184:187], v[224:227], v[62:65]
	s_setprio 0
	s_waitcnt vmcnt(6)
	s_barrier
	s_setprio 3
	v_add_u32_e32 v236, s40, v232
	v_add_u32_e32 v237, s40, v233
	ds_read_b128 v[188:191], v236
	ds_read_b128 v[196:199], v236 offset:2048
	ds_read_b128 v[200:203], v236 offset:4096
	ds_read_b128 v[204:207], v236 offset:6144
	ds_read_b128 v[212:215], v237
	ds_read_b128 v[216:219], v237 offset:2048
	ds_read_b128 v[220:223], v237 offset:4096
	ds_read_b128 v[224:227], v237 offset:6144
	s_mov_b32 m0, s51
	s_nop 0
	global_load_lds_dwordx4 v229, s[46:47]
	s_add_i32 m0, s51, 0x400
	s_nop 0
	global_load_lds_dwordx4 v231, s[46:47]
	s_add_i32 m0, s51, 0x2000
	s_nop 0
	global_load_lds_dwordx4 v228, s[48:49]
	s_add_i32 m0, s51, 0x2400
	s_nop 0
	global_load_lds_dwordx4 v230, s[48:49]
	s_add_i32 m0, s51, 0x4000
	s_nop 0
	global_load_lds_dwordx4 v229, s[48:49]
	s_add_i32 m0, s51, 0x4400
	s_nop 0
	global_load_lds_dwordx4 v231, s[48:49]
	s_waitcnt lgkmcnt(7)
	s_setprio 1
	v_mfma_f32_16x16x32_bf16 v[66:69], v[136:139], v[188:191], v[66:69]
	v_mfma_f32_16x16x32_bf16 v[82:85], v[140:143], v[188:191], v[82:85]
	v_mfma_f32_16x16x32_bf16 v[98:101], v[144:147], v[188:191], v[98:101]
	v_mfma_f32_16x16x32_bf16 v[114:117], v[148:151], v[188:191], v[114:117]
	s_waitcnt lgkmcnt(6)
	v_mfma_f32_16x16x32_bf16 v[70:73], v[136:139], v[196:199], v[70:73]
	v_mfma_f32_16x16x32_bf16 v[86:89], v[140:143], v[196:199], v[86:89]
	v_mfma_f32_16x16x32_bf16 v[102:105], v[144:147], v[196:199], v[102:105]
	v_mfma_f32_16x16x32_bf16 v[118:121], v[148:151], v[196:199], v[118:121]
	s_waitcnt lgkmcnt(5)
	v_mfma_f32_16x16x32_bf16 v[74:77], v[136:139], v[200:203], v[74:77]
	v_mfma_f32_16x16x32_bf16 v[90:93], v[140:143], v[200:203], v[90:93]
	v_mfma_f32_16x16x32_bf16 v[106:109], v[144:147], v[200:203], v[106:109]
	v_mfma_f32_16x16x32_bf16 v[122:125], v[148:151], v[200:203], v[122:125]
	s_waitcnt lgkmcnt(4)
	v_mfma_f32_16x16x32_bf16 v[78:81], v[136:139], v[204:207], v[78:81]
	v_mfma_f32_16x16x32_bf16 v[94:97], v[140:143], v[204:207], v[94:97]
	v_mfma_f32_16x16x32_bf16 v[110:113], v[144:147], v[204:207], v[110:113]
	v_mfma_f32_16x16x32_bf16 v[126:129], v[148:151], v[204:207], v[126:129]
	s_waitcnt lgkmcnt(3)
	v_mfma_f32_16x16x32_bf16 v[66:69], v[172:175], v[212:215], v[66:69]
	v_mfma_f32_16x16x32_bf16 v[82:85], v[176:179], v[212:215], v[82:85]
	v_mfma_f32_16x16x32_bf16 v[98:101], v[180:183], v[212:215], v[98:101]
	v_mfma_f32_16x16x32_bf16 v[114:117], v[184:187], v[212:215], v[114:117]
	s_waitcnt lgkmcnt(2)
	v_mfma_f32_16x16x32_bf16 v[70:73], v[172:175], v[216:219], v[70:73]
	v_mfma_f32_16x16x32_bf16 v[86:89], v[176:179], v[216:219], v[86:89]
	v_mfma_f32_16x16x32_bf16 v[102:105], v[180:183], v[216:219], v[102:105]
	v_mfma_f32_16x16x32_bf16 v[118:121], v[184:187], v[216:219], v[118:121]
	s_waitcnt lgkmcnt(1)
	v_mfma_f32_16x16x32_bf16 v[74:77], v[172:175], v[220:223], v[74:77]
	v_mfma_f32_16x16x32_bf16 v[90:93], v[176:179], v[220:223], v[90:93]
	v_mfma_f32_16x16x32_bf16 v[106:109], v[180:183], v[220:223], v[106:109]
	v_mfma_f32_16x16x32_bf16 v[122:125], v[184:187], v[220:223], v[122:125]
	s_waitcnt lgkmcnt(0)
	v_mfma_f32_16x16x32_bf16 v[78:81], v[172:175], v[224:227], v[78:81]
	v_mfma_f32_16x16x32_bf16 v[94:97], v[176:179], v[224:227], v[94:97]
	v_mfma_f32_16x16x32_bf16 v[110:113], v[180:183], v[224:227], v[110:113]
	v_mfma_f32_16x16x32_bf16 v[126:129], v[184:187], v[224:227], v[126:129]
	s_setprio 0
	v_add_u32_e32 v228, 0x80, v228
	v_add_u32_e32 v229, 0x80, v229
	v_add_u32_e32 v230, 0x80, v230
	v_add_u32_e32 v231, 0x80, v231
	s_waitcnt vmcnt(4)
	s_barrier
	s_setprio 3
	v_add_u32_e32 v234, s23, v232
	v_add_u32_e32 v236, s29, v232
	v_add_u32_e32 v235, s23, v233
	v_add_u32_e32 v237, s29, v233
	ds_read_b128 v[136:139], v234
	ds_read_b128 v[188:191], v236
	ds_read_b128 v[196:199], v236 offset:2048
	ds_read_b128 v[200:203], v236 offset:4096
	ds_read_b128 v[204:207], v236 offset:6144
	ds_read_b128 v[140:143], v234 offset:2048
	ds_read_b128 v[144:147], v234 offset:4096
	ds_read_b128 v[148:151], v234 offset:6144
	ds_read_b128 v[172:175], v235
	ds_read_b128 v[212:215], v237
	ds_read_b128 v[216:219], v237 offset:2048
	ds_read_b128 v[220:223], v237 offset:4096
	ds_read_b128 v[224:227], v237 offset:6144
	ds_read_b128 v[176:179], v235 offset:2048
	ds_read_b128 v[180:183], v235 offset:4096
	ds_read_b128 v[184:187], v235 offset:6144
	s_add_i32 m0, s51, 0x6000
	s_nop 0
	global_load_lds_dwordx4 v228, s[44:45]
	s_add_i32 m0, s51, 0x6400
	s_nop 0
	global_load_lds_dwordx4 v230, s[44:45]
	s_add_i32 m0, s51, 0x8000
	s_nop 0
	global_load_lds_dwordx4 v229, s[44:45]
	s_add_i32 m0, s51, 0x8400
	s_nop 0
	global_load_lds_dwordx4 v231, s[44:45]
	s_add_i32 m0, s51, 0xa000
	s_nop 0
	global_load_lds_dwordx4 v228, s[46:47]
	s_add_i32 m0, s51, 0xa400
	s_nop 0
	global_load_lds_dwordx4 v230, s[46:47]
	s_waitcnt lgkmcnt(11)
	s_setprio 1
	v_mfma_f32_16x16x32_bf16 v[2:5], v[136:139], v[188:191], v[2:5]
	v_mfma_f32_16x16x32_bf16 v[6:9], v[136:139], v[196:199], v[6:9]
	v_mfma_f32_16x16x32_bf16 v[10:13], v[136:139], v[200:203], v[10:13]
	v_mfma_f32_16x16x32_bf16 v[14:17], v[136:139], v[204:207], v[14:17]
	s_waitcnt lgkmcnt(10)
	v_mfma_f32_16x16x32_bf16 v[18:21], v[140:143], v[188:191], v[18:21]
	v_mfma_f32_16x16x32_bf16 v[22:25], v[140:143], v[196:199], v[22:25]
	v_mfma_f32_16x16x32_bf16 v[26:29], v[140:143], v[200:203], v[26:29]
	v_mfma_f32_16x16x32_bf16 v[30:33], v[140:143], v[204:207], v[30:33]
	s_waitcnt lgkmcnt(9)
	v_mfma_f32_16x16x32_bf16 v[34:37], v[144:147], v[188:191], v[34:37]
	v_mfma_f32_16x16x32_bf16 v[38:41], v[144:147], v[196:199], v[38:41]
	v_mfma_f32_16x16x32_bf16 v[42:45], v[144:147], v[200:203], v[42:45]
	v_mfma_f32_16x16x32_bf16 v[46:49], v[144:147], v[204:207], v[46:49]
	s_waitcnt lgkmcnt(8)
	v_mfma_f32_16x16x32_bf16 v[50:53], v[148:151], v[188:191], v[50:53]
	v_mfma_f32_16x16x32_bf16 v[54:57], v[148:151], v[196:199], v[54:57]
	v_mfma_f32_16x16x32_bf16 v[58:61], v[148:151], v[200:203], v[58:61]
	v_mfma_f32_16x16x32_bf16 v[62:65], v[148:151], v[204:207], v[62:65]
	s_waitcnt lgkmcnt(3)
	v_mfma_f32_16x16x32_bf16 v[2:5], v[172:175], v[212:215], v[2:5]
	v_mfma_f32_16x16x32_bf16 v[6:9], v[172:175], v[216:219], v[6:9]
	v_mfma_f32_16x16x32_bf16 v[10:13], v[172:175], v[220:223], v[10:13]
	v_mfma_f32_16x16x32_bf16 v[14:17], v[172:175], v[224:227], v[14:17]
	s_waitcnt lgkmcnt(2)
	v_mfma_f32_16x16x32_bf16 v[18:21], v[176:179], v[212:215], v[18:21]
	v_mfma_f32_16x16x32_bf16 v[22:25], v[176:179], v[216:219], v[22:25]
	v_mfma_f32_16x16x32_bf16 v[26:29], v[176:179], v[220:223], v[26:29]
	v_mfma_f32_16x16x32_bf16 v[30:33], v[176:179], v[224:227], v[30:33]
	s_waitcnt lgkmcnt(1)
	v_mfma_f32_16x16x32_bf16 v[34:37], v[180:183], v[212:215], v[34:37]
	v_mfma_f32_16x16x32_bf16 v[38:41], v[180:183], v[216:219], v[38:41]
	v_mfma_f32_16x16x32_bf16 v[42:45], v[180:183], v[220:223], v[42:45]
	v_mfma_f32_16x16x32_bf16 v[46:49], v[180:183], v[224:227], v[46:49]
	s_waitcnt lgkmcnt(0)
	v_mfma_f32_16x16x32_bf16 v[50:53], v[184:187], v[212:215], v[50:53]
	v_mfma_f32_16x16x32_bf16 v[54:57], v[184:187], v[216:219], v[54:57]
	v_mfma_f32_16x16x32_bf16 v[58:61], v[184:187], v[220:223], v[58:61]
	v_mfma_f32_16x16x32_bf16 v[62:65], v[184:187], v[224:227], v[62:65]
	s_setprio 0
	s_waitcnt vmcnt(6)
	s_barrier
	s_setprio 3
	v_add_u32_e32 v236, s41, v232
	v_add_u32_e32 v237, s41, v233
	ds_read_b128 v[188:191], v236
	ds_read_b128 v[196:199], v236 offset:2048
	ds_read_b128 v[200:203], v236 offset:4096
	ds_read_b128 v[204:207], v236 offset:6144
	ds_read_b128 v[212:215], v237
	ds_read_b128 v[216:219], v237 offset:2048
	ds_read_b128 v[220:223], v237 offset:4096
	ds_read_b128 v[224:227], v237 offset:6144
	s_add_i32 m0, s51, 0xc000
	s_nop 0
	global_load_lds_dwordx4 v229, s[46:47]
	s_add_i32 m0, s51, 0xc400
	s_nop 0
	global_load_lds_dwordx4 v231, s[46:47]
	s_add_i32 m0, s51, 0xe000
	s_nop 0
	global_load_lds_dwordx4 v228, s[48:49]
	s_add_i32 m0, s51, 0xe400
	s_nop 0
	global_load_lds_dwordx4 v230, s[48:49]
	s_add_i32 m0, s51, 0x10000
	s_nop 0
	global_load_lds_dwordx4 v229, s[48:49]
	s_add_i32 m0, s51, 0x10400
	s_nop 0
	global_load_lds_dwordx4 v231, s[48:49]
	s_waitcnt lgkmcnt(7)
	s_setprio 1
	v_mfma_f32_16x16x32_bf16 v[66:69], v[136:139], v[188:191], v[66:69]
	v_mfma_f32_16x16x32_bf16 v[82:85], v[140:143], v[188:191], v[82:85]
	v_mfma_f32_16x16x32_bf16 v[98:101], v[144:147], v[188:191], v[98:101]
	v_mfma_f32_16x16x32_bf16 v[114:117], v[148:151], v[188:191], v[114:117]
	s_waitcnt lgkmcnt(6)
	v_mfma_f32_16x16x32_bf16 v[70:73], v[136:139], v[196:199], v[70:73]
	v_mfma_f32_16x16x32_bf16 v[86:89], v[140:143], v[196:199], v[86:89]
	v_mfma_f32_16x16x32_bf16 v[102:105], v[144:147], v[196:199], v[102:105]
	v_mfma_f32_16x16x32_bf16 v[118:121], v[148:151], v[196:199], v[118:121]
	s_waitcnt lgkmcnt(5)
	v_mfma_f32_16x16x32_bf16 v[74:77], v[136:139], v[200:203], v[74:77]
	v_mfma_f32_16x16x32_bf16 v[90:93], v[140:143], v[200:203], v[90:93]
	v_mfma_f32_16x16x32_bf16 v[106:109], v[144:147], v[200:203], v[106:109]
	v_mfma_f32_16x16x32_bf16 v[122:125], v[148:151], v[200:203], v[122:125]
	s_waitcnt lgkmcnt(4)
	v_mfma_f32_16x16x32_bf16 v[78:81], v[136:139], v[204:207], v[78:81]
	v_mfma_f32_16x16x32_bf16 v[94:97], v[140:143], v[204:207], v[94:97]
	v_mfma_f32_16x16x32_bf16 v[110:113], v[144:147], v[204:207], v[110:113]
	v_mfma_f32_16x16x32_bf16 v[126:129], v[148:151], v[204:207], v[126:129]
	s_waitcnt lgkmcnt(3)
	v_mfma_f32_16x16x32_bf16 v[66:69], v[172:175], v[212:215], v[66:69]
	v_mfma_f32_16x16x32_bf16 v[82:85], v[176:179], v[212:215], v[82:85]
	v_mfma_f32_16x16x32_bf16 v[98:101], v[180:183], v[212:215], v[98:101]
	v_mfma_f32_16x16x32_bf16 v[114:117], v[184:187], v[212:215], v[114:117]
	s_waitcnt lgkmcnt(2)
	v_mfma_f32_16x16x32_bf16 v[70:73], v[172:175], v[216:219], v[70:73]
	v_mfma_f32_16x16x32_bf16 v[86:89], v[176:179], v[216:219], v[86:89]
	v_mfma_f32_16x16x32_bf16 v[102:105], v[180:183], v[216:219], v[102:105]
	v_mfma_f32_16x16x32_bf16 v[118:121], v[184:187], v[216:219], v[118:121]
	s_waitcnt lgkmcnt(1)
	v_mfma_f32_16x16x32_bf16 v[74:77], v[172:175], v[220:223], v[74:77]
	v_mfma_f32_16x16x32_bf16 v[90:93], v[176:179], v[220:223], v[90:93]
	v_mfma_f32_16x16x32_bf16 v[106:109], v[180:183], v[220:223], v[106:109]
	v_mfma_f32_16x16x32_bf16 v[122:125], v[184:187], v[220:223], v[122:125]
	s_waitcnt lgkmcnt(0)
	v_mfma_f32_16x16x32_bf16 v[78:81], v[172:175], v[224:227], v[78:81]
	v_mfma_f32_16x16x32_bf16 v[94:97], v[176:179], v[224:227], v[94:97]
	v_mfma_f32_16x16x32_bf16 v[110:113], v[180:183], v[224:227], v[110:113]
	v_mfma_f32_16x16x32_bf16 v[126:129], v[184:187], v[224:227], v[126:129]
	s_setprio 0
	v_add_u32_e32 v228, 0x80, v228
	v_add_u32_e32 v229, 0x80, v229
	v_add_u32_e32 v230, 0x80, v230
	v_add_u32_e32 v231, 0x80, v231
	s_waitcnt vmcnt(4)
	s_barrier
	s_setprio 3
	v_add_u32_e32 v234, s24, v232
	v_add_u32_e32 v236, s30, v232
	v_add_u32_e32 v235, s24, v233
	v_add_u32_e32 v237, s30, v233
	ds_read_b128 v[136:139], v234
	ds_read_b128 v[188:191], v236
	ds_read_b128 v[196:199], v236 offset:2048
	ds_read_b128 v[200:203], v236 offset:4096
	ds_read_b128 v[204:207], v236 offset:6144
	ds_read_b128 v[140:143], v234 offset:2048
	ds_read_b128 v[144:147], v234 offset:4096
	ds_read_b128 v[148:151], v234 offset:6144
	ds_read_b128 v[172:175], v235
	ds_read_b128 v[212:215], v237
	ds_read_b128 v[216:219], v237 offset:2048
	ds_read_b128 v[220:223], v237 offset:4096
	ds_read_b128 v[224:227], v237 offset:6144
	ds_read_b128 v[176:179], v235 offset:2048
	ds_read_b128 v[180:183], v235 offset:4096
	ds_read_b128 v[184:187], v235 offset:6144
	s_mov_b32 m0, s51
	s_nop 0
	global_load_lds_dwordx4 v228, s[44:45]
	s_add_i32 m0, s51, 0x400
	s_nop 0
	global_load_lds_dwordx4 v230, s[44:45]
	s_add_i32 m0, s51, 0x2000
	s_nop 0
	global_load_lds_dwordx4 v229, s[44:45]
	s_add_i32 m0, s51, 0x2400
	s_nop 0
	global_load_lds_dwordx4 v231, s[44:45]
	s_add_i32 m0, s51, 0x4000
	s_nop 0
	global_load_lds_dwordx4 v228, s[46:47]
	s_add_i32 m0, s51, 0x4400
	s_nop 0
	global_load_lds_dwordx4 v230, s[46:47]
	s_waitcnt lgkmcnt(11)
	s_setprio 1
	v_mfma_f32_16x16x32_bf16 v[2:5], v[136:139], v[188:191], v[2:5]
	v_mfma_f32_16x16x32_bf16 v[6:9], v[136:139], v[196:199], v[6:9]
	v_mfma_f32_16x16x32_bf16 v[10:13], v[136:139], v[200:203], v[10:13]
	v_mfma_f32_16x16x32_bf16 v[14:17], v[136:139], v[204:207], v[14:17]
	s_waitcnt lgkmcnt(10)
	v_mfma_f32_16x16x32_bf16 v[18:21], v[140:143], v[188:191], v[18:21]
	v_mfma_f32_16x16x32_bf16 v[22:25], v[140:143], v[196:199], v[22:25]
	v_mfma_f32_16x16x32_bf16 v[26:29], v[140:143], v[200:203], v[26:29]
	v_mfma_f32_16x16x32_bf16 v[30:33], v[140:143], v[204:207], v[30:33]
	s_waitcnt lgkmcnt(9)
	v_mfma_f32_16x16x32_bf16 v[34:37], v[144:147], v[188:191], v[34:37]
	v_mfma_f32_16x16x32_bf16 v[38:41], v[144:147], v[196:199], v[38:41]
	v_mfma_f32_16x16x32_bf16 v[42:45], v[144:147], v[200:203], v[42:45]
	v_mfma_f32_16x16x32_bf16 v[46:49], v[144:147], v[204:207], v[46:49]
	s_waitcnt lgkmcnt(8)
	v_mfma_f32_16x16x32_bf16 v[50:53], v[148:151], v[188:191], v[50:53]
	v_mfma_f32_16x16x32_bf16 v[54:57], v[148:151], v[196:199], v[54:57]
	v_mfma_f32_16x16x32_bf16 v[58:61], v[148:151], v[200:203], v[58:61]
	v_mfma_f32_16x16x32_bf16 v[62:65], v[148:151], v[204:207], v[62:65]
	s_waitcnt lgkmcnt(3)
	v_mfma_f32_16x16x32_bf16 v[2:5], v[172:175], v[212:215], v[2:5]
	v_mfma_f32_16x16x32_bf16 v[6:9], v[172:175], v[216:219], v[6:9]
	v_mfma_f32_16x16x32_bf16 v[10:13], v[172:175], v[220:223], v[10:13]
	v_mfma_f32_16x16x32_bf16 v[14:17], v[172:175], v[224:227], v[14:17]
	s_waitcnt lgkmcnt(2)
	v_mfma_f32_16x16x32_bf16 v[18:21], v[176:179], v[212:215], v[18:21]
	v_mfma_f32_16x16x32_bf16 v[22:25], v[176:179], v[216:219], v[22:25]
	v_mfma_f32_16x16x32_bf16 v[26:29], v[176:179], v[220:223], v[26:29]
	v_mfma_f32_16x16x32_bf16 v[30:33], v[176:179], v[224:227], v[30:33]
	s_waitcnt lgkmcnt(1)
	v_mfma_f32_16x16x32_bf16 v[34:37], v[180:183], v[212:215], v[34:37]
	v_mfma_f32_16x16x32_bf16 v[38:41], v[180:183], v[216:219], v[38:41]
	v_mfma_f32_16x16x32_bf16 v[42:45], v[180:183], v[220:223], v[42:45]
	v_mfma_f32_16x16x32_bf16 v[46:49], v[180:183], v[224:227], v[46:49]
	s_waitcnt lgkmcnt(0)
	v_mfma_f32_16x16x32_bf16 v[50:53], v[184:187], v[212:215], v[50:53]
	v_mfma_f32_16x16x32_bf16 v[54:57], v[184:187], v[216:219], v[54:57]
	v_mfma_f32_16x16x32_bf16 v[58:61], v[184:187], v[220:223], v[58:61]
	v_mfma_f32_16x16x32_bf16 v[62:65], v[184:187], v[224:227], v[62:65]
	s_setprio 0
	s_waitcnt vmcnt(6)
	s_barrier
	s_setprio 3
	v_add_u32_e32 v236, s42, v232
	v_add_u32_e32 v237, s42, v233
	ds_read_b128 v[188:191], v236
	ds_read_b128 v[196:199], v236 offset:2048
	ds_read_b128 v[200:203], v236 offset:4096
	ds_read_b128 v[204:207], v236 offset:6144
	ds_read_b128 v[212:215], v237
	ds_read_b128 v[216:219], v237 offset:2048
	ds_read_b128 v[220:223], v237 offset:4096
	ds_read_b128 v[224:227], v237 offset:6144
	s_add_i32 m0, s51, 0x6000
	s_nop 0
	global_load_lds_dwordx4 v229, s[46:47]
	s_add_i32 m0, s51, 0x6400
	s_nop 0
	global_load_lds_dwordx4 v231, s[46:47]
	s_add_i32 m0, s51, 0x8000
	s_nop 0
	global_load_lds_dwordx4 v228, s[48:49]
	s_add_i32 m0, s51, 0x8400
	s_nop 0
	global_load_lds_dwordx4 v230, s[48:49]
	s_add_i32 m0, s51, 0xa000
	s_nop 0
	global_load_lds_dwordx4 v229, s[48:49]
	s_add_i32 m0, s51, 0xa400
	s_nop 0
	global_load_lds_dwordx4 v231, s[48:49]
	s_waitcnt lgkmcnt(7)
	s_setprio 1
	v_mfma_f32_16x16x32_bf16 v[66:69], v[136:139], v[188:191], v[66:69]
	v_mfma_f32_16x16x32_bf16 v[82:85], v[140:143], v[188:191], v[82:85]
	v_mfma_f32_16x16x32_bf16 v[98:101], v[144:147], v[188:191], v[98:101]
	v_mfma_f32_16x16x32_bf16 v[114:117], v[148:151], v[188:191], v[114:117]
	s_waitcnt lgkmcnt(6)
	v_mfma_f32_16x16x32_bf16 v[70:73], v[136:139], v[196:199], v[70:73]
	v_mfma_f32_16x16x32_bf16 v[86:89], v[140:143], v[196:199], v[86:89]
	v_mfma_f32_16x16x32_bf16 v[102:105], v[144:147], v[196:199], v[102:105]
	v_mfma_f32_16x16x32_bf16 v[118:121], v[148:151], v[196:199], v[118:121]
	s_waitcnt lgkmcnt(5)
	v_mfma_f32_16x16x32_bf16 v[74:77], v[136:139], v[200:203], v[74:77]
	v_mfma_f32_16x16x32_bf16 v[90:93], v[140:143], v[200:203], v[90:93]
	v_mfma_f32_16x16x32_bf16 v[106:109], v[144:147], v[200:203], v[106:109]
	v_mfma_f32_16x16x32_bf16 v[122:125], v[148:151], v[200:203], v[122:125]
	s_waitcnt lgkmcnt(4)
	v_mfma_f32_16x16x32_bf16 v[78:81], v[136:139], v[204:207], v[78:81]
	v_mfma_f32_16x16x32_bf16 v[94:97], v[140:143], v[204:207], v[94:97]
	v_mfma_f32_16x16x32_bf16 v[110:113], v[144:147], v[204:207], v[110:113]
	v_mfma_f32_16x16x32_bf16 v[126:129], v[148:151], v[204:207], v[126:129]
	s_waitcnt lgkmcnt(3)
	v_mfma_f32_16x16x32_bf16 v[66:69], v[172:175], v[212:215], v[66:69]
	v_mfma_f32_16x16x32_bf16 v[82:85], v[176:179], v[212:215], v[82:85]
	v_mfma_f32_16x16x32_bf16 v[98:101], v[180:183], v[212:215], v[98:101]
	v_mfma_f32_16x16x32_bf16 v[114:117], v[184:187], v[212:215], v[114:117]
	s_waitcnt lgkmcnt(2)
	v_mfma_f32_16x16x32_bf16 v[70:73], v[172:175], v[216:219], v[70:73]
	v_mfma_f32_16x16x32_bf16 v[86:89], v[176:179], v[216:219], v[86:89]
	v_mfma_f32_16x16x32_bf16 v[102:105], v[180:183], v[216:219], v[102:105]
	v_mfma_f32_16x16x32_bf16 v[118:121], v[184:187], v[216:219], v[118:121]
	s_waitcnt lgkmcnt(1)
	v_mfma_f32_16x16x32_bf16 v[74:77], v[172:175], v[220:223], v[74:77]
	v_mfma_f32_16x16x32_bf16 v[90:93], v[176:179], v[220:223], v[90:93]
	v_mfma_f32_16x16x32_bf16 v[106:109], v[180:183], v[220:223], v[106:109]
	v_mfma_f32_16x16x32_bf16 v[122:125], v[184:187], v[220:223], v[122:125]
	s_waitcnt lgkmcnt(0)
	v_mfma_f32_16x16x32_bf16 v[78:81], v[172:175], v[224:227], v[78:81]
	v_mfma_f32_16x16x32_bf16 v[94:97], v[176:179], v[224:227], v[94:97]
	v_mfma_f32_16x16x32_bf16 v[110:113], v[180:183], v[224:227], v[110:113]
	v_mfma_f32_16x16x32_bf16 v[126:129], v[184:187], v[224:227], v[126:129]
	s_setprio 0
	v_add_u32_e32 v228, 0x80, v228
	v_add_u32_e32 v229, 0x80, v229
	v_add_u32_e32 v230, 0x80, v230
	v_add_u32_e32 v231, 0x80, v231
	s_waitcnt vmcnt(4)
	s_barrier
	s_add_i32 s52, s52, 1
	s_cmp_lt_u32 s52, 29
	s_cbranch_scc1 .Lfin3_loop
	s_setprio 3
	v_add_u32_e32 v234, s22, v232
	v_add_u32_e32 v236, s28, v232
	v_add_u32_e32 v235, s22, v233
	v_add_u32_e32 v237, s28, v233
	ds_read_b128 v[136:139], v234
	ds_read_b128 v[188:191], v236
	ds_read_b128 v[196:199], v236 offset:2048
	ds_read_b128 v[200:203], v236 offset:4096
	ds_read_b128 v[204:207], v236 offset:6144
	ds_read_b128 v[140:143], v234 offset:2048
	ds_read_b128 v[144:147], v234 offset:4096
	ds_read_b128 v[148:151], v234 offset:6144
	ds_read_b128 v[172:175], v235
	ds_read_b128 v[212:215], v237
	ds_read_b128 v[216:219], v237 offset:2048
	ds_read_b128 v[220:223], v237 offset:4096
	ds_read_b128 v[224:227], v237 offset:6144
	ds_read_b128 v[176:179], v235 offset:2048
	ds_read_b128 v[180:183], v235 offset:4096
	ds_read_b128 v[184:187], v235 offset:6144
	s_waitcnt lgkmcnt(11)
	s_setprio 1
	v_mfma_f32_16x16x32_bf16 v[2:5], v[136:139], v[188:191], v[2:5]
	v_mfma_f32_16x16x32_bf16 v[6:9], v[136:139], v[196:199], v[6:9]
	v_mfma_f32_16x16x32_bf16 v[10:13], v[136:139], v[200:203], v[10:13]
	v_mfma_f32_16x16x32_bf16 v[14:17], v[136:139], v[204:207], v[14:17]
	s_waitcnt lgkmcnt(10)
	v_mfma_f32_16x16x32_bf16 v[18:21], v[140:143], v[188:191], v[18:21]
	v_mfma_f32_16x16x32_bf16 v[22:25], v[140:143], v[196:199], v[22:25]
	v_mfma_f32_16x16x32_bf16 v[26:29], v[140:143], v[200:203], v[26:29]
	v_mfma_f32_16x16x32_bf16 v[30:33], v[140:143], v[204:207], v[30:33]
	s_waitcnt lgkmcnt(9)
	v_mfma_f32_16x16x32_bf16 v[34:37], v[144:147], v[188:191], v[34:37]
	v_mfma_f32_16x16x32_bf16 v[38:41], v[144:147], v[196:199], v[38:41]
	v_mfma_f32_16x16x32_bf16 v[42:45], v[144:147], v[200:203], v[42:45]
	v_mfma_f32_16x16x32_bf16 v[46:49], v[144:147], v[204:207], v[46:49]
	s_waitcnt lgkmcnt(8)
	v_mfma_f32_16x16x32_bf16 v[50:53], v[148:151], v[188:191], v[50:53]
	v_mfma_f32_16x16x32_bf16 v[54:57], v[148:151], v[196:199], v[54:57]
	v_mfma_f32_16x16x32_bf16 v[58:61], v[148:151], v[200:203], v[58:61]
	v_mfma_f32_16x16x32_bf16 v[62:65], v[148:151], v[204:207], v[62:65]
	s_waitcnt lgkmcnt(3)
	v_mfma_f32_16x16x32_bf16 v[2:5], v[172:175], v[212:215], v[2:5]
	v_mfma_f32_16x16x32_bf16 v[6:9], v[172:175], v[216:219], v[6:9]
	v_mfma_f32_16x16x32_bf16 v[10:13], v[172:175], v[220:223], v[10:13]
	v_mfma_f32_16x16x32_bf16 v[14:17], v[172:175], v[224:227], v[14:17]
	s_waitcnt lgkmcnt(2)
	v_mfma_f32_16x16x32_bf16 v[18:21], v[176:179], v[212:215], v[18:21]
	v_mfma_f32_16x16x32_bf16 v[22:25], v[176:179], v[216:219], v[22:25]
	v_mfma_f32_16x16x32_bf16 v[26:29], v[176:179], v[220:223], v[26:29]
	v_mfma_f32_16x16x32_bf16 v[30:33], v[176:179], v[224:227], v[30:33]
	s_waitcnt lgkmcnt(1)
	v_mfma_f32_16x16x32_bf16 v[34:37], v[180:183], v[212:215], v[34:37]
	v_mfma_f32_16x16x32_bf16 v[38:41], v[180:183], v[216:219], v[38:41]
	v_mfma_f32_16x16x32_bf16 v[42:45], v[180:183], v[220:223], v[42:45]
	v_mfma_f32_16x16x32_bf16 v[46:49], v[180:183], v[224:227], v[46:49]
	s_waitcnt lgkmcnt(0)
	v_mfma_f32_16x16x32_bf16 v[50:53], v[184:187], v[212:215], v[50:53]
	v_mfma_f32_16x16x32_bf16 v[54:57], v[184:187], v[216:219], v[54:57]
	v_mfma_f32_16x16x32_bf16 v[58:61], v[184:187], v[220:223], v[58:61]
	v_mfma_f32_16x16x32_bf16 v[62:65], v[184:187], v[224:227], v[62:65]
	s_setprio 0
	s_waitcnt vmcnt(0)
	s_barrier
	s_setprio 3
	v_add_u32_e32 v236, s40, v232
	v_add_u32_e32 v237, s40, v233
	ds_read_b128 v[188:191], v236
	ds_read_b128 v[196:199], v236 offset:2048
	ds_read_b128 v[200:203], v236 offset:4096
	ds_read_b128 v[204:207], v236 offset:6144
	ds_read_b128 v[212:215], v237
	ds_read_b128 v[216:219], v237 offset:2048
	ds_read_b128 v[220:223], v237 offset:4096
	ds_read_b128 v[224:227], v237 offset:6144
	s_waitcnt lgkmcnt(7)
	s_setprio 1
	v_mfma_f32_16x16x32_bf16 v[66:69], v[136:139], v[188:191], v[66:69]
	v_mfma_f32_16x16x32_bf16 v[82:85], v[140:143], v[188:191], v[82:85]
	v_mfma_f32_16x16x32_bf16 v[98:101], v[144:147], v[188:191], v[98:101]
	v_mfma_f32_16x16x32_bf16 v[114:117], v[148:151], v[188:191], v[114:117]
	s_waitcnt lgkmcnt(6)
	v_mfma_f32_16x16x32_bf16 v[70:73], v[136:139], v[196:199], v[70:73]
	v_mfma_f32_16x16x32_bf16 v[86:89], v[140:143], v[196:199], v[86:89]
	v_mfma_f32_16x16x32_bf16 v[102:105], v[144:147], v[196:199], v[102:105]
	v_mfma_f32_16x16x32_bf16 v[118:121], v[148:151], v[196:199], v[118:121]
	s_waitcnt lgkmcnt(5)
	v_mfma_f32_16x16x32_bf16 v[74:77], v[136:139], v[200:203], v[74:77]
	v_mfma_f32_16x16x32_bf16 v[90:93], v[140:143], v[200:203], v[90:93]
	v_mfma_f32_16x16x32_bf16 v[106:109], v[144:147], v[200:203], v[106:109]
	v_mfma_f32_16x16x32_bf16 v[122:125], v[148:151], v[200:203], v[122:125]
	s_waitcnt lgkmcnt(4)
	v_mfma_f32_16x16x32_bf16 v[78:81], v[136:139], v[204:207], v[78:81]
	v_mfma_f32_16x16x32_bf16 v[94:97], v[140:143], v[204:207], v[94:97]
	v_mfma_f32_16x16x32_bf16 v[110:113], v[144:147], v[204:207], v[110:113]
	v_mfma_f32_16x16x32_bf16 v[126:129], v[148:151], v[204:207], v[126:129]
	s_waitcnt lgkmcnt(3)
	v_mfma_f32_16x16x32_bf16 v[66:69], v[172:175], v[212:215], v[66:69]
	v_mfma_f32_16x16x32_bf16 v[82:85], v[176:179], v[212:215], v[82:85]
	v_mfma_f32_16x16x32_bf16 v[98:101], v[180:183], v[212:215], v[98:101]
	v_mfma_f32_16x16x32_bf16 v[114:117], v[184:187], v[212:215], v[114:117]
	s_waitcnt lgkmcnt(2)
	v_mfma_f32_16x16x32_bf16 v[70:73], v[172:175], v[216:219], v[70:73]
	v_mfma_f32_16x16x32_bf16 v[86:89], v[176:179], v[216:219], v[86:89]
	v_mfma_f32_16x16x32_bf16 v[102:105], v[180:183], v[216:219], v[102:105]
	v_mfma_f32_16x16x32_bf16 v[118:121], v[184:187], v[216:219], v[118:121]
	s_waitcnt lgkmcnt(1)
	v_mfma_f32_16x16x32_bf16 v[74:77], v[172:175], v[220:223], v[74:77]
	v_mfma_f32_16x16x32_bf16 v[90:93], v[176:179], v[220:223], v[90:93]
	v_mfma_f32_16x16x32_bf16 v[106:109], v[180:183], v[220:223], v[106:109]
	v_mfma_f32_16x16x32_bf16 v[122:125], v[184:187], v[220:223], v[122:125]
	s_waitcnt lgkmcnt(0)
	v_mfma_f32_16x16x32_bf16 v[78:81], v[172:175], v[224:227], v[78:81]
	v_mfma_f32_16x16x32_bf16 v[94:97], v[176:179], v[224:227], v[94:97]
	v_mfma_f32_16x16x32_bf16 v[110:113], v[180:183], v[224:227], v[110:113]
	v_mfma_f32_16x16x32_bf16 v[126:129], v[184:187], v[224:227], v[126:129]
	s_setprio 0
	s_nop 7
	s_barrier
	s_load_dwordx2 s[58:59], s[12:13], 0x100
	v_lshrrev_b32_e32 v241, 5, v131
	v_and_b32_e32 v242, 31, v131
	v_lshlrev_b32_e32 v243, 4, v242
	s_movk_i32 s56, 0x210
	v_mad_u32_u24 v239, v241, s56, v243
	v_add_u32_e32 v239, 16, v239
	v_lshlrev_b32_e32 v240, 13, v241
	v_or_b32_e32 v240, v240, v243
	s_lshl_b32 s56, s53, 13
	s_lshl_b32 s57, s54, 2
	s_add_i32 s56, s56, s57
	s_waitcnt lgkmcnt(0)
	s_add_u32 s58, s58, s56
	s_addc_u32 s59, s59, 0
	ds_write_b32 v238, v2
	ds_write_b32 v238, v3 offset:528
	ds_write_b32 v238, v4 offset:1056
	ds_write_b32 v238, v5 offset:1584
	ds_write_b32 v238, v6 offset:64
	ds_write_b32 v238, v7 offset:592
	ds_write_b32 v238, v8 offset:1120
	ds_write_b32 v238, v9 offset:1648
	ds_write_b32 v238, v10 offset:128
	ds_write_b32 v238, v11 offset:656
	ds_write_b32 v238, v12 offset:1184
	ds_write_b32 v238, v13 offset:1712
	ds_write_b32 v238, v14 offset:192
	ds_write_b32 v238, v15 offset:720
	ds_write_b32 v238, v16 offset:1248
	ds_write_b32 v238, v17 offset:1776
	ds_write_b32 v238, v18 offset:8448
	ds_write_b32 v238, v19 offset:8976
	ds_write_b32 v238, v20 offset:9504
	ds_write_b32 v238, v21 offset:10032
	ds_write_b32 v238, v22 offset:8512
	ds_write_b32 v238, v23 offset:9040
	ds_write_b32 v238, v24 offset:9568
	ds_write_b32 v238, v25 offset:10096
	ds_write_b32 v238, v26 offset:8576
	ds_write_b32 v238, v27 offset:9104
	ds_write_b32 v238, v28 offset:9632
	ds_write_b32 v238, v29 offset:10160
	ds_write_b32 v238, v30 offset:8640
	ds_write_b32 v238, v31 offset:9168
	ds_write_b32 v238, v32 offset:9696
	ds_write_b32 v238, v33 offset:10224
	ds_write_b32 v238, v34 offset:16896
	ds_write_b32 v238, v35 offset:17424
	ds_write_b32 v238, v36 offset:17952
	ds_write_b32 v238, v37 offset:18480
	ds_write_b32 v238, v38 offset:16960
	ds_write_b32 v238, v39 offset:17488
	ds_write_b32 v238, v40 offset:18016
	ds_write_b32 v238, v41 offset:18544
	ds_write_b32 v238, v42 offset:17024
	ds_write_b32 v238, v43 offset:17552
	ds_write_b32 v238, v44 offset:18080
	ds_write_b32 v238, v45 offset:18608
	ds_write_b32 v238, v46 offset:17088
	ds_write_b32 v238, v47 offset:17616
	ds_write_b32 v238, v48 offset:18144
	ds_write_b32 v238, v49 offset:18672
	ds_write_b32 v238, v50 offset:25344
	ds_write_b32 v238, v51 offset:25872
	ds_write_b32 v238, v52 offset:26400
	ds_write_b32 v238, v53 offset:26928
	ds_write_b32 v238, v54 offset:25408
	ds_write_b32 v238, v55 offset:25936
	ds_write_b32 v238, v56 offset:26464
	ds_write_b32 v238, v57 offset:26992
	ds_write_b32 v238, v58 offset:25472
	ds_write_b32 v238, v59 offset:26000
	ds_write_b32 v238, v60 offset:26528
	ds_write_b32 v238, v61 offset:27056
	ds_write_b32 v238, v62 offset:25536
	ds_write_b32 v238, v63 offset:26064
	ds_write_b32 v238, v64 offset:26592
	ds_write_b32 v238, v65 offset:27120
	s_mov_b32 s0, s58
	s_mov_b32 s1, s59
	global_load_dwordx4 v[136:139], v240, s[0:1]
	s_add_u32 s0, s0, 0x10000
	s_addc_u32 s1, s1, 0
	global_load_dwordx4 v[140:143], v240, s[0:1]
	s_add_u32 s0, s0, 0x10000
	s_addc_u32 s1, s1, 0
	global_load_dwordx4 v[144:147], v240, s[0:1]
	s_add_u32 s0, s0, 0x10000
	s_addc_u32 s1, s1, 0
	global_load_dwordx4 v[148:151], v240, s[0:1]
	s_add_u32 s0, s0, 0x10000
	s_addc_u32 s1, s1, 0
	global_load_dwordx4 v[172:175], v240, s[0:1]
	s_add_u32 s0, s0, 0x10000
	s_addc_u32 s1, s1, 0
	global_load_dwordx4 v[176:179], v240, s[0:1]
	s_add_u32 s0, s0, 0x10000
	s_addc_u32 s1, s1, 0
	global_load_dwordx4 v[180:183], v240, s[0:1]
	s_add_u32 s0, s0, 0x10000
	s_addc_u32 s1, s1, 0
	global_load_dwordx4 v[184:187], v240, s[0:1]
	s_add_u32 s0, s0, 0x10000
	s_addc_u32 s1, s1, 0
	global_load_dwordx4 v[188:191], v240, s[0:1]
	s_add_u32 s0, s0, 0x10000
	s_addc_u32 s1, s1, 0
	global_load_dwordx4 v[196:199], v240, s[0:1]
	s_add_u32 s0, s0, 0x10000
	s_addc_u32 s1, s1, 0
	global_load_dwordx4 v[200:203], v240, s[0:1]
	s_add_u32 s0, s0, 0x10000
	s_addc_u32 s1, s1, 0
	global_load_dwordx4 v[204:207], v240, s[0:1]
	s_add_u32 s0, s0, 0x10000
	s_addc_u32 s1, s1, 0
	global_load_dwordx4 v[212:215], v240, s[0:1]
	s_add_u32 s0, s0, 0x10000
	s_addc_u32 s1, s1, 0
	global_load_dwordx4 v[216:219], v240, s[0:1]
	s_add_u32 s0, s0, 0x10000
	s_addc_u32 s1, s1, 0
	global_load_dwordx4 v[220:223], v240, s[0:1]
	s_add_u32 s0, s0, 0x10000
	s_addc_u32 s1, s1, 0
	global_load_dwordx4 v[224:227], v240, s[0:1]
	s_waitcnt lgkmcnt(0)
	s_barrier
	ds_read_b128 v[2:5], v239
	ds_read_b128 v[6:9], v239 offset:4224
	ds_read_b128 v[10:13], v239 offset:8448
	ds_read_b128 v[14:17], v239 offset:12672
	ds_read_b128 v[18:21], v239 offset:16896
	ds_read_b128 v[22:25], v239 offset:21120
	ds_read_b128 v[26:29], v239 offset:25344
	ds_read_b128 v[30:33], v239 offset:29568
	ds_read_b128 v[34:37], v239 offset:33792
	ds_read_b128 v[38:41], v239 offset:38016
	ds_read_b128 v[42:45], v239 offset:42240
	ds_read_b128 v[46:49], v239 offset:46464
	ds_read_b128 v[50:53], v239 offset:50688
	ds_read_b128 v[54:57], v239 offset:54912
	ds_read_b128 v[58:61], v239 offset:59136
	ds_read_b128 v[62:65], v239 offset:63360
	s_mov_b32 s0, s58
	s_mov_b32 s1, s59
	s_waitcnt vmcnt(15) lgkmcnt(15)
	v_pk_add_f32 v[2:3], v[2:3], v[136:137]
	v_pk_add_f32 v[4:5], v[4:5], v[138:139]
	s_waitcnt vmcnt(14) lgkmcnt(14)
	v_pk_add_f32 v[6:7], v[6:7], v[140:141]
	v_pk_add_f32 v[8:9], v[8:9], v[142:143]
	s_waitcnt vmcnt(13) lgkmcnt(13)
	v_pk_add_f32 v[10:11], v[10:11], v[144:145]
	v_pk_add_f32 v[12:13], v[12:13], v[146:147]
	s_waitcnt vmcnt(12) lgkmcnt(12)
	v_pk_add_f32 v[14:15], v[14:15], v[148:149]
	v_pk_add_f32 v[16:17], v[16:17], v[150:151]
	s_waitcnt vmcnt(11) lgkmcnt(11)
	v_pk_add_f32 v[18:19], v[18:19], v[172:173]
	v_pk_add_f32 v[20:21], v[20:21], v[174:175]
	s_waitcnt vmcnt(10) lgkmcnt(10)
	v_pk_add_f32 v[22:23], v[22:23], v[176:177]
	v_pk_add_f32 v[24:25], v[24:25], v[178:179]
	s_waitcnt vmcnt(9) lgkmcnt(9)
	v_pk_add_f32 v[26:27], v[26:27], v[180:181]
	v_pk_add_f32 v[28:29], v[28:29], v[182:183]
	s_waitcnt vmcnt(8) lgkmcnt(8)
	v_pk_add_f32 v[30:31], v[30:31], v[184:185]
	v_pk_add_f32 v[32:33], v[32:33], v[186:187]
	s_waitcnt vmcnt(7) lgkmcnt(7)
	v_pk_add_f32 v[34:35], v[34:35], v[188:189]
	v_pk_add_f32 v[36:37], v[36:37], v[190:191]
	s_waitcnt vmcnt(6) lgkmcnt(6)
	v_pk_add_f32 v[38:39], v[38:39], v[196:197]
	v_pk_add_f32 v[40:41], v[40:41], v[198:199]
	s_waitcnt vmcnt(5) lgkmcnt(5)
	v_pk_add_f32 v[42:43], v[42:43], v[200:201]
	v_pk_add_f32 v[44:45], v[44:45], v[202:203]
	s_waitcnt vmcnt(4) lgkmcnt(4)
	v_pk_add_f32 v[46:47], v[46:47], v[204:205]
	v_pk_add_f32 v[48:49], v[48:49], v[206:207]
	s_waitcnt vmcnt(3) lgkmcnt(3)
	v_pk_add_f32 v[50:51], v[50:51], v[212:213]
	v_pk_add_f32 v[52:53], v[52:53], v[214:215]
	s_waitcnt vmcnt(2) lgkmcnt(2)
	v_pk_add_f32 v[54:55], v[54:55], v[216:217]
	v_pk_add_f32 v[56:57], v[56:57], v[218:219]
	s_waitcnt vmcnt(1) lgkmcnt(1)
	v_pk_add_f32 v[58:59], v[58:59], v[220:221]
	v_pk_add_f32 v[60:61], v[60:61], v[222:223]
	s_waitcnt vmcnt(0) lgkmcnt(0)
	v_pk_add_f32 v[62:63], v[62:63], v[224:225]
	v_pk_add_f32 v[64:65], v[64:65], v[226:227]
	global_store_dwordx4 v240, v[2:5], s[0:1]
	s_add_u32 s0, s0, 0x10000
	s_addc_u32 s1, s1, 0
	global_store_dwordx4 v240, v[6:9], s[0:1]
	s_add_u32 s0, s0, 0x10000
	s_addc_u32 s1, s1, 0
	global_store_dwordx4 v240, v[10:13], s[0:1]
	s_add_u32 s0, s0, 0x10000
	s_addc_u32 s1, s1, 0
	global_store_dwordx4 v240, v[14:17], s[0:1]
	s_add_u32 s0, s0, 0x10000
	s_addc_u32 s1, s1, 0
	global_store_dwordx4 v240, v[18:21], s[0:1]
	s_add_u32 s0, s0, 0x10000
	s_addc_u32 s1, s1, 0
	global_store_dwordx4 v240, v[22:25], s[0:1]
	s_add_u32 s0, s0, 0x10000
	s_addc_u32 s1, s1, 0
	global_store_dwordx4 v240, v[26:29], s[0:1]
	s_add_u32 s0, s0, 0x10000
	s_addc_u32 s1, s1, 0
	global_store_dwordx4 v240, v[30:33], s[0:1]
	s_add_u32 s0, s0, 0x10000
	s_addc_u32 s1, s1, 0
	global_store_dwordx4 v240, v[34:37], s[0:1]
	s_add_u32 s0, s0, 0x10000
	s_addc_u32 s1, s1, 0
	global_store_dwordx4 v240, v[38:41], s[0:1]
	s_add_u32 s0, s0, 0x10000
	s_addc_u32 s1, s1, 0
	global_store_dwordx4 v240, v[42:45], s[0:1]
	s_add_u32 s0, s0, 0x10000
	s_addc_u32 s1, s1, 0
	global_store_dwordx4 v240, v[46:49], s[0:1]
	s_add_u32 s0, s0, 0x10000
	s_addc_u32 s1, s1, 0
	global_store_dwordx4 v240, v[50:53], s[0:1]
	s_add_u32 s0, s0, 0x10000
	s_addc_u32 s1, s1, 0
	global_store_dwordx4 v240, v[54:57], s[0:1]
	s_add_u32 s0, s0, 0x10000
	s_addc_u32 s1, s1, 0
	global_store_dwordx4 v240, v[58:61], s[0:1]
	s_add_u32 s0, s0, 0x10000
	s_addc_u32 s1, s1, 0
	global_store_dwordx4 v240, v[62:65], s[0:1]
	s_add_u32 s58, s58, 0x1000
	s_addc_u32 s59, s59, 0
	s_waitcnt lgkmcnt(0)
	s_barrier
	ds_write_b32 v238, v66
	ds_write_b32 v238, v67 offset:528
	ds_write_b32 v238, v68 offset:1056
	ds_write_b32 v238, v69 offset:1584
	ds_write_b32 v238, v70 offset:64
	ds_write_b32 v238, v71 offset:592
	ds_write_b32 v238, v72 offset:1120
	ds_write_b32 v238, v73 offset:1648
	ds_write_b32 v238, v74 offset:128
	ds_write_b32 v238, v75 offset:656
	ds_write_b32 v238, v76 offset:1184
	ds_write_b32 v238, v77 offset:1712
	ds_write_b32 v238, v78 offset:192
	ds_write_b32 v238, v79 offset:720
	ds_write_b32 v238, v80 offset:1248
	ds_write_b32 v238, v81 offset:1776
	ds_write_b32 v238, v82 offset:8448
	ds_write_b32 v238, v83 offset:8976
	ds_write_b32 v238, v84 offset:9504
	ds_write_b32 v238, v85 offset:10032
	ds_write_b32 v238, v86 offset:8512
	ds_write_b32 v238, v87 offset:9040
	ds_write_b32 v238, v88 offset:9568
	ds_write_b32 v238, v89 offset:10096
	ds_write_b32 v238, v90 offset:8576
	ds_write_b32 v238, v91 offset:9104
	ds_write_b32 v238, v92 offset:9632
	ds_write_b32 v238, v93 offset:10160
	ds_write_b32 v238, v94 offset:8640
	ds_write_b32 v238, v95 offset:9168
	ds_write_b32 v238, v96 offset:9696
	ds_write_b32 v238, v97 offset:10224
	ds_write_b32 v238, v98 offset:16896
	ds_write_b32 v238, v99 offset:17424
	ds_write_b32 v238, v100 offset:17952
	ds_write_b32 v238, v101 offset:18480
	ds_write_b32 v238, v102 offset:16960
	ds_write_b32 v238, v103 offset:17488
	ds_write_b32 v238, v104 offset:18016
	ds_write_b32 v238, v105 offset:18544
	ds_write_b32 v238, v106 offset:17024
	ds_write_b32 v238, v107 offset:17552
	ds_write_b32 v238, v108 offset:18080
	ds_write_b32 v238, v109 offset:18608
	ds_write_b32 v238, v110 offset:17088
	ds_write_b32 v238, v111 offset:17616
	ds_write_b32 v238, v112 offset:18144
	ds_write_b32 v238, v113 offset:18672
	ds_write_b32 v238, v114 offset:25344
	ds_write_b32 v238, v115 offset:25872
	ds_write_b32 v238, v116 offset:26400
	ds_write_b32 v238, v117 offset:26928
	ds_write_b32 v238, v118 offset:25408
	ds_write_b32 v238, v119 offset:25936
	ds_write_b32 v238, v120 offset:26464
	ds_write_b32 v238, v121 offset:26992
	ds_write_b32 v238, v122 offset:25472
	ds_write_b32 v238, v123 offset:26000
	ds_write_b32 v238, v124 offset:26528
	ds_write_b32 v238, v125 offset:27056
	ds_write_b32 v238, v126 offset:25536
	ds_write_b32 v238, v127 offset:26064
	ds_write_b32 v238, v128 offset:26592
	ds_write_b32 v238, v129 offset:27120
	s_mov_b32 s0, s58
	s_mov_b32 s1, s59
	global_load_dwordx4 v[136:139], v240, s[0:1]
	s_add_u32 s0, s0, 0x10000
	s_addc_u32 s1, s1, 0
	global_load_dwordx4 v[140:143], v240, s[0:1]
	s_add_u32 s0, s0, 0x10000
	s_addc_u32 s1, s1, 0
	global_load_dwordx4 v[144:147], v240, s[0:1]
	s_add_u32 s0, s0, 0x10000
	s_addc_u32 s1, s1, 0
	global_load_dwordx4 v[148:151], v240, s[0:1]
	s_add_u32 s0, s0, 0x10000
	s_addc_u32 s1, s1, 0
	global_load_dwordx4 v[172:175], v240, s[0:1]
	s_add_u32 s0, s0, 0x10000
	s_addc_u32 s1, s1, 0
	global_load_dwordx4 v[176:179], v240, s[0:1]
	s_add_u32 s0, s0, 0x10000
	s_addc_u32 s1, s1, 0
	global_load_dwordx4 v[180:183], v240, s[0:1]
	s_add_u32 s0, s0, 0x10000
	s_addc_u32 s1, s1, 0
	global_load_dwordx4 v[184:187], v240, s[0:1]
	s_add_u32 s0, s0, 0x10000
	s_addc_u32 s1, s1, 0
	global_load_dwordx4 v[188:191], v240, s[0:1]
	s_add_u32 s0, s0, 0x10000
	s_addc_u32 s1, s1, 0
	global_load_dwordx4 v[196:199], v240, s[0:1]
	s_add_u32 s0, s0, 0x10000
	s_addc_u32 s1, s1, 0
	global_load_dwordx4 v[200:203], v240, s[0:1]
	s_add_u32 s0, s0, 0x10000
	s_addc_u32 s1, s1, 0
	global_load_dwordx4 v[204:207], v240, s[0:1]
	s_add_u32 s0, s0, 0x10000
	s_addc_u32 s1, s1, 0
	global_load_dwordx4 v[212:215], v240, s[0:1]
	s_add_u32 s0, s0, 0x10000
	s_addc_u32 s1, s1, 0
	global_load_dwordx4 v[216:219], v240, s[0:1]
	s_add_u32 s0, s0, 0x10000
	s_addc_u32 s1, s1, 0
	global_load_dwordx4 v[220:223], v240, s[0:1]
	s_add_u32 s0, s0, 0x10000
	s_addc_u32 s1, s1, 0
	global_load_dwordx4 v[224:227], v240, s[0:1]
	s_waitcnt lgkmcnt(0)
	s_barrier
	ds_read_b128 v[66:69], v239
	ds_read_b128 v[70:73], v239 offset:4224
	ds_read_b128 v[74:77], v239 offset:8448
	ds_read_b128 v[78:81], v239 offset:12672
	ds_read_b128 v[82:85], v239 offset:16896
	ds_read_b128 v[86:89], v239 offset:21120
	ds_read_b128 v[90:93], v239 offset:25344
	ds_read_b128 v[94:97], v239 offset:29568
	ds_read_b128 v[98:101], v239 offset:33792
	ds_read_b128 v[102:105], v239 offset:38016
	ds_read_b128 v[106:109], v239 offset:42240
	ds_read_b128 v[110:113], v239 offset:46464
	ds_read_b128 v[114:117], v239 offset:50688
	ds_read_b128 v[118:121], v239 offset:54912
	ds_read_b128 v[122:125], v239 offset:59136
	ds_read_b128 v[126:129], v239 offset:63360
	s_mov_b32 s0, s58
	s_mov_b32 s1, s59
	s_waitcnt vmcnt(15) lgkmcnt(15)
	v_pk_add_f32 v[66:67], v[66:67], v[136:137]
	v_pk_add_f32 v[68:69], v[68:69], v[138:139]
	s_waitcnt vmcnt(14) lgkmcnt(14)
	v_pk_add_f32 v[70:71], v[70:71], v[140:141]
	v_pk_add_f32 v[72:73], v[72:73], v[142:143]
	s_waitcnt vmcnt(13) lgkmcnt(13)
	v_pk_add_f32 v[74:75], v[74:75], v[144:145]
	v_pk_add_f32 v[76:77], v[76:77], v[146:147]
	s_waitcnt vmcnt(12) lgkmcnt(12)
	v_pk_add_f32 v[78:79], v[78:79], v[148:149]
	v_pk_add_f32 v[80:81], v[80:81], v[150:151]
	s_waitcnt vmcnt(11) lgkmcnt(11)
	v_pk_add_f32 v[82:83], v[82:83], v[172:173]
	v_pk_add_f32 v[84:85], v[84:85], v[174:175]
	s_waitcnt vmcnt(10) lgkmcnt(10)
	v_pk_add_f32 v[86:87], v[86:87], v[176:177]
	v_pk_add_f32 v[88:89], v[88:89], v[178:179]
	s_waitcnt vmcnt(9) lgkmcnt(9)
	v_pk_add_f32 v[90:91], v[90:91], v[180:181]
	v_pk_add_f32 v[92:93], v[92:93], v[182:183]
	s_waitcnt vmcnt(8) lgkmcnt(8)
	v_pk_add_f32 v[94:95], v[94:95], v[184:185]
	v_pk_add_f32 v[96:97], v[96:97], v[186:187]
	s_waitcnt vmcnt(7) lgkmcnt(7)
	v_pk_add_f32 v[98:99], v[98:99], v[188:189]
	v_pk_add_f32 v[100:101], v[100:101], v[190:191]
	s_waitcnt vmcnt(6) lgkmcnt(6)
	v_pk_add_f32 v[102:103], v[102:103], v[196:197]
	v_pk_add_f32 v[104:105], v[104:105], v[198:199]
	s_waitcnt vmcnt(5) lgkmcnt(5)
	v_pk_add_f32 v[106:107], v[106:107], v[200:201]
	v_pk_add_f32 v[108:109], v[108:109], v[202:203]
	s_waitcnt vmcnt(4) lgkmcnt(4)
	v_pk_add_f32 v[110:111], v[110:111], v[204:205]
	v_pk_add_f32 v[112:113], v[112:113], v[206:207]
	s_waitcnt vmcnt(3) lgkmcnt(3)
	v_pk_add_f32 v[114:115], v[114:115], v[212:213]
	v_pk_add_f32 v[116:117], v[116:117], v[214:215]
	s_waitcnt vmcnt(2) lgkmcnt(2)
	v_pk_add_f32 v[118:119], v[118:119], v[216:217]
	v_pk_add_f32 v[120:121], v[120:121], v[218:219]
	s_waitcnt vmcnt(1) lgkmcnt(1)
	v_pk_add_f32 v[122:123], v[122:123], v[220:221]
	v_pk_add_f32 v[124:125], v[124:125], v[222:223]
	s_waitcnt vmcnt(0) lgkmcnt(0)
	v_pk_add_f32 v[126:127], v[126:127], v[224:225]
	v_pk_add_f32 v[128:129], v[128:129], v[226:227]
	global_store_dwordx4 v240, v[66:69], s[0:1]
	s_add_u32 s0, s0, 0x10000
	s_addc_u32 s1, s1, 0
	global_store_dwordx4 v240, v[70:73], s[0:1]
	s_add_u32 s0, s0, 0x10000
	s_addc_u32 s1, s1, 0
	global_store_dwordx4 v240, v[74:77], s[0:1]
	s_add_u32 s0, s0, 0x10000
	s_addc_u32 s1, s1, 0
	global_store_dwordx4 v240, v[78:81], s[0:1]
	s_add_u32 s0, s0, 0x10000
	s_addc_u32 s1, s1, 0
	global_store_dwordx4 v240, v[82:85], s[0:1]
	s_add_u32 s0, s0, 0x10000
	s_addc_u32 s1, s1, 0
	global_store_dwordx4 v240, v[86:89], s[0:1]
	s_add_u32 s0, s0, 0x10000
	s_addc_u32 s1, s1, 0
	global_store_dwordx4 v240, v[90:93], s[0:1]
	s_add_u32 s0, s0, 0x10000
	s_addc_u32 s1, s1, 0
	global_store_dwordx4 v240, v[94:97], s[0:1]
	s_add_u32 s0, s0, 0x10000
	s_addc_u32 s1, s1, 0
	global_store_dwordx4 v240, v[98:101], s[0:1]
	s_add_u32 s0, s0, 0x10000
	s_addc_u32 s1, s1, 0
	global_store_dwordx4 v240, v[102:105], s[0:1]
	s_add_u32 s0, s0, 0x10000
	s_addc_u32 s1, s1, 0
	global_store_dwordx4 v240, v[106:109], s[0:1]
	s_add_u32 s0, s0, 0x10000
	s_addc_u32 s1, s1, 0
	global_store_dwordx4 v240, v[110:113], s[0:1]
	s_add_u32 s0, s0, 0x10000
	s_addc_u32 s1, s1, 0
	global_store_dwordx4 v240, v[114:117], s[0:1]
	s_add_u32 s0, s0, 0x10000
	s_addc_u32 s1, s1, 0
	global_store_dwordx4 v240, v[118:121], s[0:1]
	s_add_u32 s0, s0, 0x10000
	s_addc_u32 s1, s1, 0
	global_store_dwordx4 v240, v[122:125], s[0:1]
	s_add_u32 s0, s0, 0x10000
	s_addc_u32 s1, s1, 0
	global_store_dwordx4 v240, v[126:129], s[0:1]
	s_add_i32 s21, s21, s72
	s_cmpk_lt_i32 s21, 0x200
	s_waitcnt lgkmcnt(0)
	s_barrier
	s_cbranch_scc1 .Lfin3_tile

.Lgu2_loop:
	s_setprio 3
	v_add_u32_e32 v234, s22, v232
	v_add_u32_e32 v236, s28, v232
	v_add_u32_e32 v235, s22, v233
	v_add_u32_e32 v237, s28, v233
	ds_read_b128 v[136:139], v234
	ds_read_b128 v[188:191], v236
	ds_read_b128 v[196:199], v236 offset:2048
	ds_read_b128 v[200:203], v236 offset:4096
	ds_read_b128 v[204:207], v236 offset:6144
	ds_read_b128 v[140:143], v234 offset:2048
	ds_read_b128 v[144:147], v234 offset:4096
	ds_read_b128 v[148:151], v234 offset:6144
	ds_read_b128 v[172:175], v235
	ds_read_b128 v[212:215], v237
	ds_read_b128 v[216:219], v237 offset:2048
	ds_read_b128 v[220:223], v237 offset:4096
	ds_read_b128 v[224:227], v237 offset:6144
	ds_read_b128 v[176:179], v235 offset:2048
	ds_read_b128 v[180:183], v235 offset:4096
	ds_read_b128 v[184:187], v235 offset:6144
	s_add_i32 m0, s51, 0xc000
	s_nop 0
	global_load_lds_dwordx4 v228, s[44:45]
	s_add_i32 m0, s51, 0xc400
	s_nop 0
	global_load_lds_dwordx4 v230, s[44:45]
	s_add_i32 m0, s51, 0xe000
	s_nop 0
	global_load_lds_dwordx4 v229, s[44:45]
	s_add_i32 m0, s51, 0xe400
	s_nop 0
	global_load_lds_dwordx4 v231, s[44:45]
	s_add_i32 m0, s51, 0x10000
	s_nop 0
	global_load_lds_dwordx4 v228, s[46:47]
	s_add_i32 m0, s51, 0x10400
	s_nop 0
	global_load_lds_dwordx4 v230, s[46:47]
	s_waitcnt lgkmcnt(11)
	s_setprio 1
	v_mfma_f32_16x16x32_bf16 v[2:5], v[136:139], v[188:191], v[2:5]
	v_mfma_f32_16x16x32_bf16 v[6:9], v[136:139], v[196:199], v[6:9]
	v_mfma_f32_16x16x32_bf16 v[10:13], v[136:139], v[200:203], v[10:13]
	v_mfma_f32_16x16x32_bf16 v[14:17], v[136:139], v[204:207], v[14:17]
	s_waitcnt lgkmcnt(10)
	v_mfma_f32_16x16x32_bf16 v[18:21], v[140:143], v[188:191], v[18:21]
	v_mfma_f32_16x16x32_bf16 v[22:25], v[140:143], v[196:199], v[22:25]
	v_mfma_f32_16x16x32_bf16 v[26:29], v[140:143], v[200:203], v[26:29]
	v_mfma_f32_16x16x32_bf16 v[30:33], v[140:143], v[204:207], v[30:33]
	s_waitcnt lgkmcnt(9)
	v_mfma_f32_16x16x32_bf16 v[34:37], v[144:147], v[188:191], v[34:37]
	v_mfma_f32_16x16x32_bf16 v[38:41], v[144:147], v[196:199], v[38:41]
	v_mfma_f32_16x16x32_bf16 v[42:45], v[144:147], v[200:203], v[42:45]
	v_mfma_f32_16x16x32_bf16 v[46:49], v[144:147], v[204:207], v[46:49]
	s_waitcnt lgkmcnt(8)
	v_mfma_f32_16x16x32_bf16 v[50:53], v[148:151], v[188:191], v[50:53]
	v_mfma_f32_16x16x32_bf16 v[54:57], v[148:151], v[196:199], v[54:57]
	v_mfma_f32_16x16x32_bf16 v[58:61], v[148:151], v[200:203], v[58:61]
	v_mfma_f32_16x16x32_bf16 v[62:65], v[148:151], v[204:207], v[62:65]
	s_waitcnt lgkmcnt(3)
	v_mfma_f32_16x16x32_bf16 v[2:5], v[172:175], v[212:215], v[2:5]
	v_mfma_f32_16x16x32_bf16 v[6:9], v[172:175], v[216:219], v[6:9]
	v_mfma_f32_16x16x32_bf16 v[10:13], v[172:175], v[220:223], v[10:13]
	v_mfma_f32_16x16x32_bf16 v[14:17], v[172:175], v[224:227], v[14:17]
	s_waitcnt lgkmcnt(2)
	v_mfma_f32_16x16x32_bf16 v[18:21], v[176:179], v[212:215], v[18:21]
	v_mfma_f32_16x16x32_bf16 v[22:25], v[176:179], v[216:219], v[22:25]
	v_mfma_f32_16x16x32_bf16 v[26:29], v[176:179], v[220:223], v[26:29]
	v_mfma_f32_16x16x32_bf16 v[30:33], v[176:179], v[224:227], v[30:33]
	s_waitcnt lgkmcnt(1)
	v_mfma_f32_16x16x32_bf16 v[34:37], v[180:183], v[212:215], v[34:37]
	v_mfma_f32_16x16x32_bf16 v[38:41], v[180:183], v[216:219], v[38:41]
	v_mfma_f32_16x16x32_bf16 v[42:45], v[180:183], v[220:223], v[42:45]
	v_mfma_f32_16x16x32_bf16 v[46:49], v[180:183], v[224:227], v[46:49]
	s_waitcnt lgkmcnt(0)
	v_mfma_f32_16x16x32_bf16 v[50:53], v[184:187], v[212:215], v[50:53]
	v_mfma_f32_16x16x32_bf16 v[54:57], v[184:187], v[216:219], v[54:57]
	v_mfma_f32_16x16x32_bf16 v[58:61], v[184:187], v[220:223], v[58:61]
	v_mfma_f32_16x16x32_bf16 v[62:65], v[184:187], v[224:227], v[62:65]
	s_setprio 0
	s_waitcnt vmcnt(6)
	s_barrier
.Lgu2_loop_a0:
	s_setprio 3
	v_add_u32_e32 v236, s40, v232
	v_add_u32_e32 v237, s40, v233
	ds_read_b128 v[188:191], v236
	ds_read_b128 v[196:199], v236 offset:2048
	ds_read_b128 v[200:203], v236 offset:4096
	ds_read_b128 v[204:207], v236 offset:6144
	ds_read_b128 v[212:215], v237
	ds_read_b128 v[216:219], v237 offset:2048
	ds_read_b128 v[220:223], v237 offset:4096
	ds_read_b128 v[224:227], v237 offset:6144
	s_mov_b32 m0, s51
	s_nop 0
	global_load_lds_dwordx4 v229, s[46:47]
	s_add_i32 m0, s51, 0x400
	s_nop 0
	global_load_lds_dwordx4 v231, s[46:47]
	s_add_i32 m0, s51, 0x2000
	s_nop 0
	global_load_lds_dwordx4 v228, s[48:49]
	s_add_i32 m0, s51, 0x2400
	s_nop 0
	global_load_lds_dwordx4 v230, s[48:49]
	s_add_i32 m0, s51, 0x4000
	s_nop 0
	global_load_lds_dwordx4 v229, s[48:49]
	s_add_i32 m0, s51, 0x4400
	s_nop 0
	global_load_lds_dwordx4 v231, s[48:49]
	s_waitcnt lgkmcnt(7)
	s_setprio 1
	v_mfma_f32_16x16x32_bf16 v[66:69], v[136:139], v[188:191], v[66:69]
	v_mfma_f32_16x16x32_bf16 v[82:85], v[140:143], v[188:191], v[82:85]
	v_mfma_f32_16x16x32_bf16 v[98:101], v[144:147], v[188:191], v[98:101]
	v_mfma_f32_16x16x32_bf16 v[114:117], v[148:151], v[188:191], v[114:117]
	s_waitcnt lgkmcnt(6)
	v_mfma_f32_16x16x32_bf16 v[70:73], v[136:139], v[196:199], v[70:73]
	v_mfma_f32_16x16x32_bf16 v[86:89], v[140:143], v[196:199], v[86:89]
	v_mfma_f32_16x16x32_bf16 v[102:105], v[144:147], v[196:199], v[102:105]
	v_mfma_f32_16x16x32_bf16 v[118:121], v[148:151], v[196:199], v[118:121]
	s_waitcnt lgkmcnt(5)
	v_mfma_f32_16x16x32_bf16 v[74:77], v[136:139], v[200:203], v[74:77]
	v_mfma_f32_16x16x32_bf16 v[90:93], v[140:143], v[200:203], v[90:93]
	v_mfma_f32_16x16x32_bf16 v[106:109], v[144:147], v[200:203], v[106:109]
	v_mfma_f32_16x16x32_bf16 v[122:125], v[148:151], v[200:203], v[122:125]
	s_waitcnt lgkmcnt(4)
	v_mfma_f32_16x16x32_bf16 v[78:81], v[136:139], v[204:207], v[78:81]
	v_mfma_f32_16x16x32_bf16 v[94:97], v[140:143], v[204:207], v[94:97]
	v_mfma_f32_16x16x32_bf16 v[110:113], v[144:147], v[204:207], v[110:113]
	v_mfma_f32_16x16x32_bf16 v[126:129], v[148:151], v[204:207], v[126:129]
	s_waitcnt lgkmcnt(3)
	v_mfma_f32_16x16x32_bf16 v[66:69], v[172:175], v[212:215], v[66:69]
	v_mfma_f32_16x16x32_bf16 v[82:85], v[176:179], v[212:215], v[82:85]
	v_mfma_f32_16x16x32_bf16 v[98:101], v[180:183], v[212:215], v[98:101]
	v_mfma_f32_16x16x32_bf16 v[114:117], v[184:187], v[212:215], v[114:117]
	s_waitcnt lgkmcnt(2)
	v_mfma_f32_16x16x32_bf16 v[70:73], v[172:175], v[216:219], v[70:73]
	v_mfma_f32_16x16x32_bf16 v[86:89], v[176:179], v[216:219], v[86:89]
	v_mfma_f32_16x16x32_bf16 v[102:105], v[180:183], v[216:219], v[102:105]
	v_mfma_f32_16x16x32_bf16 v[118:121], v[184:187], v[216:219], v[118:121]
	s_waitcnt lgkmcnt(1)
	v_mfma_f32_16x16x32_bf16 v[74:77], v[172:175], v[220:223], v[74:77]
	v_mfma_f32_16x16x32_bf16 v[90:93], v[176:179], v[220:223], v[90:93]
	v_mfma_f32_16x16x32_bf16 v[106:109], v[180:183], v[220:223], v[106:109]
	v_mfma_f32_16x16x32_bf16 v[122:125], v[184:187], v[220:223], v[122:125]
	s_waitcnt lgkmcnt(0)
	v_mfma_f32_16x16x32_bf16 v[78:81], v[172:175], v[224:227], v[78:81]
	v_mfma_f32_16x16x32_bf16 v[94:97], v[176:179], v[224:227], v[94:97]
	v_mfma_f32_16x16x32_bf16 v[110:113], v[180:183], v[224:227], v[110:113]
	v_mfma_f32_16x16x32_bf16 v[126:129], v[184:187], v[224:227], v[126:129]
	s_setprio 0
	v_add_u32_e32 v228, 0x80, v228
	v_add_u32_e32 v229, 0x80, v229
	v_add_u32_e32 v230, 0x80, v230
	v_add_u32_e32 v231, 0x80, v231
	s_waitcnt vmcnt(4)
	s_barrier
	s_setprio 3
	v_add_u32_e32 v234, s23, v232
	v_add_u32_e32 v236, s29, v232
	v_add_u32_e32 v235, s23, v233
	v_add_u32_e32 v237, s29, v233
	ds_read_b128 v[136:139], v234
	ds_read_b128 v[188:191], v236
	ds_read_b128 v[196:199], v236 offset:2048
	ds_read_b128 v[200:203], v236 offset:4096
	ds_read_b128 v[204:207], v236 offset:6144
	ds_read_b128 v[140:143], v234 offset:2048
	ds_read_b128 v[144:147], v234 offset:4096
	ds_read_b128 v[148:151], v234 offset:6144
	ds_read_b128 v[172:175], v235
	ds_read_b128 v[212:215], v237
	ds_read_b128 v[216:219], v237 offset:2048
	ds_read_b128 v[220:223], v237 offset:4096
	ds_read_b128 v[224:227], v237 offset:6144
	ds_read_b128 v[176:179], v235 offset:2048
	ds_read_b128 v[180:183], v235 offset:4096
	ds_read_b128 v[184:187], v235 offset:6144
	s_add_i32 m0, s51, 0x6000
	s_nop 0
	global_load_lds_dwordx4 v228, s[44:45]
	s_add_i32 m0, s51, 0x6400
	s_nop 0
	global_load_lds_dwordx4 v230, s[44:45]
	s_add_i32 m0, s51, 0x8000
	s_nop 0
	global_load_lds_dwordx4 v229, s[44:45]
	s_add_i32 m0, s51, 0x8400
	s_nop 0
	global_load_lds_dwordx4 v231, s[44:45]
	s_add_i32 m0, s51, 0xa000
	s_nop 0
	global_load_lds_dwordx4 v228, s[46:47]
	s_add_i32 m0, s51, 0xa400
	s_nop 0
	global_load_lds_dwordx4 v230, s[46:47]
	s_waitcnt lgkmcnt(11)
	s_setprio 1
	v_mfma_f32_16x16x32_bf16 v[2:5], v[136:139], v[188:191], v[2:5]
	v_mfma_f32_16x16x32_bf16 v[6:9], v[136:139], v[196:199], v[6:9]
	v_mfma_f32_16x16x32_bf16 v[10:13], v[136:139], v[200:203], v[10:13]
	v_mfma_f32_16x16x32_bf16 v[14:17], v[136:139], v[204:207], v[14:17]
	s_waitcnt lgkmcnt(10)
	v_mfma_f32_16x16x32_bf16 v[18:21], v[140:143], v[188:191], v[18:21]
	v_mfma_f32_16x16x32_bf16 v[22:25], v[140:143], v[196:199], v[22:25]
	v_mfma_f32_16x16x32_bf16 v[26:29], v[140:143], v[200:203], v[26:29]
	v_mfma_f32_16x16x32_bf16 v[30:33], v[140:143], v[204:207], v[30:33]
	s_waitcnt lgkmcnt(9)
	v_mfma_f32_16x16x32_bf16 v[34:37], v[144:147], v[188:191], v[34:37]
	v_mfma_f32_16x16x32_bf16 v[38:41], v[144:147], v[196:199], v[38:41]
	v_mfma_f32_16x16x32_bf16 v[42:45], v[144:147], v[200:203], v[42:45]
	v_mfma_f32_16x16x32_bf16 v[46:49], v[144:147], v[204:207], v[46:49]
	s_waitcnt lgkmcnt(8)
	v_mfma_f32_16x16x32_bf16 v[50:53], v[148:151], v[188:191], v[50:53]
	v_mfma_f32_16x16x32_bf16 v[54:57], v[148:151], v[196:199], v[54:57]
	v_mfma_f32_16x16x32_bf16 v[58:61], v[148:151], v[200:203], v[58:61]
	v_mfma_f32_16x16x32_bf16 v[62:65], v[148:151], v[204:207], v[62:65]
	s_waitcnt lgkmcnt(3)
	v_mfma_f32_16x16x32_bf16 v[2:5], v[172:175], v[212:215], v[2:5]
	v_mfma_f32_16x16x32_bf16 v[6:9], v[172:175], v[216:219], v[6:9]
	v_mfma_f32_16x16x32_bf16 v[10:13], v[172:175], v[220:223], v[10:13]
	v_mfma_f32_16x16x32_bf16 v[14:17], v[172:175], v[224:227], v[14:17]
	s_waitcnt lgkmcnt(2)
	v_mfma_f32_16x16x32_bf16 v[18:21], v[176:179], v[212:215], v[18:21]
	v_mfma_f32_16x16x32_bf16 v[22:25], v[176:179], v[216:219], v[22:25]
	v_mfma_f32_16x16x32_bf16 v[26:29], v[176:179], v[220:223], v[26:29]
	v_mfma_f32_16x16x32_bf16 v[30:33], v[176:179], v[224:227], v[30:33]
	s_waitcnt lgkmcnt(1)
	v_mfma_f32_16x16x32_bf16 v[34:37], v[180:183], v[212:215], v[34:37]
	v_mfma_f32_16x16x32_bf16 v[38:41], v[180:183], v[216:219], v[38:41]
	v_mfma_f32_16x16x32_bf16 v[42:45], v[180:183], v[220:223], v[42:45]
	v_mfma_f32_16x16x32_bf16 v[46:49], v[180:183], v[224:227], v[46:49]
	s_waitcnt lgkmcnt(0)
	v_mfma_f32_16x16x32_bf16 v[50:53], v[184:187], v[212:215], v[50:53]
	v_mfma_f32_16x16x32_bf16 v[54:57], v[184:187], v[216:219], v[54:57]
	v_mfma_f32_16x16x32_bf16 v[58:61], v[184:187], v[220:223], v[58:61]
	v_mfma_f32_16x16x32_bf16 v[62:65], v[184:187], v[224:227], v[62:65]
	s_setprio 0
	s_waitcnt vmcnt(6)
	s_barrier
	s_setprio 3
	v_add_u32_e32 v236, s41, v232
	v_add_u32_e32 v237, s41, v233
	ds_read_b128 v[188:191], v236
	ds_read_b128 v[196:199], v236 offset:2048
	ds_read_b128 v[200:203], v236 offset:4096
	ds_read_b128 v[204:207], v236 offset:6144
	ds_read_b128 v[212:215], v237
	ds_read_b128 v[216:219], v237 offset:2048
	ds_read_b128 v[220:223], v237 offset:4096
	ds_read_b128 v[224:227], v237 offset:6144
	s_add_i32 m0, s51, 0xc000
	s_nop 0
	global_load_lds_dwordx4 v229, s[46:47]
	s_add_i32 m0, s51, 0xc400
	s_nop 0
	global_load_lds_dwordx4 v231, s[46:47]
	s_add_i32 m0, s51, 0xe000
	s_nop 0
	global_load_lds_dwordx4 v228, s[48:49]
	s_add_i32 m0, s51, 0xe400
	s_nop 0
	global_load_lds_dwordx4 v230, s[48:49]
	s_add_i32 m0, s51, 0x10000
	s_nop 0
	global_load_lds_dwordx4 v229, s[48:49]
	s_add_i32 m0, s51, 0x10400
	s_nop 0
	global_load_lds_dwordx4 v231, s[48:49]
	s_waitcnt lgkmcnt(7)
	s_setprio 1
	v_mfma_f32_16x16x32_bf16 v[66:69], v[136:139], v[188:191], v[66:69]
	v_mfma_f32_16x16x32_bf16 v[82:85], v[140:143], v[188:191], v[82:85]
	v_mfma_f32_16x16x32_bf16 v[98:101], v[144:147], v[188:191], v[98:101]
	v_mfma_f32_16x16x32_bf16 v[114:117], v[148:151], v[188:191], v[114:117]
	s_waitcnt lgkmcnt(6)
	v_mfma_f32_16x16x32_bf16 v[70:73], v[136:139], v[196:199], v[70:73]
	v_mfma_f32_16x16x32_bf16 v[86:89], v[140:143], v[196:199], v[86:89]
	v_mfma_f32_16x16x32_bf16 v[102:105], v[144:147], v[196:199], v[102:105]
	v_mfma_f32_16x16x32_bf16 v[118:121], v[148:151], v[196:199], v[118:121]
	s_waitcnt lgkmcnt(5)
	v_mfma_f32_16x16x32_bf16 v[74:77], v[136:139], v[200:203], v[74:77]
	v_mfma_f32_16x16x32_bf16 v[90:93], v[140:143], v[200:203], v[90:93]
	v_mfma_f32_16x16x32_bf16 v[106:109], v[144:147], v[200:203], v[106:109]
	v_mfma_f32_16x16x32_bf16 v[122:125], v[148:151], v[200:203], v[122:125]
	s_waitcnt lgkmcnt(4)
	v_mfma_f32_16x16x32_bf16 v[78:81], v[136:139], v[204:207], v[78:81]
	v_mfma_f32_16x16x32_bf16 v[94:97], v[140:143], v[204:207], v[94:97]
	v_mfma_f32_16x16x32_bf16 v[110:113], v[144:147], v[204:207], v[110:113]
	v_mfma_f32_16x16x32_bf16 v[126:129], v[148:151], v[204:207], v[126:129]
	s_waitcnt lgkmcnt(3)
	v_mfma_f32_16x16x32_bf16 v[66:69], v[172:175], v[212:215], v[66:69]
	v_mfma_f32_16x16x32_bf16 v[82:85], v[176:179], v[212:215], v[82:85]
	v_mfma_f32_16x16x32_bf16 v[98:101], v[180:183], v[212:215], v[98:101]
	v_mfma_f32_16x16x32_bf16 v[114:117], v[184:187], v[212:215], v[114:117]
	s_waitcnt lgkmcnt(2)
	v_mfma_f32_16x16x32_bf16 v[70:73], v[172:175], v[216:219], v[70:73]
	v_mfma_f32_16x16x32_bf16 v[86:89], v[176:179], v[216:219], v[86:89]
	v_mfma_f32_16x16x32_bf16 v[102:105], v[180:183], v[216:219], v[102:105]
	v_mfma_f32_16x16x32_bf16 v[118:121], v[184:187], v[216:219], v[118:121]
	s_waitcnt lgkmcnt(1)
	v_mfma_f32_16x16x32_bf16 v[74:77], v[172:175], v[220:223], v[74:77]
	v_mfma_f32_16x16x32_bf16 v[90:93], v[176:179], v[220:223], v[90:93]
	v_mfma_f32_16x16x32_bf16 v[106:109], v[180:183], v[220:223], v[106:109]
	v_mfma_f32_16x16x32_bf16 v[122:125], v[184:187], v[220:223], v[122:125]
	s_waitcnt lgkmcnt(0)
	v_mfma_f32_16x16x32_bf16 v[78:81], v[172:175], v[224:227], v[78:81]
	v_mfma_f32_16x16x32_bf16 v[94:97], v[176:179], v[224:227], v[94:97]
	v_mfma_f32_16x16x32_bf16 v[110:113], v[180:183], v[224:227], v[110:113]
	v_mfma_f32_16x16x32_bf16 v[126:129], v[184:187], v[224:227], v[126:129]
	s_setprio 0
	v_add_u32_e32 v228, 0x80, v228
	v_add_u32_e32 v229, 0x80, v229
	v_add_u32_e32 v230, 0x80, v230
	v_add_u32_e32 v231, 0x80, v231
	s_waitcnt vmcnt(4)
	s_barrier
	s_setprio 3
	v_add_u32_e32 v234, s24, v232
	v_add_u32_e32 v236, s30, v232
	v_add_u32_e32 v235, s24, v233
	v_add_u32_e32 v237, s30, v233
	ds_read_b128 v[136:139], v234
	ds_read_b128 v[188:191], v236
	ds_read_b128 v[196:199], v236 offset:2048
	ds_read_b128 v[200:203], v236 offset:4096
	ds_read_b128 v[204:207], v236 offset:6144
	ds_read_b128 v[140:143], v234 offset:2048
	ds_read_b128 v[144:147], v234 offset:4096
	ds_read_b128 v[148:151], v234 offset:6144
	ds_read_b128 v[172:175], v235
	ds_read_b128 v[212:215], v237
	ds_read_b128 v[216:219], v237 offset:2048
	ds_read_b128 v[220:223], v237 offset:4096
	ds_read_b128 v[224:227], v237 offset:6144
	ds_read_b128 v[176:179], v235 offset:2048
	ds_read_b128 v[180:183], v235 offset:4096
	ds_read_b128 v[184:187], v235 offset:6144
	s_mov_b32 m0, s51
	s_nop 0
	global_load_lds_dwordx4 v228, s[44:45]
	s_add_i32 m0, s51, 0x400
	s_nop 0
	global_load_lds_dwordx4 v230, s[44:45]
	s_add_i32 m0, s51, 0x2000
	s_nop 0
	global_load_lds_dwordx4 v229, s[44:45]
	s_add_i32 m0, s51, 0x2400
	s_nop 0
	global_load_lds_dwordx4 v231, s[44:45]
	s_add_i32 m0, s51, 0x4000
	s_nop 0
	global_load_lds_dwordx4 v228, s[46:47]
	s_add_i32 m0, s51, 0x4400
	s_nop 0
	global_load_lds_dwordx4 v230, s[46:47]
	s_waitcnt lgkmcnt(11)
	s_setprio 1
	v_mfma_f32_16x16x32_bf16 v[2:5], v[136:139], v[188:191], v[2:5]
	v_mfma_f32_16x16x32_bf16 v[6:9], v[136:139], v[196:199], v[6:9]
	v_mfma_f32_16x16x32_bf16 v[10:13], v[136:139], v[200:203], v[10:13]
	v_mfma_f32_16x16x32_bf16 v[14:17], v[136:139], v[204:207], v[14:17]
	s_waitcnt lgkmcnt(10)
	v_mfma_f32_16x16x32_bf16 v[18:21], v[140:143], v[188:191], v[18:21]
	v_mfma_f32_16x16x32_bf16 v[22:25], v[140:143], v[196:199], v[22:25]
	v_mfma_f32_16x16x32_bf16 v[26:29], v[140:143], v[200:203], v[26:29]
	v_mfma_f32_16x16x32_bf16 v[30:33], v[140:143], v[204:207], v[30:33]
	s_waitcnt lgkmcnt(9)
	v_mfma_f32_16x16x32_bf16 v[34:37], v[144:147], v[188:191], v[34:37]
	v_mfma_f32_16x16x32_bf16 v[38:41], v[144:147], v[196:199], v[38:41]
	v_mfma_f32_16x16x32_bf16 v[42:45], v[144:147], v[200:203], v[42:45]
	v_mfma_f32_16x16x32_bf16 v[46:49], v[144:147], v[204:207], v[46:49]
	s_waitcnt lgkmcnt(8)
	v_mfma_f32_16x16x32_bf16 v[50:53], v[148:151], v[188:191], v[50:53]
	v_mfma_f32_16x16x32_bf16 v[54:57], v[148:151], v[196:199], v[54:57]
	v_mfma_f32_16x16x32_bf16 v[58:61], v[148:151], v[200:203], v[58:61]
	v_mfma_f32_16x16x32_bf16 v[62:65], v[148:151], v[204:207], v[62:65]
	s_waitcnt lgkmcnt(3)
	v_mfma_f32_16x16x32_bf16 v[2:5], v[172:175], v[212:215], v[2:5]
	v_mfma_f32_16x16x32_bf16 v[6:9], v[172:175], v[216:219], v[6:9]
	v_mfma_f32_16x16x32_bf16 v[10:13], v[172:175], v[220:223], v[10:13]
	v_mfma_f32_16x16x32_bf16 v[14:17], v[172:175], v[224:227], v[14:17]
	s_waitcnt lgkmcnt(2)
	v_mfma_f32_16x16x32_bf16 v[18:21], v[176:179], v[212:215], v[18:21]
	v_mfma_f32_16x16x32_bf16 v[22:25], v[176:179], v[216:219], v[22:25]
	v_mfma_f32_16x16x32_bf16 v[26:29], v[176:179], v[220:223], v[26:29]
	v_mfma_f32_16x16x32_bf16 v[30:33], v[176:179], v[224:227], v[30:33]
	s_waitcnt lgkmcnt(1)
	v_mfma_f32_16x16x32_bf16 v[34:37], v[180:183], v[212:215], v[34:37]
	v_mfma_f32_16x16x32_bf16 v[38:41], v[180:183], v[216:219], v[38:41]
	v_mfma_f32_16x16x32_bf16 v[42:45], v[180:183], v[220:223], v[42:45]
	v_mfma_f32_16x16x32_bf16 v[46:49], v[180:183], v[224:227], v[46:49]
	s_waitcnt lgkmcnt(0)
	v_mfma_f32_16x16x32_bf16 v[50:53], v[184:187], v[212:215], v[50:53]
	v_mfma_f32_16x16x32_bf16 v[54:57], v[184:187], v[216:219], v[54:57]
	v_mfma_f32_16x16x32_bf16 v[58:61], v[184:187], v[220:223], v[58:61]
	v_mfma_f32_16x16x32_bf16 v[62:65], v[184:187], v[224:227], v[62:65]
	s_setprio 0
	s_waitcnt vmcnt(6)
	s_barrier
	s_setprio 3
	v_add_u32_e32 v236, s42, v232
	v_add_u32_e32 v237, s42, v233
	ds_read_b128 v[188:191], v236
	ds_read_b128 v[196:199], v236 offset:2048
	ds_read_b128 v[200:203], v236 offset:4096
	ds_read_b128 v[204:207], v236 offset:6144
	ds_read_b128 v[212:215], v237
	ds_read_b128 v[216:219], v237 offset:2048
	ds_read_b128 v[220:223], v237 offset:4096
	ds_read_b128 v[224:227], v237 offset:6144
	s_add_i32 m0, s51, 0x6000
	s_nop 0
	global_load_lds_dwordx4 v229, s[46:47]
	s_add_i32 m0, s51, 0x6400
	s_nop 0
	global_load_lds_dwordx4 v231, s[46:47]
	s_add_i32 m0, s51, 0x8000
	s_nop 0
	global_load_lds_dwordx4 v228, s[48:49]
	s_add_i32 m0, s51, 0x8400
	s_nop 0
	global_load_lds_dwordx4 v230, s[48:49]
	s_add_i32 m0, s51, 0xa000
	s_nop 0
	global_load_lds_dwordx4 v229, s[48:49]
	s_add_i32 m0, s51, 0xa400
	s_nop 0
	global_load_lds_dwordx4 v231, s[48:49]
	s_waitcnt lgkmcnt(7)
	s_setprio 1
	v_mfma_f32_16x16x32_bf16 v[66:69], v[136:139], v[188:191], v[66:69]
	v_mfma_f32_16x16x32_bf16 v[82:85], v[140:143], v[188:191], v[82:85]
	v_mfma_f32_16x16x32_bf16 v[98:101], v[144:147], v[188:191], v[98:101]
	v_mfma_f32_16x16x32_bf16 v[114:117], v[148:151], v[188:191], v[114:117]
	s_waitcnt lgkmcnt(6)
	v_mfma_f32_16x16x32_bf16 v[70:73], v[136:139], v[196:199], v[70:73]
	v_mfma_f32_16x16x32_bf16 v[86:89], v[140:143], v[196:199], v[86:89]
	v_mfma_f32_16x16x32_bf16 v[102:105], v[144:147], v[196:199], v[102:105]
	v_mfma_f32_16x16x32_bf16 v[118:121], v[148:151], v[196:199], v[118:121]
	s_waitcnt lgkmcnt(5)
	v_mfma_f32_16x16x32_bf16 v[74:77], v[136:139], v[200:203], v[74:77]
	v_mfma_f32_16x16x32_bf16 v[90:93], v[140:143], v[200:203], v[90:93]
	v_mfma_f32_16x16x32_bf16 v[106:109], v[144:147], v[200:203], v[106:109]
	v_mfma_f32_16x16x32_bf16 v[122:125], v[148:151], v[200:203], v[122:125]
	s_waitcnt lgkmcnt(4)
	v_mfma_f32_16x16x32_bf16 v[78:81], v[136:139], v[204:207], v[78:81]
	v_mfma_f32_16x16x32_bf16 v[94:97], v[140:143], v[204:207], v[94:97]
	v_mfma_f32_16x16x32_bf16 v[110:113], v[144:147], v[204:207], v[110:113]
	v_mfma_f32_16x16x32_bf16 v[126:129], v[148:151], v[204:207], v[126:129]
	s_waitcnt lgkmcnt(3)
	v_mfma_f32_16x16x32_bf16 v[66:69], v[172:175], v[212:215], v[66:69]
	v_mfma_f32_16x16x32_bf16 v[82:85], v[176:179], v[212:215], v[82:85]
	v_mfma_f32_16x16x32_bf16 v[98:101], v[180:183], v[212:215], v[98:101]
	v_mfma_f32_16x16x32_bf16 v[114:117], v[184:187], v[212:215], v[114:117]
	s_waitcnt lgkmcnt(2)
	v_mfma_f32_16x16x32_bf16 v[70:73], v[172:175], v[216:219], v[70:73]
	v_mfma_f32_16x16x32_bf16 v[86:89], v[176:179], v[216:219], v[86:89]
	v_mfma_f32_16x16x32_bf16 v[102:105], v[180:183], v[216:219], v[102:105]
	v_mfma_f32_16x16x32_bf16 v[118:121], v[184:187], v[216:219], v[118:121]
	s_waitcnt lgkmcnt(1)
	v_mfma_f32_16x16x32_bf16 v[74:77], v[172:175], v[220:223], v[74:77]
	v_mfma_f32_16x16x32_bf16 v[90:93], v[176:179], v[220:223], v[90:93]
	v_mfma_f32_16x16x32_bf16 v[106:109], v[180:183], v[220:223], v[106:109]
	v_mfma_f32_16x16x32_bf16 v[122:125], v[184:187], v[220:223], v[122:125]
	s_waitcnt lgkmcnt(0)
	v_mfma_f32_16x16x32_bf16 v[78:81], v[172:175], v[224:227], v[78:81]
	v_mfma_f32_16x16x32_bf16 v[94:97], v[176:179], v[224:227], v[94:97]
	v_mfma_f32_16x16x32_bf16 v[110:113], v[180:183], v[224:227], v[110:113]
	v_mfma_f32_16x16x32_bf16 v[126:129], v[184:187], v[224:227], v[126:129]
	s_setprio 0
	v_add_u32_e32 v228, 0x80, v228
	v_add_u32_e32 v229, 0x80, v229
	v_add_u32_e32 v230, 0x80, v230
	v_add_u32_e32 v231, 0x80, v231
	s_waitcnt vmcnt(4)
	s_barrier
	s_add_i32 s52, s52, 1
	s_cmp_lt_u32 s52, 10
	s_cbranch_scc1 .Lgu2_loop
	s_setprio 3
	v_add_u32_e32 v234, s22, v232
	v_add_u32_e32 v236, s28, v232
	v_add_u32_e32 v235, s22, v233
	v_add_u32_e32 v237, s28, v233
	ds_read_b128 v[136:139], v234
	ds_read_b128 v[188:191], v236
	ds_read_b128 v[196:199], v236 offset:2048
	ds_read_b128 v[200:203], v236 offset:4096
	ds_read_b128 v[204:207], v236 offset:6144
	ds_read_b128 v[140:143], v234 offset:2048
	ds_read_b128 v[144:147], v234 offset:4096
	ds_read_b128 v[148:151], v234 offset:6144
	ds_read_b128 v[172:175], v235
	ds_read_b128 v[212:215], v237
	ds_read_b128 v[216:219], v237 offset:2048
	ds_read_b128 v[220:223], v237 offset:4096
	ds_read_b128 v[224:227], v237 offset:6144
	ds_read_b128 v[176:179], v235 offset:2048
	ds_read_b128 v[180:183], v235 offset:4096
	ds_read_b128 v[184:187], v235 offset:6144
	s_add_i32 m0, s51, 0xc000
	s_nop 0
	global_load_lds_dwordx4 v228, s[44:45]
	s_add_i32 m0, s51, 0xc400
	s_nop 0
	global_load_lds_dwordx4 v230, s[44:45]
	s_add_i32 m0, s51, 0xe000
	s_nop 0
	global_load_lds_dwordx4 v229, s[44:45]
	s_add_i32 m0, s51, 0xe400
	s_nop 0
	global_load_lds_dwordx4 v231, s[44:45]
	s_add_i32 m0, s51, 0x10000
	s_nop 0
	global_load_lds_dwordx4 v228, s[46:47]
	s_add_i32 m0, s51, 0x10400
	s_nop 0
	global_load_lds_dwordx4 v230, s[46:47]
	s_waitcnt lgkmcnt(11)
	s_setprio 1
	v_mfma_f32_16x16x32_bf16 v[2:5], v[136:139], v[188:191], v[2:5]
	v_mfma_f32_16x16x32_bf16 v[6:9], v[136:139], v[196:199], v[6:9]
	v_mfma_f32_16x16x32_bf16 v[10:13], v[136:139], v[200:203], v[10:13]
	v_mfma_f32_16x16x32_bf16 v[14:17], v[136:139], v[204:207], v[14:17]
	s_waitcnt lgkmcnt(10)
	v_mfma_f32_16x16x32_bf16 v[18:21], v[140:143], v[188:191], v[18:21]
	v_mfma_f32_16x16x32_bf16 v[22:25], v[140:143], v[196:199], v[22:25]
	v_mfma_f32_16x16x32_bf16 v[26:29], v[140:143], v[200:203], v[26:29]
	v_mfma_f32_16x16x32_bf16 v[30:33], v[140:143], v[204:207], v[30:33]
	s_waitcnt lgkmcnt(9)
	v_mfma_f32_16x16x32_bf16 v[34:37], v[144:147], v[188:191], v[34:37]
	v_mfma_f32_16x16x32_bf16 v[38:41], v[144:147], v[196:199], v[38:41]
	v_mfma_f32_16x16x32_bf16 v[42:45], v[144:147], v[200:203], v[42:45]
	v_mfma_f32_16x16x32_bf16 v[46:49], v[144:147], v[204:207], v[46:49]
	s_waitcnt lgkmcnt(8)
	v_mfma_f32_16x16x32_bf16 v[50:53], v[148:151], v[188:191], v[50:53]
	v_mfma_f32_16x16x32_bf16 v[54:57], v[148:151], v[196:199], v[54:57]
	v_mfma_f32_16x16x32_bf16 v[58:61], v[148:151], v[200:203], v[58:61]
	v_mfma_f32_16x16x32_bf16 v[62:65], v[148:151], v[204:207], v[62:65]
	s_waitcnt lgkmcnt(3)
	v_mfma_f32_16x16x32_bf16 v[2:5], v[172:175], v[212:215], v[2:5]
	v_mfma_f32_16x16x32_bf16 v[6:9], v[172:175], v[216:219], v[6:9]
	v_mfma_f32_16x16x32_bf16 v[10:13], v[172:175], v[220:223], v[10:13]
	v_mfma_f32_16x16x32_bf16 v[14:17], v[172:175], v[224:227], v[14:17]
	s_waitcnt lgkmcnt(2)
	v_mfma_f32_16x16x32_bf16 v[18:21], v[176:179], v[212:215], v[18:21]
	v_mfma_f32_16x16x32_bf16 v[22:25], v[176:179], v[216:219], v[22:25]
	v_mfma_f32_16x16x32_bf16 v[26:29], v[176:179], v[220:223], v[26:29]
	v_mfma_f32_16x16x32_bf16 v[30:33], v[176:179], v[224:227], v[30:33]
	s_waitcnt lgkmcnt(1)
	v_mfma_f32_16x16x32_bf16 v[34:37], v[180:183], v[212:215], v[34:37]
	v_mfma_f32_16x16x32_bf16 v[38:41], v[180:183], v[216:219], v[38:41]
	v_mfma_f32_16x16x32_bf16 v[42:45], v[180:183], v[220:223], v[42:45]
	v_mfma_f32_16x16x32_bf16 v[46:49], v[180:183], v[224:227], v[46:49]
	s_waitcnt lgkmcnt(0)
	v_mfma_f32_16x16x32_bf16 v[50:53], v[184:187], v[212:215], v[50:53]
	v_mfma_f32_16x16x32_bf16 v[54:57], v[184:187], v[216:219], v[54:57]
	v_mfma_f32_16x16x32_bf16 v[58:61], v[184:187], v[220:223], v[58:61]
	v_mfma_f32_16x16x32_bf16 v[62:65], v[184:187], v[224:227], v[62:65]
	s_setprio 0
	s_waitcnt vmcnt(6)
	s_barrier
	s_setprio 3
	v_add_u32_e32 v236, s40, v232
	v_add_u32_e32 v237, s40, v233
	ds_read_b128 v[188:191], v236
	ds_read_b128 v[196:199], v236 offset:2048
	ds_read_b128 v[200:203], v236 offset:4096
	ds_read_b128 v[204:207], v236 offset:6144
	ds_read_b128 v[212:215], v237
	ds_read_b128 v[216:219], v237 offset:2048
	ds_read_b128 v[220:223], v237 offset:4096
	ds_read_b128 v[224:227], v237 offset:6144
	s_mov_b32 m0, s51
	s_nop 0
	global_load_lds_dwordx4 v229, s[46:47]
	s_add_i32 m0, s51, 0x400
	s_nop 0
	global_load_lds_dwordx4 v231, s[46:47]
	s_add_i32 m0, s51, 0x2000
	s_nop 0
	global_load_lds_dwordx4 v228, s[48:49]
	s_add_i32 m0, s51, 0x2400
	s_nop 0
	global_load_lds_dwordx4 v230, s[48:49]
	s_add_i32 m0, s51, 0x4000
	s_nop 0
	global_load_lds_dwordx4 v229, s[48:49]
	s_add_i32 m0, s51, 0x4400
	s_nop 0
	global_load_lds_dwordx4 v231, s[48:49]
	s_waitcnt lgkmcnt(7)
	s_setprio 1
	v_mfma_f32_16x16x32_bf16 v[66:69], v[136:139], v[188:191], v[66:69]
	v_mfma_f32_16x16x32_bf16 v[82:85], v[140:143], v[188:191], v[82:85]
	v_mfma_f32_16x16x32_bf16 v[98:101], v[144:147], v[188:191], v[98:101]
	v_mfma_f32_16x16x32_bf16 v[114:117], v[148:151], v[188:191], v[114:117]
	s_waitcnt lgkmcnt(6)
	v_mfma_f32_16x16x32_bf16 v[70:73], v[136:139], v[196:199], v[70:73]
	v_mfma_f32_16x16x32_bf16 v[86:89], v[140:143], v[196:199], v[86:89]
	v_mfma_f32_16x16x32_bf16 v[102:105], v[144:147], v[196:199], v[102:105]
	v_mfma_f32_16x16x32_bf16 v[118:121], v[148:151], v[196:199], v[118:121]
	s_waitcnt lgkmcnt(5)
	v_mfma_f32_16x16x32_bf16 v[74:77], v[136:139], v[200:203], v[74:77]
	v_mfma_f32_16x16x32_bf16 v[90:93], v[140:143], v[200:203], v[90:93]
	v_mfma_f32_16x16x32_bf16 v[106:109], v[144:147], v[200:203], v[106:109]
	v_mfma_f32_16x16x32_bf16 v[122:125], v[148:151], v[200:203], v[122:125]
	s_waitcnt lgkmcnt(4)
	v_mfma_f32_16x16x32_bf16 v[78:81], v[136:139], v[204:207], v[78:81]
	v_mfma_f32_16x16x32_bf16 v[94:97], v[140:143], v[204:207], v[94:97]
	v_mfma_f32_16x16x32_bf16 v[110:113], v[144:147], v[204:207], v[110:113]
	v_mfma_f32_16x16x32_bf16 v[126:129], v[148:151], v[204:207], v[126:129]
	s_waitcnt lgkmcnt(3)
	v_mfma_f32_16x16x32_bf16 v[66:69], v[172:175], v[212:215], v[66:69]
	v_mfma_f32_16x16x32_bf16 v[82:85], v[176:179], v[212:215], v[82:85]
	v_mfma_f32_16x16x32_bf16 v[98:101], v[180:183], v[212:215], v[98:101]
	v_mfma_f32_16x16x32_bf16 v[114:117], v[184:187], v[212:215], v[114:117]
	s_waitcnt lgkmcnt(2)
	v_mfma_f32_16x16x32_bf16 v[70:73], v[172:175], v[216:219], v[70:73]
	v_mfma_f32_16x16x32_bf16 v[86:89], v[176:179], v[216:219], v[86:89]
	v_mfma_f32_16x16x32_bf16 v[102:105], v[180:183], v[216:219], v[102:105]
	v_mfma_f32_16x16x32_bf16 v[118:121], v[184:187], v[216:219], v[118:121]
	s_waitcnt lgkmcnt(1)
	v_mfma_f32_16x16x32_bf16 v[74:77], v[172:175], v[220:223], v[74:77]
	v_mfma_f32_16x16x32_bf16 v[90:93], v[176:179], v[220:223], v[90:93]
	v_mfma_f32_16x16x32_bf16 v[106:109], v[180:183], v[220:223], v[106:109]
	v_mfma_f32_16x16x32_bf16 v[122:125], v[184:187], v[220:223], v[122:125]
	s_waitcnt lgkmcnt(0)
	v_mfma_f32_16x16x32_bf16 v[78:81], v[172:175], v[224:227], v[78:81]
	v_mfma_f32_16x16x32_bf16 v[94:97], v[176:179], v[224:227], v[94:97]
	v_mfma_f32_16x16x32_bf16 v[110:113], v[180:183], v[224:227], v[110:113]
	v_mfma_f32_16x16x32_bf16 v[126:129], v[184:187], v[224:227], v[126:129]
	s_setprio 0
	v_add_u32_e32 v228, 0x80, v228
	v_add_u32_e32 v229, 0x80, v229
	v_add_u32_e32 v230, 0x80, v230
	v_add_u32_e32 v231, 0x80, v231
	s_waitcnt vmcnt(4)
	s_barrier
	s_setprio 3
	v_add_u32_e32 v234, s23, v232
	v_add_u32_e32 v236, s29, v232
	v_add_u32_e32 v235, s23, v233
	v_add_u32_e32 v237, s29, v233
	ds_read_b128 v[136:139], v234
	ds_read_b128 v[188:191], v236
	ds_read_b128 v[196:199], v236 offset:2048
	ds_read_b128 v[200:203], v236 offset:4096
	ds_read_b128 v[204:207], v236 offset:6144
	ds_read_b128 v[140:143], v234 offset:2048
	ds_read_b128 v[144:147], v234 offset:4096
	ds_read_b128 v[148:151], v234 offset:6144
	ds_read_b128 v[172:175], v235
	ds_read_b128 v[212:215], v237
	ds_read_b128 v[216:219], v237 offset:2048
	ds_read_b128 v[220:223], v237 offset:4096
	ds_read_b128 v[224:227], v237 offset:6144
	ds_read_b128 v[176:179], v235 offset:2048
	ds_read_b128 v[180:183], v235 offset:4096
	ds_read_b128 v[184:187], v235 offset:6144
	s_waitcnt lgkmcnt(11)
	s_setprio 1
	v_mfma_f32_16x16x32_bf16 v[2:5], v[136:139], v[188:191], v[2:5]
	v_mfma_f32_16x16x32_bf16 v[6:9], v[136:139], v[196:199], v[6:9]
	v_mfma_f32_16x16x32_bf16 v[10:13], v[136:139], v[200:203], v[10:13]
	v_mfma_f32_16x16x32_bf16 v[14:17], v[136:139], v[204:207], v[14:17]
	s_waitcnt lgkmcnt(10)
	v_mfma_f32_16x16x32_bf16 v[18:21], v[140:143], v[188:191], v[18:21]
	v_mfma_f32_16x16x32_bf16 v[22:25], v[140:143], v[196:199], v[22:25]
	v_mfma_f32_16x16x32_bf16 v[26:29], v[140:143], v[200:203], v[26:29]
	v_mfma_f32_16x16x32_bf16 v[30:33], v[140:143], v[204:207], v[30:33]
	s_waitcnt lgkmcnt(9)
	v_mfma_f32_16x16x32_bf16 v[34:37], v[144:147], v[188:191], v[34:37]
	v_mfma_f32_16x16x32_bf16 v[38:41], v[144:147], v[196:199], v[38:41]
	v_mfma_f32_16x16x32_bf16 v[42:45], v[144:147], v[200:203], v[42:45]
	v_mfma_f32_16x16x32_bf16 v[46:49], v[144:147], v[204:207], v[46:49]
	s_waitcnt lgkmcnt(8)
	v_mfma_f32_16x16x32_bf16 v[50:53], v[148:151], v[188:191], v[50:53]
	v_mfma_f32_16x16x32_bf16 v[54:57], v[148:151], v[196:199], v[54:57]
	v_mfma_f32_16x16x32_bf16 v[58:61], v[148:151], v[200:203], v[58:61]
	v_mfma_f32_16x16x32_bf16 v[62:65], v[148:151], v[204:207], v[62:65]
	s_waitcnt lgkmcnt(3)
	v_mfma_f32_16x16x32_bf16 v[2:5], v[172:175], v[212:215], v[2:5]
	v_mfma_f32_16x16x32_bf16 v[6:9], v[172:175], v[216:219], v[6:9]
	v_mfma_f32_16x16x32_bf16 v[10:13], v[172:175], v[220:223], v[10:13]
	v_mfma_f32_16x16x32_bf16 v[14:17], v[172:175], v[224:227], v[14:17]
	s_waitcnt lgkmcnt(2)
	v_mfma_f32_16x16x32_bf16 v[18:21], v[176:179], v[212:215], v[18:21]
	v_mfma_f32_16x16x32_bf16 v[22:25], v[176:179], v[216:219], v[22:25]
	v_mfma_f32_16x16x32_bf16 v[26:29], v[176:179], v[220:223], v[26:29]
	v_mfma_f32_16x16x32_bf16 v[30:33], v[176:179], v[224:227], v[30:33]
	s_waitcnt lgkmcnt(1)
	v_mfma_f32_16x16x32_bf16 v[34:37], v[180:183], v[212:215], v[34:37]
	v_mfma_f32_16x16x32_bf16 v[38:41], v[180:183], v[216:219], v[38:41]
	v_mfma_f32_16x16x32_bf16 v[42:45], v[180:183], v[220:223], v[42:45]
	v_mfma_f32_16x16x32_bf16 v[46:49], v[180:183], v[224:227], v[46:49]
	s_waitcnt lgkmcnt(0)
	v_mfma_f32_16x16x32_bf16 v[50:53], v[184:187], v[212:215], v[50:53]
	v_mfma_f32_16x16x32_bf16 v[54:57], v[184:187], v[216:219], v[54:57]
	v_mfma_f32_16x16x32_bf16 v[58:61], v[184:187], v[220:223], v[58:61]
	v_mfma_f32_16x16x32_bf16 v[62:65], v[184:187], v[224:227], v[62:65]
	s_setprio 0
	s_waitcnt vmcnt(0)
	s_barrier
	s_setprio 3
	v_add_u32_e32 v236, s41, v232
	v_add_u32_e32 v237, s41, v233
	ds_read_b128 v[188:191], v236
	ds_read_b128 v[196:199], v236 offset:2048
	ds_read_b128 v[200:203], v236 offset:4096
	ds_read_b128 v[204:207], v236 offset:6144
	ds_read_b128 v[212:215], v237
	ds_read_b128 v[216:219], v237 offset:2048
	ds_read_b128 v[220:223], v237 offset:4096
	ds_read_b128 v[224:227], v237 offset:6144
	s_waitcnt lgkmcnt(7)
	s_setprio 1
	v_mfma_f32_16x16x32_bf16 v[66:69], v[136:139], v[188:191], v[66:69]
	v_mfma_f32_16x16x32_bf16 v[82:85], v[140:143], v[188:191], v[82:85]
	v_mfma_f32_16x16x32_bf16 v[98:101], v[144:147], v[188:191], v[98:101]
	v_mfma_f32_16x16x32_bf16 v[114:117], v[148:151], v[188:191], v[114:117]
	s_waitcnt lgkmcnt(6)
	v_mfma_f32_16x16x32_bf16 v[70:73], v[136:139], v[196:199], v[70:73]
	v_mfma_f32_16x16x32_bf16 v[86:89], v[140:143], v[196:199], v[86:89]
	v_mfma_f32_16x16x32_bf16 v[102:105], v[144:147], v[196:199], v[102:105]
	v_mfma_f32_16x16x32_bf16 v[118:121], v[148:151], v[196:199], v[118:121]
	s_waitcnt lgkmcnt(5)
	v_mfma_f32_16x16x32_bf16 v[74:77], v[136:139], v[200:203], v[74:77]
	v_mfma_f32_16x16x32_bf16 v[90:93], v[140:143], v[200:203], v[90:93]
	v_mfma_f32_16x16x32_bf16 v[106:109], v[144:147], v[200:203], v[106:109]
	v_mfma_f32_16x16x32_bf16 v[122:125], v[148:151], v[200:203], v[122:125]
	s_waitcnt lgkmcnt(4)
	v_mfma_f32_16x16x32_bf16 v[78:81], v[136:139], v[204:207], v[78:81]
	v_mfma_f32_16x16x32_bf16 v[94:97], v[140:143], v[204:207], v[94:97]
	v_mfma_f32_16x16x32_bf16 v[110:113], v[144:147], v[204:207], v[110:113]
	v_mfma_f32_16x16x32_bf16 v[126:129], v[148:151], v[204:207], v[126:129]
	s_waitcnt lgkmcnt(3)
	v_mfma_f32_16x16x32_bf16 v[66:69], v[172:175], v[212:215], v[66:69]
	v_mfma_f32_16x16x32_bf16 v[82:85], v[176:179], v[212:215], v[82:85]
	v_mfma_f32_16x16x32_bf16 v[98:101], v[180:183], v[212:215], v[98:101]
	v_mfma_f32_16x16x32_bf16 v[114:117], v[184:187], v[212:215], v[114:117]
	s_waitcnt lgkmcnt(2)
	v_mfma_f32_16x16x32_bf16 v[70:73], v[172:175], v[216:219], v[70:73]
	v_mfma_f32_16x16x32_bf16 v[86:89], v[176:179], v[216:219], v[86:89]
	v_mfma_f32_16x16x32_bf16 v[102:105], v[180:183], v[216:219], v[102:105]
	v_mfma_f32_16x16x32_bf16 v[118:121], v[184:187], v[216:219], v[118:121]
	s_waitcnt lgkmcnt(1)
	v_mfma_f32_16x16x32_bf16 v[74:77], v[172:175], v[220:223], v[74:77]
	v_mfma_f32_16x16x32_bf16 v[90:93], v[176:179], v[220:223], v[90:93]
	v_mfma_f32_16x16x32_bf16 v[106:109], v[180:183], v[220:223], v[106:109]
	v_mfma_f32_16x16x32_bf16 v[122:125], v[184:187], v[220:223], v[122:125]
	s_waitcnt lgkmcnt(0)
	v_mfma_f32_16x16x32_bf16 v[78:81], v[172:175], v[224:227], v[78:81]
	v_mfma_f32_16x16x32_bf16 v[94:97], v[176:179], v[224:227], v[94:97]
	v_mfma_f32_16x16x32_bf16 v[110:113], v[180:183], v[224:227], v[110:113]
	v_mfma_f32_16x16x32_bf16 v[126:129], v[184:187], v[224:227], v[126:129]
	s_setprio 0
	s_nop 7
	s_barrier
	s_mul_i32 s43, s53, 0x2c80
	s_add_i32 s43, s43, s54
	s_add_i32 s55, s55, 1
	s_cmp_lt_u32 s55, 5
	s_cbranch_scc0 .Lgu2_nonext
	s_load_dwordx2 s[44:45], s[12:13], 0x160
	s_load_dwordx2 s[46:47], s[12:13], 0x130
	s_bfe_u32 s53, s21, 0x30006
	s_lshl_b32 s53, s53, 3
	s_and_b32 s56, s21, 7
	s_or_b32 s53, s53, s56
	s_lshl_b32 s53, s53, 7
	s_bfe_u32 s54, s21, 0x30003
	s_lshl_b32 s56, s55, 4
	s_add_i32 s54, s54, s56
	s_lshl_b32 s54, s54, 7
	v_lshrrev_b32_e32 v196, 6, v131
	v_and_b32_e32 v197, 63, v131
	s_nop 0
	v_readfirstlane_b32 s50, v196
	v_lshrrev_b32_e32 v196, 3, v197
	v_lshrrev_b32_e32 v198, 4, v197
	v_and_b32_e32 v199, 7, v197
	s_movk_i32 s56, 0x1080
	v_xor_b32_e32 v200, v199, v198
	v_lshlrev_b32_e32 v200, 4, v200
	v_mad_u32_u24 v228, v196, s56, v200
	v_or_b32_e32 v198, 4, v198
	v_xor_b32_e32 v200, v199, v198
	v_lshlrev_b32_e32 v200, 4, v200
	v_add_u32_e32 v196, 8, v196
	v_mad_u32_u24 v230, v196, s56, v200
	v_add_u32_e32 v229, 0x42000, v228
	v_add_u32_e32 v231, 0x42000, v230
	v_and_b32_e32 v196, 15, v197
	v_lshrrev_b32_e32 v198, 4, v197
	v_bfe_u32 v199, v197, 1, 3
	v_xor_b32_e32 v199, v198, v199
	v_lshlrev_b32_e32 v199, 4, v199
	v_lshl_or_b32 v232, v196, 7, v199
	v_xor_b32_e32 v233, 64, v232
	s_lshr_b32 s56, s50, 1
	s_and_b32 s57, s50, 1
	s_mul_i32 s0, s56, 64*528
	s_lshl_b32 s52, s57, 8
	s_add_i32 s0, s0, s52
	s_add_i32 s0, s0, 16
	v_mul_u32_u24_e32 v198, 4*528, v198
	v_lshl_add_u32 v198, v196, 2, v198
	v_add_u32_e32 v238, s0, v198
	s_add_i32 s22, s56, 0
	s_lshl_b32 s22, s22, 13
	s_add_i32 s22, s22, 16
	s_add_i32 s28, s57, 2
	s_lshl_b32 s28, s28, 13
	s_add_i32 s28, s28, 16
	s_add_i32 s40, s57, 4
	s_lshl_b32 s40, s40, 13
	s_add_i32 s40, s40, 16
	s_add_i32 s23, s56, 6
	s_lshl_b32 s23, s23, 13
	s_add_i32 s23, s23, 16
	s_add_i32 s29, s57, 8
	s_cmp_ge_u32 s29, 9
	s_cselect_b32 s0, 9, 0
	s_sub_i32 s29, s29, s0
	s_lshl_b32 s29, s29, 13
	s_add_i32 s29, s29, 16
	s_add_i32 s41, s57, 1
	s_lshl_b32 s41, s41, 13
	s_add_i32 s41, s41, 16
	s_add_i32 s24, s56, 3
	s_lshl_b32 s24, s24, 13
	s_add_i32 s24, s24, 16
	s_add_i32 s30, s57, 5
	s_lshl_b32 s30, s30, 13
	s_add_i32 s30, s30, 16
	s_add_i32 s42, s57, 7
	s_lshl_b32 s42, s42, 13
	s_add_i32 s42, s42, 16
	s_lshl_b32 s56, s50, 4
	s_add_i32 s57, s53, s56
	s_add_i32 s56, s54, s56
	s_mul_i32 s57, s57, 0x1080
	s_mul_i32 s56, s56, 0x1080
	s_waitcnt lgkmcnt(0)
	s_add_u32 s44, s44, s57
	s_addc_u32 s45, s45, 0
	s_add_u32 s46, s46, s56
	s_addc_u32 s47, s47, 0
	s_add_u32 s48, s46, 0x420000
	s_addc_u32 s49, s47, 0
	s_lshl_b32 s51, s50, 11
	s_add_i32 s51, s51, 16
	s_mov_b32 m0, s51
	s_nop 0
	global_load_lds_dwordx4 v228, s[44:45]
	s_add_i32 m0, s51, 0x400
	s_nop 0
	global_load_lds_dwordx4 v230, s[44:45]
	s_add_i32 m0, s51, 0x2000
	s_nop 0
	global_load_lds_dwordx4 v229, s[44:45]
	s_add_i32 m0, s51, 0x2400
	s_nop 0
	global_load_lds_dwordx4 v231, s[44:45]
	s_add_i32 m0, s51, 0x4000
	s_nop 0
	global_load_lds_dwordx4 v228, s[46:47]
	s_add_i32 m0, s51, 0x4400
	s_nop 0
	global_load_lds_dwordx4 v230, s[46:47]
	s_add_i32 m0, s51, 0x6000
	s_nop 0
	global_load_lds_dwordx4 v229, s[46:47]
	s_add_i32 m0, s51, 0x6400
	s_nop 0
	global_load_lds_dwordx4 v231, s[46:47]
	s_add_i32 m0, s51, 0x8000
	s_nop 0
	global_load_lds_dwordx4 v228, s[48:49]
	s_add_i32 m0, s51, 0x8400
	s_nop 0
	global_load_lds_dwordx4 v230, s[48:49]
	s_add_i32 m0, s51, 0xa000
	s_nop 0
	global_load_lds_dwordx4 v229, s[48:49]
	s_add_i32 m0, s51, 0xa400
	s_nop 0
	global_load_lds_dwordx4 v231, s[48:49]
	v_add_u32_e32 v228, 0x80, v228
	v_add_u32_e32 v229, 0x80, v229
	v_add_u32_e32 v230, 0x80, v230
	v_add_u32_e32 v231, 0x80, v231
.Lgu2_nonext:
	s_load_dwordx2 s[58:59], s[12:13], 0x180
	v_mov_b32_e32 v241, 0x3a000000
	v_mov_b32_e32 v242, 0x358637bd
	v_fma_f32 v152, v152, v241, v242
	v_fma_f32 v153, v153, v241, v242
	v_fma_f32 v154, v154, v241, v242
	v_fma_f32 v155, v155, v241, v242
	v_fma_f32 v244, v244, v241, v242
	v_fma_f32 v245, v245, v241, v242
	v_fma_f32 v246, v246, v241, v242
	v_fma_f32 v247, v247, v241, v242
	v_fma_f32 v248, v248, v241, v242
	v_fma_f32 v249, v249, v241, v242
	v_fma_f32 v250, v250, v241, v242
	v_fma_f32 v251, v251, v241, v242
	v_fma_f32 v252, v252, v241, v242
	v_fma_f32 v253, v253, v241, v242
	v_fma_f32 v254, v254, v241, v242
	v_fma_f32 v255, v255, v241, v242
	v_rsq_f32_e32 v152, v152
	v_rsq_f32_e32 v153, v153
	v_rsq_f32_e32 v154, v154
	v_rsq_f32_e32 v155, v155
	v_rsq_f32_e32 v244, v244
	v_rsq_f32_e32 v245, v245
	v_rsq_f32_e32 v246, v246
	v_rsq_f32_e32 v247, v247
	v_rsq_f32_e32 v248, v248
	v_rsq_f32_e32 v249, v249
	v_rsq_f32_e32 v250, v250
	v_rsq_f32_e32 v251, v251
	v_rsq_f32_e32 v252, v252
	v_rsq_f32_e32 v253, v253
	v_rsq_f32_e32 v254, v254
	v_rsq_f32_e32 v255, v255
	v_and_b32_e32 v241, 63, v131
	v_lshrrev_b32_e32 v242, 4, v241
	v_and_b32_e32 v241, 15, v241
	s_lshr_b32 s56, s50, 1
	s_and_b32 s57, s50, 1
	s_mul_i32 s56, s56, 64*144
	s_lshl_b32 s57, s57, 6
	s_add_i32 s56, s56, s57
	s_add_i32 s56, s56, 49168
	v_mul_u32_u24_e32 v242, 4*144, v242
	v_lshl_add_u32 v242, v241, 1, v242
	v_add_u32_e32 v188, s56, v242
	v_lshrrev_b32_e32 v241, 3, v131
	v_and_b32_e32 v242, 7, v131
	v_lshlrev_b32_e32 v242, 4, v242
	v_mul_u32_u24_e32 v189, 144, v241
	s_mov_b32 s57, 0xc010
	v_add3_u32 v189, v189, v242, s57
	s_movk_i32 s56, 0x2c80
	v_mad_u32_u24 v243, v241, s56, v242
	s_mov_b32 s56, s43
	s_waitcnt lgkmcnt(0)
	s_add_u32 s58, s58, s56
	s_addc_u32 s59, s59, 0
	v_mul_f32_e32 v2, v2, v152
	v_mul_f32_e32 v6, v6, v152
	v_mul_f32_e32 v10, v10, v152
	v_mul_f32_e32 v14, v14, v152
	v_mul_f32_e32 v136, 0xbfb8aa3b, v2
	v_mul_f32_e32 v137, 0xbfb8aa3b, v6
	v_exp_f32_e32 v136, v136
	v_exp_f32_e32 v137, v137
	v_mul_f32_e32 v10, v10, v2
	v_mul_f32_e32 v14, v14, v6
	v_add_f32_e32 v136, 1.0, v136
	v_add_f32_e32 v137, 1.0, v137
	v_rcp_f32_e32 v136, v136
	v_rcp_f32_e32 v137, v137
	s_nop 0
	v_mul_f32_e32 v10, v10, v136
	v_mul_f32_e32 v14, v14, v137
	v_cvt_pk_bf16_f32 v10, v10, v14
	ds_write_b16 v188, v10
	ds_write_b16_d16_hi v188, v10 offset:32
	v_mul_f32_e32 v3, v3, v153
	v_mul_f32_e32 v7, v7, v153
	v_mul_f32_e32 v11, v11, v153
	v_mul_f32_e32 v15, v15, v153
	v_mul_f32_e32 v136, 0xbfb8aa3b, v3
	v_mul_f32_e32 v137, 0xbfb8aa3b, v7
	v_exp_f32_e32 v136, v136
	v_exp_f32_e32 v137, v137
	v_mul_f32_e32 v11, v11, v3
	v_mul_f32_e32 v15, v15, v7
	v_add_f32_e32 v136, 1.0, v136
	v_add_f32_e32 v137, 1.0, v137
	v_rcp_f32_e32 v136, v136
	v_rcp_f32_e32 v137, v137
	s_nop 0
	v_mul_f32_e32 v11, v11, v136
	v_mul_f32_e32 v15, v15, v137
	v_cvt_pk_bf16_f32 v11, v11, v15
	ds_write_b16 v188, v11 offset:144
	ds_write_b16_d16_hi v188, v11 offset:176
	v_mul_f32_e32 v4, v4, v154
	v_mul_f32_e32 v8, v8, v154
	v_mul_f32_e32 v12, v12, v154
	v_mul_f32_e32 v16, v16, v154
	v_mul_f32_e32 v136, 0xbfb8aa3b, v4
	v_mul_f32_e32 v137, 0xbfb8aa3b, v8
	v_exp_f32_e32 v136, v136
	v_exp_f32_e32 v137, v137
	v_mul_f32_e32 v12, v12, v4
	v_mul_f32_e32 v16, v16, v8
	v_add_f32_e32 v136, 1.0, v136
	v_add_f32_e32 v137, 1.0, v137
	v_rcp_f32_e32 v136, v136
	v_rcp_f32_e32 v137, v137
	s_nop 0
	v_mul_f32_e32 v12, v12, v136
	v_mul_f32_e32 v16, v16, v137
	v_cvt_pk_bf16_f32 v12, v12, v16
	ds_write_b16 v188, v12 offset:288
	ds_write_b16_d16_hi v188, v12 offset:320
	v_mul_f32_e32 v5, v5, v155
	v_mul_f32_e32 v9, v9, v155
	v_mul_f32_e32 v13, v13, v155
	v_mul_f32_e32 v17, v17, v155
	v_mul_f32_e32 v136, 0xbfb8aa3b, v5
	v_mul_f32_e32 v137, 0xbfb8aa3b, v9
	v_exp_f32_e32 v136, v136
	v_exp_f32_e32 v137, v137
	v_mul_f32_e32 v13, v13, v5
	v_mul_f32_e32 v17, v17, v9
	v_add_f32_e32 v136, 1.0, v136
	v_add_f32_e32 v137, 1.0, v137
	v_rcp_f32_e32 v136, v136
	v_rcp_f32_e32 v137, v137
	s_nop 0
	v_mul_f32_e32 v13, v13, v136
	v_mul_f32_e32 v17, v17, v137
	v_cvt_pk_bf16_f32 v13, v13, v17
	ds_write_b16 v188, v13 offset:432
	ds_write_b16_d16_hi v188, v13 offset:464
	v_mul_f32_e32 v18, v18, v244
	v_mul_f32_e32 v22, v22, v244
	v_mul_f32_e32 v26, v26, v244
	v_mul_f32_e32 v30, v30, v244
	v_mul_f32_e32 v136, 0xbfb8aa3b, v18
	v_mul_f32_e32 v137, 0xbfb8aa3b, v22
	v_exp_f32_e32 v136, v136
	v_exp_f32_e32 v137, v137
	v_mul_f32_e32 v26, v26, v18
	v_mul_f32_e32 v30, v30, v22
	v_add_f32_e32 v136, 1.0, v136
	v_add_f32_e32 v137, 1.0, v137
	v_rcp_f32_e32 v136, v136
	v_rcp_f32_e32 v137, v137
	s_nop 0
	v_mul_f32_e32 v26, v26, v136
	v_mul_f32_e32 v30, v30, v137
	v_cvt_pk_bf16_f32 v26, v26, v30
	ds_write_b16 v188, v26 offset:2304
	ds_write_b16_d16_hi v188, v26 offset:2336
	v_mul_f32_e32 v19, v19, v245
	v_mul_f32_e32 v23, v23, v245
	v_mul_f32_e32 v27, v27, v245
	v_mul_f32_e32 v31, v31, v245
	v_mul_f32_e32 v136, 0xbfb8aa3b, v19
	v_mul_f32_e32 v137, 0xbfb8aa3b, v23
	v_exp_f32_e32 v136, v136
	v_exp_f32_e32 v137, v137
	v_mul_f32_e32 v27, v27, v19
	v_mul_f32_e32 v31, v31, v23
	v_add_f32_e32 v136, 1.0, v136
	v_add_f32_e32 v137, 1.0, v137
	v_rcp_f32_e32 v136, v136
	v_rcp_f32_e32 v137, v137
	s_nop 0
	v_mul_f32_e32 v27, v27, v136
	v_mul_f32_e32 v31, v31, v137
	v_cvt_pk_bf16_f32 v27, v27, v31
	ds_write_b16 v188, v27 offset:2448
	ds_write_b16_d16_hi v188, v27 offset:2480
	v_mul_f32_e32 v20, v20, v246
	v_mul_f32_e32 v24, v24, v246
	v_mul_f32_e32 v28, v28, v246
	v_mul_f32_e32 v32, v32, v246
	v_mul_f32_e32 v136, 0xbfb8aa3b, v20
	v_mul_f32_e32 v137, 0xbfb8aa3b, v24
	v_exp_f32_e32 v136, v136
	v_exp_f32_e32 v137, v137
	v_mul_f32_e32 v28, v28, v20
	v_mul_f32_e32 v32, v32, v24
	v_add_f32_e32 v136, 1.0, v136
	v_add_f32_e32 v137, 1.0, v137
	v_rcp_f32_e32 v136, v136
	v_rcp_f32_e32 v137, v137
	s_nop 0
	v_mul_f32_e32 v28, v28, v136
	v_mul_f32_e32 v32, v32, v137
	v_cvt_pk_bf16_f32 v28, v28, v32
	ds_write_b16 v188, v28 offset:2592
	ds_write_b16_d16_hi v188, v28 offset:2624
	v_mul_f32_e32 v21, v21, v247
	v_mul_f32_e32 v25, v25, v247
	v_mul_f32_e32 v29, v29, v247
	v_mul_f32_e32 v33, v33, v247
	v_mul_f32_e32 v136, 0xbfb8aa3b, v21
	v_mul_f32_e32 v137, 0xbfb8aa3b, v25
	v_exp_f32_e32 v136, v136
	v_exp_f32_e32 v137, v137
	v_mul_f32_e32 v29, v29, v21
	v_mul_f32_e32 v33, v33, v25
	v_add_f32_e32 v136, 1.0, v136
	v_add_f32_e32 v137, 1.0, v137
	v_rcp_f32_e32 v136, v136
	v_rcp_f32_e32 v137, v137
	s_nop 0
	v_mul_f32_e32 v29, v29, v136
	v_mul_f32_e32 v33, v33, v137
	v_cvt_pk_bf16_f32 v29, v29, v33
	ds_write_b16 v188, v29 offset:2736
	ds_write_b16_d16_hi v188, v29 offset:2768
	v_mul_f32_e32 v34, v34, v248
	v_mul_f32_e32 v38, v38, v248
	v_mul_f32_e32 v42, v42, v248
	v_mul_f32_e32 v46, v46, v248
	v_mul_f32_e32 v136, 0xbfb8aa3b, v34
	v_mul_f32_e32 v137, 0xbfb8aa3b, v38
	v_exp_f32_e32 v136, v136
	v_exp_f32_e32 v137, v137
	v_mul_f32_e32 v42, v42, v34
	v_mul_f32_e32 v46, v46, v38
	v_add_f32_e32 v136, 1.0, v136
	v_add_f32_e32 v137, 1.0, v137
	v_rcp_f32_e32 v136, v136
	v_rcp_f32_e32 v137, v137
	s_nop 0
	v_mul_f32_e32 v42, v42, v136
	v_mul_f32_e32 v46, v46, v137
	v_cvt_pk_bf16_f32 v42, v42, v46
	ds_write_b16 v188, v42 offset:4608
	ds_write_b16_d16_hi v188, v42 offset:4640
	v_mul_f32_e32 v35, v35, v249
	v_mul_f32_e32 v39, v39, v249
	v_mul_f32_e32 v43, v43, v249
	v_mul_f32_e32 v47, v47, v249
	v_mul_f32_e32 v136, 0xbfb8aa3b, v35
	v_mul_f32_e32 v137, 0xbfb8aa3b, v39
	v_exp_f32_e32 v136, v136
	v_exp_f32_e32 v137, v137
	v_mul_f32_e32 v43, v43, v35
	v_mul_f32_e32 v47, v47, v39
	v_add_f32_e32 v136, 1.0, v136
	v_add_f32_e32 v137, 1.0, v137
	v_rcp_f32_e32 v136, v136
	v_rcp_f32_e32 v137, v137
	s_nop 0
	v_mul_f32_e32 v43, v43, v136
	v_mul_f32_e32 v47, v47, v137
	v_cvt_pk_bf16_f32 v43, v43, v47
	ds_write_b16 v188, v43 offset:4752
	ds_write_b16_d16_hi v188, v43 offset:4784
	v_mul_f32_e32 v36, v36, v250
	v_mul_f32_e32 v40, v40, v250
	v_mul_f32_e32 v44, v44, v250
	v_mul_f32_e32 v48, v48, v250
	v_mul_f32_e32 v136, 0xbfb8aa3b, v36
	v_mul_f32_e32 v137, 0xbfb8aa3b, v40
	v_exp_f32_e32 v136, v136
	v_exp_f32_e32 v137, v137
	v_mul_f32_e32 v44, v44, v36
	v_mul_f32_e32 v48, v48, v40
	v_add_f32_e32 v136, 1.0, v136
	v_add_f32_e32 v137, 1.0, v137
	v_rcp_f32_e32 v136, v136
	v_rcp_f32_e32 v137, v137
	s_nop 0
	v_mul_f32_e32 v44, v44, v136
	v_mul_f32_e32 v48, v48, v137
	v_cvt_pk_bf16_f32 v44, v44, v48
	ds_write_b16 v188, v44 offset:4896
	ds_write_b16_d16_hi v188, v44 offset:4928
	v_mul_f32_e32 v37, v37, v251
	v_mul_f32_e32 v41, v41, v251
	v_mul_f32_e32 v45, v45, v251
	v_mul_f32_e32 v49, v49, v251
	v_mul_f32_e32 v136, 0xbfb8aa3b, v37
	v_mul_f32_e32 v137, 0xbfb8aa3b, v41
	v_exp_f32_e32 v136, v136
	v_exp_f32_e32 v137, v137
	v_mul_f32_e32 v45, v45, v37
	v_mul_f32_e32 v49, v49, v41
	v_add_f32_e32 v136, 1.0, v136
	v_add_f32_e32 v137, 1.0, v137
	v_rcp_f32_e32 v136, v136
	v_rcp_f32_e32 v137, v137
	s_nop 0
	v_mul_f32_e32 v45, v45, v136
	v_mul_f32_e32 v49, v49, v137
	v_cvt_pk_bf16_f32 v45, v45, v49
	ds_write_b16 v188, v45 offset:5040
	ds_write_b16_d16_hi v188, v45 offset:5072
	v_mul_f32_e32 v50, v50, v252
	v_mul_f32_e32 v54, v54, v252
	v_mul_f32_e32 v58, v58, v252
	v_mul_f32_e32 v62, v62, v252
	v_mul_f32_e32 v136, 0xbfb8aa3b, v50
	v_mul_f32_e32 v137, 0xbfb8aa3b, v54
	v_exp_f32_e32 v136, v136
	v_exp_f32_e32 v137, v137
	v_mul_f32_e32 v58, v58, v50
	v_mul_f32_e32 v62, v62, v54
	v_add_f32_e32 v136, 1.0, v136
	v_add_f32_e32 v137, 1.0, v137
	v_rcp_f32_e32 v136, v136
	v_rcp_f32_e32 v137, v137
	s_nop 0
	v_mul_f32_e32 v58, v58, v136
	v_mul_f32_e32 v62, v62, v137
	v_cvt_pk_bf16_f32 v58, v58, v62
	ds_write_b16 v188, v58 offset:6912
	ds_write_b16_d16_hi v188, v58 offset:6944
	v_mul_f32_e32 v51, v51, v253
	v_mul_f32_e32 v55, v55, v253
	v_mul_f32_e32 v59, v59, v253
	v_mul_f32_e32 v63, v63, v253
	v_mul_f32_e32 v136, 0xbfb8aa3b, v51
	v_mul_f32_e32 v137, 0xbfb8aa3b, v55
	v_exp_f32_e32 v136, v136
	v_exp_f32_e32 v137, v137
	v_mul_f32_e32 v59, v59, v51
	v_mul_f32_e32 v63, v63, v55
	v_add_f32_e32 v136, 1.0, v136
	v_add_f32_e32 v137, 1.0, v137
	v_rcp_f32_e32 v136, v136
	v_rcp_f32_e32 v137, v137
	s_nop 0
	v_mul_f32_e32 v59, v59, v136
	v_mul_f32_e32 v63, v63, v137
	v_cvt_pk_bf16_f32 v59, v59, v63
	ds_write_b16 v188, v59 offset:7056
	ds_write_b16_d16_hi v188, v59 offset:7088
	v_mul_f32_e32 v52, v52, v254
	v_mul_f32_e32 v56, v56, v254
	v_mul_f32_e32 v60, v60, v254
	v_mul_f32_e32 v64, v64, v254
	v_mul_f32_e32 v136, 0xbfb8aa3b, v52
	v_mul_f32_e32 v137, 0xbfb8aa3b, v56
	v_exp_f32_e32 v136, v136
	v_exp_f32_e32 v137, v137
	v_mul_f32_e32 v60, v60, v52
	v_mul_f32_e32 v64, v64, v56
	v_add_f32_e32 v136, 1.0, v136
	v_add_f32_e32 v137, 1.0, v137
	v_rcp_f32_e32 v136, v136
	v_rcp_f32_e32 v137, v137
	s_nop 0
	v_mul_f32_e32 v60, v60, v136
	v_mul_f32_e32 v64, v64, v137
	v_cvt_pk_bf16_f32 v60, v60, v64
	ds_write_b16 v188, v60 offset:7200
	ds_write_b16_d16_hi v188, v60 offset:7232
	v_mul_f32_e32 v53, v53, v255
	v_mul_f32_e32 v57, v57, v255
	v_mul_f32_e32 v61, v61, v255
	v_mul_f32_e32 v65, v65, v255
	v_mul_f32_e32 v136, 0xbfb8aa3b, v53
	v_mul_f32_e32 v137, 0xbfb8aa3b, v57
	v_exp_f32_e32 v136, v136
	v_exp_f32_e32 v137, v137
	v_mul_f32_e32 v61, v61, v53
	v_mul_f32_e32 v65, v65, v57
	v_add_f32_e32 v136, 1.0, v136
	v_add_f32_e32 v137, 1.0, v137
	v_rcp_f32_e32 v136, v136
	v_rcp_f32_e32 v137, v137
	s_nop 0
	v_mul_f32_e32 v61, v61, v136
	v_mul_f32_e32 v65, v65, v137
	v_cvt_pk_bf16_f32 v61, v61, v65
	ds_write_b16 v188, v61 offset:7344
	ds_write_b16_d16_hi v188, v61 offset:7376
	s_waitcnt lgkmcnt(0)
	s_barrier
	ds_read_b128 v[144:147], v189
	ds_read_b128 v[148:151], v189 offset:4608
	ds_read_b128 v[172:175], v189 offset:9216
	ds_read_b128 v[176:179], v189 offset:13824
	s_mov_b32 s56, s58
	s_mov_b32 s57, s59
	s_waitcnt lgkmcnt(3)
	global_store_dwordx4 v243, v[144:147], s[56:57]
	s_add_u32 s56, s56, 0x59000
	s_addc_u32 s57, s57, 0
	s_waitcnt lgkmcnt(2)
	global_store_dwordx4 v243, v[148:151], s[56:57]
	s_add_u32 s56, s56, 0x59000
	s_addc_u32 s57, s57, 0
	s_waitcnt lgkmcnt(1)
	global_store_dwordx4 v243, v[172:175], s[56:57]
	s_add_u32 s56, s56, 0x59000
	s_addc_u32 s57, s57, 0
	s_waitcnt lgkmcnt(0)
	global_store_dwordx4 v243, v[176:179], s[56:57]
	s_add_u32 s58, s58, 0x400
	s_addc_u32 s59, s59, 0
	s_barrier
	v_mul_f32_e32 v66, v66, v152
	v_mul_f32_e32 v70, v70, v152
	v_mul_f32_e32 v74, v74, v152
	v_mul_f32_e32 v78, v78, v152
	v_mul_f32_e32 v136, 0xbfb8aa3b, v66
	v_mul_f32_e32 v137, 0xbfb8aa3b, v70
	v_exp_f32_e32 v136, v136
	v_exp_f32_e32 v137, v137
	v_mul_f32_e32 v74, v74, v66
	v_mul_f32_e32 v78, v78, v70
	v_add_f32_e32 v136, 1.0, v136
	v_add_f32_e32 v137, 1.0, v137
	v_rcp_f32_e32 v136, v136
	v_rcp_f32_e32 v137, v137
	s_nop 0
	v_mul_f32_e32 v74, v74, v136
	v_mul_f32_e32 v78, v78, v137
	v_cvt_pk_bf16_f32 v74, v74, v78
	ds_write_b16 v188, v74
	ds_write_b16_d16_hi v188, v74 offset:32
	v_mul_f32_e32 v67, v67, v153
	v_mul_f32_e32 v71, v71, v153
	v_mul_f32_e32 v75, v75, v153
	v_mul_f32_e32 v79, v79, v153
	v_mul_f32_e32 v136, 0xbfb8aa3b, v67
	v_mul_f32_e32 v137, 0xbfb8aa3b, v71
	v_exp_f32_e32 v136, v136
	v_exp_f32_e32 v137, v137
	v_mul_f32_e32 v75, v75, v67
	v_mul_f32_e32 v79, v79, v71
	v_add_f32_e32 v136, 1.0, v136
	v_add_f32_e32 v137, 1.0, v137
	v_rcp_f32_e32 v136, v136
	v_rcp_f32_e32 v137, v137
	s_nop 0
	v_mul_f32_e32 v75, v75, v136
	v_mul_f32_e32 v79, v79, v137
	v_cvt_pk_bf16_f32 v75, v75, v79
	ds_write_b16 v188, v75 offset:144
	ds_write_b16_d16_hi v188, v75 offset:176
	v_mul_f32_e32 v68, v68, v154
	v_mul_f32_e32 v72, v72, v154
	v_mul_f32_e32 v76, v76, v154
	v_mul_f32_e32 v80, v80, v154
	v_mul_f32_e32 v136, 0xbfb8aa3b, v68
	v_mul_f32_e32 v137, 0xbfb8aa3b, v72
	v_exp_f32_e32 v136, v136
	v_exp_f32_e32 v137, v137
	v_mul_f32_e32 v76, v76, v68
	v_mul_f32_e32 v80, v80, v72
	v_add_f32_e32 v136, 1.0, v136
	v_add_f32_e32 v137, 1.0, v137
	v_rcp_f32_e32 v136, v136
	v_rcp_f32_e32 v137, v137
	s_nop 0
	v_mul_f32_e32 v76, v76, v136
	v_mul_f32_e32 v80, v80, v137
	v_cvt_pk_bf16_f32 v76, v76, v80
	ds_write_b16 v188, v76 offset:288
	ds_write_b16_d16_hi v188, v76 offset:320
	v_mul_f32_e32 v69, v69, v155
	v_mul_f32_e32 v73, v73, v155
	v_mul_f32_e32 v77, v77, v155
	v_mul_f32_e32 v81, v81, v155
	v_mul_f32_e32 v136, 0xbfb8aa3b, v69
	v_mul_f32_e32 v137, 0xbfb8aa3b, v73
	v_exp_f32_e32 v136, v136
	v_exp_f32_e32 v137, v137
	v_mul_f32_e32 v77, v77, v69
	v_mul_f32_e32 v81, v81, v73
	v_add_f32_e32 v136, 1.0, v136
	v_add_f32_e32 v137, 1.0, v137
	v_rcp_f32_e32 v136, v136
	v_rcp_f32_e32 v137, v137
	s_nop 0
	v_mul_f32_e32 v77, v77, v136
	v_mul_f32_e32 v81, v81, v137
	v_cvt_pk_bf16_f32 v77, v77, v81
	ds_write_b16 v188, v77 offset:432
	ds_write_b16_d16_hi v188, v77 offset:464
	v_mul_f32_e32 v82, v82, v244
	v_mul_f32_e32 v86, v86, v244
	v_mul_f32_e32 v90, v90, v244
	v_mul_f32_e32 v94, v94, v244
	v_mul_f32_e32 v136, 0xbfb8aa3b, v82
	v_mul_f32_e32 v137, 0xbfb8aa3b, v86
	v_exp_f32_e32 v136, v136
	v_exp_f32_e32 v137, v137
	v_mul_f32_e32 v90, v90, v82
	v_mul_f32_e32 v94, v94, v86
	v_add_f32_e32 v136, 1.0, v136
	v_add_f32_e32 v137, 1.0, v137
	v_rcp_f32_e32 v136, v136
	v_rcp_f32_e32 v137, v137
	s_nop 0
	v_mul_f32_e32 v90, v90, v136
	v_mul_f32_e32 v94, v94, v137
	v_cvt_pk_bf16_f32 v90, v90, v94
	ds_write_b16 v188, v90 offset:2304
	ds_write_b16_d16_hi v188, v90 offset:2336
	v_mul_f32_e32 v83, v83, v245
	v_mul_f32_e32 v87, v87, v245
	v_mul_f32_e32 v91, v91, v245
	v_mul_f32_e32 v95, v95, v245
	v_mul_f32_e32 v136, 0xbfb8aa3b, v83
	v_mul_f32_e32 v137, 0xbfb8aa3b, v87
	v_exp_f32_e32 v136, v136
	v_exp_f32_e32 v137, v137
	v_mul_f32_e32 v91, v91, v83
	v_mul_f32_e32 v95, v95, v87
	v_add_f32_e32 v136, 1.0, v136
	v_add_f32_e32 v137, 1.0, v137
	v_rcp_f32_e32 v136, v136
	v_rcp_f32_e32 v137, v137
	s_nop 0
	v_mul_f32_e32 v91, v91, v136
	v_mul_f32_e32 v95, v95, v137
	v_cvt_pk_bf16_f32 v91, v91, v95
	ds_write_b16 v188, v91 offset:2448
	ds_write_b16_d16_hi v188, v91 offset:2480
	v_mul_f32_e32 v84, v84, v246
	v_mul_f32_e32 v88, v88, v246
	v_mul_f32_e32 v92, v92, v246
	v_mul_f32_e32 v96, v96, v246
	v_mul_f32_e32 v136, 0xbfb8aa3b, v84
	v_mul_f32_e32 v137, 0xbfb8aa3b, v88
	v_exp_f32_e32 v136, v136
	v_exp_f32_e32 v137, v137
	v_mul_f32_e32 v92, v92, v84
	v_mul_f32_e32 v96, v96, v88
	v_add_f32_e32 v136, 1.0, v136
	v_add_f32_e32 v137, 1.0, v137
	v_rcp_f32_e32 v136, v136
	v_rcp_f32_e32 v137, v137
	s_nop 0
	v_mul_f32_e32 v92, v92, v136
	v_mul_f32_e32 v96, v96, v137
	v_cvt_pk_bf16_f32 v92, v92, v96
	ds_write_b16 v188, v92 offset:2592
	ds_write_b16_d16_hi v188, v92 offset:2624
	v_mul_f32_e32 v85, v85, v247
	v_mul_f32_e32 v89, v89, v247
	v_mul_f32_e32 v93, v93, v247
	v_mul_f32_e32 v97, v97, v247
	v_mul_f32_e32 v136, 0xbfb8aa3b, v85
	v_mul_f32_e32 v137, 0xbfb8aa3b, v89
	v_exp_f32_e32 v136, v136
	v_exp_f32_e32 v137, v137
	v_mul_f32_e32 v93, v93, v85
	v_mul_f32_e32 v97, v97, v89
	v_add_f32_e32 v136, 1.0, v136
	v_add_f32_e32 v137, 1.0, v137
	v_rcp_f32_e32 v136, v136
	v_rcp_f32_e32 v137, v137
	s_nop 0
	v_mul_f32_e32 v93, v93, v136
	v_mul_f32_e32 v97, v97, v137
	v_cvt_pk_bf16_f32 v93, v93, v97
	ds_write_b16 v188, v93 offset:2736
	ds_write_b16_d16_hi v188, v93 offset:2768
	v_mul_f32_e32 v98, v98, v248
	v_mul_f32_e32 v102, v102, v248
	v_mul_f32_e32 v106, v106, v248
	v_mul_f32_e32 v110, v110, v248
	v_mul_f32_e32 v136, 0xbfb8aa3b, v98
	v_mul_f32_e32 v137, 0xbfb8aa3b, v102
	v_exp_f32_e32 v136, v136
	v_exp_f32_e32 v137, v137
	v_mul_f32_e32 v106, v106, v98
	v_mul_f32_e32 v110, v110, v102
	v_add_f32_e32 v136, 1.0, v136
	v_add_f32_e32 v137, 1.0, v137
	v_rcp_f32_e32 v136, v136
	v_rcp_f32_e32 v137, v137
	s_nop 0
	v_mul_f32_e32 v106, v106, v136
	v_mul_f32_e32 v110, v110, v137
	v_cvt_pk_bf16_f32 v106, v106, v110
	ds_write_b16 v188, v106 offset:4608
	ds_write_b16_d16_hi v188, v106 offset:4640
	v_mul_f32_e32 v99, v99, v249
	v_mul_f32_e32 v103, v103, v249
	v_mul_f32_e32 v107, v107, v249
	v_mul_f32_e32 v111, v111, v249
	v_mul_f32_e32 v136, 0xbfb8aa3b, v99
	v_mul_f32_e32 v137, 0xbfb8aa3b, v103
	v_exp_f32_e32 v136, v136
	v_exp_f32_e32 v137, v137
	v_mul_f32_e32 v107, v107, v99
	v_mul_f32_e32 v111, v111, v103
	v_add_f32_e32 v136, 1.0, v136
	v_add_f32_e32 v137, 1.0, v137
	v_rcp_f32_e32 v136, v136
	v_rcp_f32_e32 v137, v137
	s_nop 0
	v_mul_f32_e32 v107, v107, v136
	v_mul_f32_e32 v111, v111, v137
	v_cvt_pk_bf16_f32 v107, v107, v111
	ds_write_b16 v188, v107 offset:4752
	ds_write_b16_d16_hi v188, v107 offset:4784
	v_mul_f32_e32 v100, v100, v250
	v_mul_f32_e32 v104, v104, v250
	v_mul_f32_e32 v108, v108, v250
	v_mul_f32_e32 v112, v112, v250
	v_mul_f32_e32 v136, 0xbfb8aa3b, v100
	v_mul_f32_e32 v137, 0xbfb8aa3b, v104
	v_exp_f32_e32 v136, v136
	v_exp_f32_e32 v137, v137
	v_mul_f32_e32 v108, v108, v100
	v_mul_f32_e32 v112, v112, v104
	v_add_f32_e32 v136, 1.0, v136
	v_add_f32_e32 v137, 1.0, v137
	v_rcp_f32_e32 v136, v136
	v_rcp_f32_e32 v137, v137
	s_nop 0
	v_mul_f32_e32 v108, v108, v136
	v_mul_f32_e32 v112, v112, v137
	v_cvt_pk_bf16_f32 v108, v108, v112
	ds_write_b16 v188, v108 offset:4896
	ds_write_b16_d16_hi v188, v108 offset:4928
	v_mul_f32_e32 v101, v101, v251
	v_mul_f32_e32 v105, v105, v251
	v_mul_f32_e32 v109, v109, v251
	v_mul_f32_e32 v113, v113, v251
	v_mul_f32_e32 v136, 0xbfb8aa3b, v101
	v_mul_f32_e32 v137, 0xbfb8aa3b, v105
	v_exp_f32_e32 v136, v136
	v_exp_f32_e32 v137, v137
	v_mul_f32_e32 v109, v109, v101
	v_mul_f32_e32 v113, v113, v105
	v_add_f32_e32 v136, 1.0, v136
	v_add_f32_e32 v137, 1.0, v137
	v_rcp_f32_e32 v136, v136
	v_rcp_f32_e32 v137, v137
	s_nop 0
	v_mul_f32_e32 v109, v109, v136
	v_mul_f32_e32 v113, v113, v137
	v_cvt_pk_bf16_f32 v109, v109, v113
	ds_write_b16 v188, v109 offset:5040
	ds_write_b16_d16_hi v188, v109 offset:5072
	v_mul_f32_e32 v114, v114, v252
	v_mul_f32_e32 v118, v118, v252
	v_mul_f32_e32 v122, v122, v252
	v_mul_f32_e32 v126, v126, v252
	v_mul_f32_e32 v136, 0xbfb8aa3b, v114
	v_mul_f32_e32 v137, 0xbfb8aa3b, v118
	v_exp_f32_e32 v136, v136
	v_exp_f32_e32 v137, v137
	v_mul_f32_e32 v122, v122, v114
	v_mul_f32_e32 v126, v126, v118
	v_add_f32_e32 v136, 1.0, v136
	v_add_f32_e32 v137, 1.0, v137
	v_rcp_f32_e32 v136, v136
	v_rcp_f32_e32 v137, v137
	s_nop 0
	v_mul_f32_e32 v122, v122, v136
	v_mul_f32_e32 v126, v126, v137
	v_cvt_pk_bf16_f32 v122, v122, v126
	ds_write_b16 v188, v122 offset:6912
	ds_write_b16_d16_hi v188, v122 offset:6944
	v_mul_f32_e32 v115, v115, v253
	v_mul_f32_e32 v119, v119, v253
	v_mul_f32_e32 v123, v123, v253
	v_mul_f32_e32 v127, v127, v253
	v_mul_f32_e32 v136, 0xbfb8aa3b, v115
	v_mul_f32_e32 v137, 0xbfb8aa3b, v119
	v_exp_f32_e32 v136, v136
	v_exp_f32_e32 v137, v137
	v_mul_f32_e32 v123, v123, v115
	v_mul_f32_e32 v127, v127, v119
	v_add_f32_e32 v136, 1.0, v136
	v_add_f32_e32 v137, 1.0, v137
	v_rcp_f32_e32 v136, v136
	v_rcp_f32_e32 v137, v137
	s_nop 0
	v_mul_f32_e32 v123, v123, v136
	v_mul_f32_e32 v127, v127, v137
	v_cvt_pk_bf16_f32 v123, v123, v127
	ds_write_b16 v188, v123 offset:7056
	ds_write_b16_d16_hi v188, v123 offset:7088
	v_mul_f32_e32 v116, v116, v254
	v_mul_f32_e32 v120, v120, v254
	v_mul_f32_e32 v124, v124, v254
	v_mul_f32_e32 v128, v128, v254
	v_mul_f32_e32 v136, 0xbfb8aa3b, v116
	v_mul_f32_e32 v137, 0xbfb8aa3b, v120
	v_exp_f32_e32 v136, v136
	v_exp_f32_e32 v137, v137
	v_mul_f32_e32 v124, v124, v116
	v_mul_f32_e32 v128, v128, v120
	v_add_f32_e32 v136, 1.0, v136
	v_add_f32_e32 v137, 1.0, v137
	v_rcp_f32_e32 v136, v136
	v_rcp_f32_e32 v137, v137
	s_nop 0
	v_mul_f32_e32 v124, v124, v136
	v_mul_f32_e32 v128, v128, v137
	v_cvt_pk_bf16_f32 v124, v124, v128
	ds_write_b16 v188, v124 offset:7200
	ds_write_b16_d16_hi v188, v124 offset:7232
	v_mul_f32_e32 v117, v117, v255
	v_mul_f32_e32 v121, v121, v255
	v_mul_f32_e32 v125, v125, v255
	v_mul_f32_e32 v129, v129, v255
	v_mul_f32_e32 v136, 0xbfb8aa3b, v117
	v_mul_f32_e32 v137, 0xbfb8aa3b, v121
	v_exp_f32_e32 v136, v136
	v_exp_f32_e32 v137, v137
	v_mul_f32_e32 v125, v125, v117
	v_mul_f32_e32 v129, v129, v121
	v_add_f32_e32 v136, 1.0, v136
	v_add_f32_e32 v137, 1.0, v137
	v_rcp_f32_e32 v136, v136
	v_rcp_f32_e32 v137, v137
	s_nop 0
	v_mul_f32_e32 v125, v125, v136
	v_mul_f32_e32 v129, v129, v137
	v_cvt_pk_bf16_f32 v125, v125, v129
	ds_write_b16 v188, v125 offset:7344
	ds_write_b16_d16_hi v188, v125 offset:7376
	s_waitcnt lgkmcnt(0)
	s_barrier
	ds_read_b128 v[144:147], v189
	ds_read_b128 v[148:151], v189 offset:4608
	ds_read_b128 v[172:175], v189 offset:9216
	ds_read_b128 v[176:179], v189 offset:13824
	s_mov_b32 s56, s58
	s_mov_b32 s57, s59
	s_waitcnt lgkmcnt(3)
	global_store_dwordx4 v243, v[144:147], s[56:57]
	s_add_u32 s56, s56, 0x59000
	s_addc_u32 s57, s57, 0
	s_waitcnt lgkmcnt(2)
	global_store_dwordx4 v243, v[148:151], s[56:57]
	s_add_u32 s56, s56, 0x59000
	s_addc_u32 s57, s57, 0
	s_waitcnt lgkmcnt(1)
	global_store_dwordx4 v243, v[172:175], s[56:57]
	s_add_u32 s56, s56, 0x59000
	s_addc_u32 s57, s57, 0
	s_waitcnt lgkmcnt(0)
	global_store_dwordx4 v243, v[176:179], s[56:57]
	s_cmp_lt_u32 s55, 5
	s_barrier
	s_cbranch_scc0 .Lgu2_lastp
	v_mov_b32_e32 v2, 0
	v_mov_b32_e32 v3, 0
	v_mov_b32_e32 v4, 0
	v_mov_b32_e32 v5, 0
	v_mov_b32_e32 v6, 0
	v_mov_b32_e32 v7, 0
	v_mov_b32_e32 v8, 0
	v_mov_b32_e32 v9, 0
	v_mov_b32_e32 v10, 0
	v_mov_b32_e32 v11, 0
	v_mov_b32_e32 v12, 0
	v_mov_b32_e32 v13, 0
	v_mov_b32_e32 v14, 0
	v_mov_b32_e32 v15, 0
	v_mov_b32_e32 v16, 0
	v_mov_b32_e32 v17, 0
	v_mov_b32_e32 v18, 0
	v_mov_b32_e32 v19, 0
	v_mov_b32_e32 v20, 0
	v_mov_b32_e32 v21, 0
	v_mov_b32_e32 v22, 0
	v_mov_b32_e32 v23, 0
	v_mov_b32_e32 v24, 0
	v_mov_b32_e32 v25, 0
	v_mov_b32_e32 v26, 0
	v_mov_b32_e32 v27, 0
	v_mov_b32_e32 v28, 0
	v_mov_b32_e32 v29, 0
	v_mov_b32_e32 v30, 0
	v_mov_b32_e32 v31, 0
	v_mov_b32_e32 v32, 0
	v_mov_b32_e32 v33, 0
	v_mov_b32_e32 v34, 0
	v_mov_b32_e32 v35, 0
	v_mov_b32_e32 v36, 0
	v_mov_b32_e32 v37, 0
	v_mov_b32_e32 v38, 0
	v_mov_b32_e32 v39, 0
	v_mov_b32_e32 v40, 0
	v_mov_b32_e32 v41, 0
	v_mov_b32_e32 v42, 0
	v_mov_b32_e32 v43, 0
	v_mov_b32_e32 v44, 0
	v_mov_b32_e32 v45, 0
	v_mov_b32_e32 v46, 0
	v_mov_b32_e32 v47, 0
	v_mov_b32_e32 v48, 0
	v_mov_b32_e32 v49, 0
	v_mov_b32_e32 v50, 0
	v_mov_b32_e32 v51, 0
	v_mov_b32_e32 v52, 0
	v_mov_b32_e32 v53, 0
	v_mov_b32_e32 v54, 0
	v_mov_b32_e32 v55, 0
	v_mov_b32_e32 v56, 0
	v_mov_b32_e32 v57, 0
	v_mov_b32_e32 v58, 0
	v_mov_b32_e32 v59, 0
	v_mov_b32_e32 v60, 0
	v_mov_b32_e32 v61, 0
	v_mov_b32_e32 v62, 0
	v_mov_b32_e32 v63, 0
	v_mov_b32_e32 v64, 0
	v_mov_b32_e32 v65, 0
	v_mov_b32_e32 v66, 0
	v_mov_b32_e32 v67, 0
	v_mov_b32_e32 v68, 0
	v_mov_b32_e32 v69, 0
	v_mov_b32_e32 v70, 0
	v_mov_b32_e32 v71, 0
	v_mov_b32_e32 v72, 0
	v_mov_b32_e32 v73, 0
	v_mov_b32_e32 v74, 0
	v_mov_b32_e32 v75, 0
	v_mov_b32_e32 v76, 0
	v_mov_b32_e32 v77, 0
	v_mov_b32_e32 v78, 0
	v_mov_b32_e32 v79, 0
	v_mov_b32_e32 v80, 0
	v_mov_b32_e32 v81, 0
	v_mov_b32_e32 v82, 0
	v_mov_b32_e32 v83, 0
	v_mov_b32_e32 v84, 0
	v_mov_b32_e32 v85, 0
	v_mov_b32_e32 v86, 0
	v_mov_b32_e32 v87, 0
	v_mov_b32_e32 v88, 0
	v_mov_b32_e32 v89, 0
	v_mov_b32_e32 v90, 0
	v_mov_b32_e32 v91, 0
	v_mov_b32_e32 v92, 0
	v_mov_b32_e32 v93, 0
	v_mov_b32_e32 v94, 0
	v_mov_b32_e32 v95, 0
	v_mov_b32_e32 v96, 0
	v_mov_b32_e32 v97, 0
	v_mov_b32_e32 v98, 0
	v_mov_b32_e32 v99, 0
	v_mov_b32_e32 v100, 0
	v_mov_b32_e32 v101, 0
	v_mov_b32_e32 v102, 0
	v_mov_b32_e32 v103, 0
	v_mov_b32_e32 v104, 0
	v_mov_b32_e32 v105, 0
	v_mov_b32_e32 v106, 0
	v_mov_b32_e32 v107, 0
	v_mov_b32_e32 v108, 0
	v_mov_b32_e32 v109, 0
	v_mov_b32_e32 v110, 0
	v_mov_b32_e32 v111, 0
	v_mov_b32_e32 v112, 0
	v_mov_b32_e32 v113, 0
	v_mov_b32_e32 v114, 0
	v_mov_b32_e32 v115, 0
	v_mov_b32_e32 v116, 0
	v_mov_b32_e32 v117, 0
	v_mov_b32_e32 v118, 0
	v_mov_b32_e32 v119, 0
	v_mov_b32_e32 v120, 0
	v_mov_b32_e32 v121, 0
	v_mov_b32_e32 v122, 0
	v_mov_b32_e32 v123, 0
	v_mov_b32_e32 v124, 0
	v_mov_b32_e32 v125, 0
	v_mov_b32_e32 v126, 0
	v_mov_b32_e32 v127, 0
	v_mov_b32_e32 v128, 0
	v_mov_b32_e32 v129, 0
	s_load_dwordx2 s[56:57], s[12:13], 0x1d0
	v_bfe_u32 v241, v131, 4, 2
	s_lshr_b32 s0, s50, 1
	s_lshl_b32 s0, s0, 6
	s_add_i32 s0, s0, s53
	s_lshl_b32 s0, s0, 2
	v_lshlrev_b32_e32 v241, 4, v241
	s_waitcnt lgkmcnt(0)
	s_add_u32 s56, s56, s0
	s_addc_u32 s57, s57, 0
	global_load_dwordx4 v[152:155], v241, s[56:57]
	global_load_dwordx4 v[244:247], v241, s[56:57] offset:64
	global_load_dwordx4 v[248:251], v241, s[56:57] offset:128
	global_load_dwordx4 v[252:255], v241, s[56:57] offset:192
	s_waitcnt vmcnt(12)
	s_barrier
	s_mov_b32 s52, 0
	s_setprio 3
	v_add_u32_e32 v234, s22, v232
	v_add_u32_e32 v236, s28, v232
	v_add_u32_e32 v235, s22, v233
	v_add_u32_e32 v237, s28, v233
	ds_read_b128 v[136:139], v234
	ds_read_b128 v[188:191], v236
	ds_read_b128 v[196:199], v236 offset:2048
	ds_read_b128 v[200:203], v236 offset:4096
	ds_read_b128 v[204:207], v236 offset:6144
	ds_read_b128 v[140:143], v234 offset:2048
	ds_read_b128 v[144:147], v234 offset:4096
	ds_read_b128 v[148:151], v234 offset:6144
	ds_read_b128 v[172:175], v235
	ds_read_b128 v[212:215], v237
	ds_read_b128 v[216:219], v237 offset:2048
	ds_read_b128 v[220:223], v237 offset:4096
	ds_read_b128 v[224:227], v237 offset:6144
	ds_read_b128 v[176:179], v235 offset:2048
	ds_read_b128 v[180:183], v235 offset:4096
	ds_read_b128 v[184:187], v235 offset:6144
	s_add_i32 m0, s51, 0xc000
	s_nop 0
	global_load_lds_dwordx4 v228, s[44:45]
	s_add_i32 m0, s51, 0xc400
	s_nop 0
	global_load_lds_dwordx4 v230, s[44:45]
	s_add_i32 m0, s51, 0xe000
	s_nop 0
	global_load_lds_dwordx4 v229, s[44:45]
	s_add_i32 m0, s51, 0xe400
	s_nop 0
	global_load_lds_dwordx4 v231, s[44:45]
	s_add_i32 m0, s51, 0x10000
	s_nop 0
	global_load_lds_dwordx4 v228, s[46:47]
	s_add_i32 m0, s51, 0x10400
	s_nop 0
	global_load_lds_dwordx4 v230, s[46:47]
	s_waitcnt lgkmcnt(11)
	s_setprio 1
	v_mfma_f32_16x16x32_bf16 v[2:5], v[136:139], v[188:191], v[2:5]
	v_mfma_f32_16x16x32_bf16 v[6:9], v[136:139], v[196:199], v[6:9]
	v_mfma_f32_16x16x32_bf16 v[10:13], v[136:139], v[200:203], v[10:13]
	v_mfma_f32_16x16x32_bf16 v[14:17], v[136:139], v[204:207], v[14:17]
	s_waitcnt lgkmcnt(10)
	v_mfma_f32_16x16x32_bf16 v[18:21], v[140:143], v[188:191], v[18:21]
	v_mfma_f32_16x16x32_bf16 v[22:25], v[140:143], v[196:199], v[22:25]
	v_mfma_f32_16x16x32_bf16 v[26:29], v[140:143], v[200:203], v[26:29]
	v_mfma_f32_16x16x32_bf16 v[30:33], v[140:143], v[204:207], v[30:33]
	s_waitcnt lgkmcnt(9)
	v_mfma_f32_16x16x32_bf16 v[34:37], v[144:147], v[188:191], v[34:37]
	v_mfma_f32_16x16x32_bf16 v[38:41], v[144:147], v[196:199], v[38:41]
	v_mfma_f32_16x16x32_bf16 v[42:45], v[144:147], v[200:203], v[42:45]
	v_mfma_f32_16x16x32_bf16 v[46:49], v[144:147], v[204:207], v[46:49]
	s_waitcnt lgkmcnt(8)
	v_mfma_f32_16x16x32_bf16 v[50:53], v[148:151], v[188:191], v[50:53]
	v_mfma_f32_16x16x32_bf16 v[54:57], v[148:151], v[196:199], v[54:57]
	v_mfma_f32_16x16x32_bf16 v[58:61], v[148:151], v[200:203], v[58:61]
	v_mfma_f32_16x16x32_bf16 v[62:65], v[148:151], v[204:207], v[62:65]
	s_waitcnt lgkmcnt(3)
	v_mfma_f32_16x16x32_bf16 v[2:5], v[172:175], v[212:215], v[2:5]
	v_mfma_f32_16x16x32_bf16 v[6:9], v[172:175], v[216:219], v[6:9]
	v_mfma_f32_16x16x32_bf16 v[10:13], v[172:175], v[220:223], v[10:13]
	v_mfma_f32_16x16x32_bf16 v[14:17], v[172:175], v[224:227], v[14:17]
	s_waitcnt lgkmcnt(2)
	v_mfma_f32_16x16x32_bf16 v[18:21], v[176:179], v[212:215], v[18:21]
	v_mfma_f32_16x16x32_bf16 v[22:25], v[176:179], v[216:219], v[22:25]
	v_mfma_f32_16x16x32_bf16 v[26:29], v[176:179], v[220:223], v[26:29]
	v_mfma_f32_16x16x32_bf16 v[30:33], v[176:179], v[224:227], v[30:33]
	s_waitcnt lgkmcnt(1)
	v_mfma_f32_16x16x32_bf16 v[34:37], v[180:183], v[212:215], v[34:37]
	v_mfma_f32_16x16x32_bf16 v[38:41], v[180:183], v[216:219], v[38:41]
	v_mfma_f32_16x16x32_bf16 v[42:45], v[180:183], v[220:223], v[42:45]
	v_mfma_f32_16x16x32_bf16 v[46:49], v[180:183], v[224:227], v[46:49]
	s_waitcnt lgkmcnt(0)
	v_mfma_f32_16x16x32_bf16 v[50:53], v[184:187], v[212:215], v[50:53]
	v_mfma_f32_16x16x32_bf16 v[54:57], v[184:187], v[216:219], v[54:57]
	v_mfma_f32_16x16x32_bf16 v[58:61], v[184:187], v[220:223], v[58:61]
	v_mfma_f32_16x16x32_bf16 v[62:65], v[184:187], v[224:227], v[62:65]
	s_setprio 0
	s_waitcnt vmcnt(18)
	s_barrier
	s_branch .Lgu2_loop_a0

.Lres1_loop:
	s_setprio 3
	v_add_u32_e32 v234, s22, v232
	v_add_u32_e32 v236, s28, v232
	v_add_u32_e32 v235, s22, v233
	v_add_u32_e32 v237, s28, v233
	ds_read_b128 v[136:139], v234
	ds_read_b128 v[188:191], v236
	ds_read_b128 v[196:199], v236 offset:2048
	ds_read_b128 v[200:203], v236 offset:4096
	ds_read_b128 v[204:207], v236 offset:6144
	ds_read_b128 v[140:143], v234 offset:2048
	ds_read_b128 v[144:147], v234 offset:4096
	ds_read_b128 v[148:151], v234 offset:6144
	ds_read_b128 v[172:175], v235
	ds_read_b128 v[212:215], v237
	ds_read_b128 v[216:219], v237 offset:2048
	ds_read_b128 v[220:223], v237 offset:4096
	ds_read_b128 v[224:227], v237 offset:6144
	ds_read_b128 v[176:179], v235 offset:2048
	ds_read_b128 v[180:183], v235 offset:4096
	ds_read_b128 v[184:187], v235 offset:6144
	s_add_i32 m0, s51, 0xc000
	s_nop 0
	global_load_lds_dwordx4 v228, s[44:45]
	s_add_i32 m0, s51, 0xc400
	s_nop 0
	global_load_lds_dwordx4 v230, s[44:45]
	s_add_i32 m0, s51, 0xe000
	s_nop 0
	global_load_lds_dwordx4 v229, s[44:45]
	s_add_i32 m0, s51, 0xe400
	s_nop 0
	global_load_lds_dwordx4 v231, s[44:45]
	s_add_i32 m0, s51, 0x10000
	s_nop 0
	global_load_lds_dwordx4 v228, s[46:47]
	s_add_i32 m0, s51, 0x10400
	s_nop 0
	global_load_lds_dwordx4 v230, s[46:47]
	s_waitcnt lgkmcnt(11)
	s_setprio 1
	v_mfma_f32_16x16x32_bf16 v[2:5], v[136:139], v[188:191], v[2:5]
	v_mfma_f32_16x16x32_bf16 v[6:9], v[136:139], v[196:199], v[6:9]
	v_mfma_f32_16x16x32_bf16 v[10:13], v[136:139], v[200:203], v[10:13]
	v_mfma_f32_16x16x32_bf16 v[14:17], v[136:139], v[204:207], v[14:17]
	s_waitcnt lgkmcnt(10)
	v_mfma_f32_16x16x32_bf16 v[18:21], v[140:143], v[188:191], v[18:21]
	v_mfma_f32_16x16x32_bf16 v[22:25], v[140:143], v[196:199], v[22:25]
	v_mfma_f32_16x16x32_bf16 v[26:29], v[140:143], v[200:203], v[26:29]
	v_mfma_f32_16x16x32_bf16 v[30:33], v[140:143], v[204:207], v[30:33]
	s_waitcnt lgkmcnt(9)
	v_mfma_f32_16x16x32_bf16 v[34:37], v[144:147], v[188:191], v[34:37]
	v_mfma_f32_16x16x32_bf16 v[38:41], v[144:147], v[196:199], v[38:41]
	v_mfma_f32_16x16x32_bf16 v[42:45], v[144:147], v[200:203], v[42:45]
	v_mfma_f32_16x16x32_bf16 v[46:49], v[144:147], v[204:207], v[46:49]
	s_waitcnt lgkmcnt(8)
	v_mfma_f32_16x16x32_bf16 v[50:53], v[148:151], v[188:191], v[50:53]
	v_mfma_f32_16x16x32_bf16 v[54:57], v[148:151], v[196:199], v[54:57]
	v_mfma_f32_16x16x32_bf16 v[58:61], v[148:151], v[200:203], v[58:61]
	v_mfma_f32_16x16x32_bf16 v[62:65], v[148:151], v[204:207], v[62:65]
	s_waitcnt lgkmcnt(3)
	v_mfma_f32_16x16x32_bf16 v[2:5], v[172:175], v[212:215], v[2:5]
	v_mfma_f32_16x16x32_bf16 v[6:9], v[172:175], v[216:219], v[6:9]
	v_mfma_f32_16x16x32_bf16 v[10:13], v[172:175], v[220:223], v[10:13]
	v_mfma_f32_16x16x32_bf16 v[14:17], v[172:175], v[224:227], v[14:17]
	s_waitcnt lgkmcnt(2)
	v_mfma_f32_16x16x32_bf16 v[18:21], v[176:179], v[212:215], v[18:21]
	v_mfma_f32_16x16x32_bf16 v[22:25], v[176:179], v[216:219], v[22:25]
	v_mfma_f32_16x16x32_bf16 v[26:29], v[176:179], v[220:223], v[26:29]
	v_mfma_f32_16x16x32_bf16 v[30:33], v[176:179], v[224:227], v[30:33]
	s_waitcnt lgkmcnt(1)
	v_mfma_f32_16x16x32_bf16 v[34:37], v[180:183], v[212:215], v[34:37]
	v_mfma_f32_16x16x32_bf16 v[38:41], v[180:183], v[216:219], v[38:41]
	v_mfma_f32_16x16x32_bf16 v[42:45], v[180:183], v[220:223], v[42:45]
	v_mfma_f32_16x16x32_bf16 v[46:49], v[180:183], v[224:227], v[46:49]
	s_waitcnt lgkmcnt(0)
	v_mfma_f32_16x16x32_bf16 v[50:53], v[184:187], v[212:215], v[50:53]
	v_mfma_f32_16x16x32_bf16 v[54:57], v[184:187], v[216:219], v[54:57]
	v_mfma_f32_16x16x32_bf16 v[58:61], v[184:187], v[220:223], v[58:61]
	v_mfma_f32_16x16x32_bf16 v[62:65], v[184:187], v[224:227], v[62:65]
	s_setprio 0
	s_waitcnt vmcnt(6)
	s_barrier
	s_setprio 3
	v_add_u32_e32 v236, s40, v232
	v_add_u32_e32 v237, s40, v233
	ds_read_b128 v[188:191], v236
	ds_read_b128 v[196:199], v236 offset:2048
	ds_read_b128 v[200:203], v236 offset:4096
	ds_read_b128 v[204:207], v236 offset:6144
	ds_read_b128 v[212:215], v237
	ds_read_b128 v[216:219], v237 offset:2048
	ds_read_b128 v[220:223], v237 offset:4096
	ds_read_b128 v[224:227], v237 offset:6144
	s_mov_b32 m0, s51
	s_nop 0
	global_load_lds_dwordx4 v229, s[46:47]
	s_add_i32 m0, s51, 0x400
	s_nop 0
	global_load_lds_dwordx4 v231, s[46:47]
	s_add_i32 m0, s51, 0x2000
	s_nop 0
	global_load_lds_dwordx4 v228, s[48:49]
	s_add_i32 m0, s51, 0x2400
	s_nop 0
	global_load_lds_dwordx4 v230, s[48:49]
	s_add_i32 m0, s51, 0x4000
	s_nop 0
	global_load_lds_dwordx4 v229, s[48:49]
	s_add_i32 m0, s51, 0x4400
	s_nop 0
	global_load_lds_dwordx4 v231, s[48:49]
	s_waitcnt lgkmcnt(7)
	s_setprio 1
	v_mfma_f32_16x16x32_bf16 v[66:69], v[136:139], v[188:191], v[66:69]
	v_mfma_f32_16x16x32_bf16 v[82:85], v[140:143], v[188:191], v[82:85]
	v_mfma_f32_16x16x32_bf16 v[98:101], v[144:147], v[188:191], v[98:101]
	v_mfma_f32_16x16x32_bf16 v[114:117], v[148:151], v[188:191], v[114:117]
	s_waitcnt lgkmcnt(6)
	v_mfma_f32_16x16x32_bf16 v[70:73], v[136:139], v[196:199], v[70:73]
	v_mfma_f32_16x16x32_bf16 v[86:89], v[140:143], v[196:199], v[86:89]
	v_mfma_f32_16x16x32_bf16 v[102:105], v[144:147], v[196:199], v[102:105]
	v_mfma_f32_16x16x32_bf16 v[118:121], v[148:151], v[196:199], v[118:121]
	s_waitcnt lgkmcnt(5)
	v_mfma_f32_16x16x32_bf16 v[74:77], v[136:139], v[200:203], v[74:77]
	v_mfma_f32_16x16x32_bf16 v[90:93], v[140:143], v[200:203], v[90:93]
	v_mfma_f32_16x16x32_bf16 v[106:109], v[144:147], v[200:203], v[106:109]
	v_mfma_f32_16x16x32_bf16 v[122:125], v[148:151], v[200:203], v[122:125]
	s_waitcnt lgkmcnt(4)
	v_mfma_f32_16x16x32_bf16 v[78:81], v[136:139], v[204:207], v[78:81]
	v_mfma_f32_16x16x32_bf16 v[94:97], v[140:143], v[204:207], v[94:97]
	v_mfma_f32_16x16x32_bf16 v[110:113], v[144:147], v[204:207], v[110:113]
	v_mfma_f32_16x16x32_bf16 v[126:129], v[148:151], v[204:207], v[126:129]
	s_waitcnt lgkmcnt(3)
	v_mfma_f32_16x16x32_bf16 v[66:69], v[172:175], v[212:215], v[66:69]
	v_mfma_f32_16x16x32_bf16 v[82:85], v[176:179], v[212:215], v[82:85]
	v_mfma_f32_16x16x32_bf16 v[98:101], v[180:183], v[212:215], v[98:101]
	v_mfma_f32_16x16x32_bf16 v[114:117], v[184:187], v[212:215], v[114:117]
	s_waitcnt lgkmcnt(2)
	v_mfma_f32_16x16x32_bf16 v[70:73], v[172:175], v[216:219], v[70:73]
	v_mfma_f32_16x16x32_bf16 v[86:89], v[176:179], v[216:219], v[86:89]
	v_mfma_f32_16x16x32_bf16 v[102:105], v[180:183], v[216:219], v[102:105]
	v_mfma_f32_16x16x32_bf16 v[118:121], v[184:187], v[216:219], v[118:121]
	s_waitcnt lgkmcnt(1)
	v_mfma_f32_16x16x32_bf16 v[74:77], v[172:175], v[220:223], v[74:77]
	v_mfma_f32_16x16x32_bf16 v[90:93], v[176:179], v[220:223], v[90:93]
	v_mfma_f32_16x16x32_bf16 v[106:109], v[180:183], v[220:223], v[106:109]
	v_mfma_f32_16x16x32_bf16 v[122:125], v[184:187], v[220:223], v[122:125]
	s_waitcnt lgkmcnt(0)
	v_mfma_f32_16x16x32_bf16 v[78:81], v[172:175], v[224:227], v[78:81]
	v_mfma_f32_16x16x32_bf16 v[94:97], v[176:179], v[224:227], v[94:97]
	v_mfma_f32_16x16x32_bf16 v[110:113], v[180:183], v[224:227], v[110:113]
	v_mfma_f32_16x16x32_bf16 v[126:129], v[184:187], v[224:227], v[126:129]
	s_setprio 0
	v_add_u32_e32 v228, 0x80, v228
	v_add_u32_e32 v229, 0x80, v229
	v_add_u32_e32 v230, 0x80, v230
	v_add_u32_e32 v231, 0x80, v231
	s_waitcnt vmcnt(4)
	s_barrier
	s_setprio 3
	v_add_u32_e32 v234, s23, v232
	v_add_u32_e32 v236, s29, v232
	v_add_u32_e32 v235, s23, v233
	v_add_u32_e32 v237, s29, v233
	ds_read_b128 v[136:139], v234
	ds_read_b128 v[188:191], v236
	ds_read_b128 v[196:199], v236 offset:2048
	ds_read_b128 v[200:203], v236 offset:4096
	ds_read_b128 v[204:207], v236 offset:6144
	ds_read_b128 v[140:143], v234 offset:2048
	ds_read_b128 v[144:147], v234 offset:4096
	ds_read_b128 v[148:151], v234 offset:6144
	ds_read_b128 v[172:175], v235
	ds_read_b128 v[212:215], v237
	ds_read_b128 v[216:219], v237 offset:2048
	ds_read_b128 v[220:223], v237 offset:4096
	ds_read_b128 v[224:227], v237 offset:6144
	ds_read_b128 v[176:179], v235 offset:2048
	ds_read_b128 v[180:183], v235 offset:4096
	ds_read_b128 v[184:187], v235 offset:6144
	s_add_i32 m0, s51, 0x6000
	s_nop 0
	global_load_lds_dwordx4 v228, s[44:45]
	s_add_i32 m0, s51, 0x6400
	s_nop 0
	global_load_lds_dwordx4 v230, s[44:45]
	s_add_i32 m0, s51, 0x8000
	s_nop 0
	global_load_lds_dwordx4 v229, s[44:45]
	s_add_i32 m0, s51, 0x8400
	s_nop 0
	global_load_lds_dwordx4 v231, s[44:45]
	s_add_i32 m0, s51, 0xa000
	s_nop 0
	global_load_lds_dwordx4 v228, s[46:47]
	s_add_i32 m0, s51, 0xa400
	s_nop 0
	global_load_lds_dwordx4 v230, s[46:47]
	s_waitcnt lgkmcnt(11)
	s_setprio 1
	v_mfma_f32_16x16x32_bf16 v[2:5], v[136:139], v[188:191], v[2:5]
	v_mfma_f32_16x16x32_bf16 v[6:9], v[136:139], v[196:199], v[6:9]
	v_mfma_f32_16x16x32_bf16 v[10:13], v[136:139], v[200:203], v[10:13]
	v_mfma_f32_16x16x32_bf16 v[14:17], v[136:139], v[204:207], v[14:17]
	s_waitcnt lgkmcnt(10)
	v_mfma_f32_16x16x32_bf16 v[18:21], v[140:143], v[188:191], v[18:21]
	v_mfma_f32_16x16x32_bf16 v[22:25], v[140:143], v[196:199], v[22:25]
	v_mfma_f32_16x16x32_bf16 v[26:29], v[140:143], v[200:203], v[26:29]
	v_mfma_f32_16x16x32_bf16 v[30:33], v[140:143], v[204:207], v[30:33]
	s_waitcnt lgkmcnt(9)
	v_mfma_f32_16x16x32_bf16 v[34:37], v[144:147], v[188:191], v[34:37]
	v_mfma_f32_16x16x32_bf16 v[38:41], v[144:147], v[196:199], v[38:41]
	v_mfma_f32_16x16x32_bf16 v[42:45], v[144:147], v[200:203], v[42:45]
	v_mfma_f32_16x16x32_bf16 v[46:49], v[144:147], v[204:207], v[46:49]
	s_waitcnt lgkmcnt(8)
	v_mfma_f32_16x16x32_bf16 v[50:53], v[148:151], v[188:191], v[50:53]
	v_mfma_f32_16x16x32_bf16 v[54:57], v[148:151], v[196:199], v[54:57]
	v_mfma_f32_16x16x32_bf16 v[58:61], v[148:151], v[200:203], v[58:61]
	v_mfma_f32_16x16x32_bf16 v[62:65], v[148:151], v[204:207], v[62:65]
	s_waitcnt lgkmcnt(3)
	v_mfma_f32_16x16x32_bf16 v[2:5], v[172:175], v[212:215], v[2:5]
	v_mfma_f32_16x16x32_bf16 v[6:9], v[172:175], v[216:219], v[6:9]
	v_mfma_f32_16x16x32_bf16 v[10:13], v[172:175], v[220:223], v[10:13]
	v_mfma_f32_16x16x32_bf16 v[14:17], v[172:175], v[224:227], v[14:17]
	s_waitcnt lgkmcnt(2)
	v_mfma_f32_16x16x32_bf16 v[18:21], v[176:179], v[212:215], v[18:21]
	v_mfma_f32_16x16x32_bf16 v[22:25], v[176:179], v[216:219], v[22:25]
	v_mfma_f32_16x16x32_bf16 v[26:29], v[176:179], v[220:223], v[26:29]
	v_mfma_f32_16x16x32_bf16 v[30:33], v[176:179], v[224:227], v[30:33]
	s_waitcnt lgkmcnt(1)
	v_mfma_f32_16x16x32_bf16 v[34:37], v[180:183], v[212:215], v[34:37]
	v_mfma_f32_16x16x32_bf16 v[38:41], v[180:183], v[216:219], v[38:41]
	v_mfma_f32_16x16x32_bf16 v[42:45], v[180:183], v[220:223], v[42:45]
	v_mfma_f32_16x16x32_bf16 v[46:49], v[180:183], v[224:227], v[46:49]
	s_waitcnt lgkmcnt(0)
	v_mfma_f32_16x16x32_bf16 v[50:53], v[184:187], v[212:215], v[50:53]
	v_mfma_f32_16x16x32_bf16 v[54:57], v[184:187], v[216:219], v[54:57]
	v_mfma_f32_16x16x32_bf16 v[58:61], v[184:187], v[220:223], v[58:61]
	v_mfma_f32_16x16x32_bf16 v[62:65], v[184:187], v[224:227], v[62:65]
	s_setprio 0
	s_waitcnt vmcnt(6)
	s_barrier
	s_setprio 3
	v_add_u32_e32 v236, s41, v232
	v_add_u32_e32 v237, s41, v233
	ds_read_b128 v[188:191], v236
	ds_read_b128 v[196:199], v236 offset:2048
	ds_read_b128 v[200:203], v236 offset:4096
	ds_read_b128 v[204:207], v236 offset:6144
	ds_read_b128 v[212:215], v237
	ds_read_b128 v[216:219], v237 offset:2048
	ds_read_b128 v[220:223], v237 offset:4096
	ds_read_b128 v[224:227], v237 offset:6144
	s_add_i32 m0, s51, 0xc000
	s_nop 0
	global_load_lds_dwordx4 v229, s[46:47]
	s_add_i32 m0, s51, 0xc400
	s_nop 0
	global_load_lds_dwordx4 v231, s[46:47]
	s_add_i32 m0, s51, 0xe000
	s_nop 0
	global_load_lds_dwordx4 v228, s[48:49]
	s_add_i32 m0, s51, 0xe400
	s_nop 0
	global_load_lds_dwordx4 v230, s[48:49]
	s_add_i32 m0, s51, 0x10000
	s_nop 0
	global_load_lds_dwordx4 v229, s[48:49]
	s_add_i32 m0, s51, 0x10400
	s_nop 0
	global_load_lds_dwordx4 v231, s[48:49]
	s_waitcnt lgkmcnt(7)
	s_setprio 1
	v_mfma_f32_16x16x32_bf16 v[66:69], v[136:139], v[188:191], v[66:69]
	v_mfma_f32_16x16x32_bf16 v[82:85], v[140:143], v[188:191], v[82:85]
	v_mfma_f32_16x16x32_bf16 v[98:101], v[144:147], v[188:191], v[98:101]
	v_mfma_f32_16x16x32_bf16 v[114:117], v[148:151], v[188:191], v[114:117]
	s_waitcnt lgkmcnt(6)
	v_mfma_f32_16x16x32_bf16 v[70:73], v[136:139], v[196:199], v[70:73]
	v_mfma_f32_16x16x32_bf16 v[86:89], v[140:143], v[196:199], v[86:89]
	v_mfma_f32_16x16x32_bf16 v[102:105], v[144:147], v[196:199], v[102:105]
	v_mfma_f32_16x16x32_bf16 v[118:121], v[148:151], v[196:199], v[118:121]
	s_waitcnt lgkmcnt(5)
	v_mfma_f32_16x16x32_bf16 v[74:77], v[136:139], v[200:203], v[74:77]
	v_mfma_f32_16x16x32_bf16 v[90:93], v[140:143], v[200:203], v[90:93]
	v_mfma_f32_16x16x32_bf16 v[106:109], v[144:147], v[200:203], v[106:109]
	v_mfma_f32_16x16x32_bf16 v[122:125], v[148:151], v[200:203], v[122:125]
	s_waitcnt lgkmcnt(4)
	v_mfma_f32_16x16x32_bf16 v[78:81], v[136:139], v[204:207], v[78:81]
	v_mfma_f32_16x16x32_bf16 v[94:97], v[140:143], v[204:207], v[94:97]
	v_mfma_f32_16x16x32_bf16 v[110:113], v[144:147], v[204:207], v[110:113]
	v_mfma_f32_16x16x32_bf16 v[126:129], v[148:151], v[204:207], v[126:129]
	s_waitcnt lgkmcnt(3)
	v_mfma_f32_16x16x32_bf16 v[66:69], v[172:175], v[212:215], v[66:69]
	v_mfma_f32_16x16x32_bf16 v[82:85], v[176:179], v[212:215], v[82:85]
	v_mfma_f32_16x16x32_bf16 v[98:101], v[180:183], v[212:215], v[98:101]
	v_mfma_f32_16x16x32_bf16 v[114:117], v[184:187], v[212:215], v[114:117]
	s_waitcnt lgkmcnt(2)
	v_mfma_f32_16x16x32_bf16 v[70:73], v[172:175], v[216:219], v[70:73]
	v_mfma_f32_16x16x32_bf16 v[86:89], v[176:179], v[216:219], v[86:89]
	v_mfma_f32_16x16x32_bf16 v[102:105], v[180:183], v[216:219], v[102:105]
	v_mfma_f32_16x16x32_bf16 v[118:121], v[184:187], v[216:219], v[118:121]
	s_waitcnt lgkmcnt(1)
	v_mfma_f32_16x16x32_bf16 v[74:77], v[172:175], v[220:223], v[74:77]
	v_mfma_f32_16x16x32_bf16 v[90:93], v[176:179], v[220:223], v[90:93]
	v_mfma_f32_16x16x32_bf16 v[106:109], v[180:183], v[220:223], v[106:109]
	v_mfma_f32_16x16x32_bf16 v[122:125], v[184:187], v[220:223], v[122:125]
	s_waitcnt lgkmcnt(0)
	v_mfma_f32_16x16x32_bf16 v[78:81], v[172:175], v[224:227], v[78:81]
	v_mfma_f32_16x16x32_bf16 v[94:97], v[176:179], v[224:227], v[94:97]
	v_mfma_f32_16x16x32_bf16 v[110:113], v[180:183], v[224:227], v[110:113]
	v_mfma_f32_16x16x32_bf16 v[126:129], v[184:187], v[224:227], v[126:129]
	s_setprio 0
	v_add_u32_e32 v228, 0x80, v228
	v_add_u32_e32 v229, 0x80, v229
	v_add_u32_e32 v230, 0x80, v230
	v_add_u32_e32 v231, 0x80, v231
	s_waitcnt vmcnt(4)
	s_barrier
	s_setprio 3
	v_add_u32_e32 v234, s24, v232
	v_add_u32_e32 v236, s30, v232
	v_add_u32_e32 v235, s24, v233
	v_add_u32_e32 v237, s30, v233
	ds_read_b128 v[136:139], v234
	ds_read_b128 v[188:191], v236
	ds_read_b128 v[196:199], v236 offset:2048
	ds_read_b128 v[200:203], v236 offset:4096
	ds_read_b128 v[204:207], v236 offset:6144
	ds_read_b128 v[140:143], v234 offset:2048
	ds_read_b128 v[144:147], v234 offset:4096
	ds_read_b128 v[148:151], v234 offset:6144
	ds_read_b128 v[172:175], v235
	ds_read_b128 v[212:215], v237
	ds_read_b128 v[216:219], v237 offset:2048
	ds_read_b128 v[220:223], v237 offset:4096
	ds_read_b128 v[224:227], v237 offset:6144
	ds_read_b128 v[176:179], v235 offset:2048
	ds_read_b128 v[180:183], v235 offset:4096
	ds_read_b128 v[184:187], v235 offset:6144
	s_mov_b32 m0, s51
	s_nop 0
	global_load_lds_dwordx4 v228, s[44:45]
	s_add_i32 m0, s51, 0x400
	s_nop 0
	global_load_lds_dwordx4 v230, s[44:45]
	s_add_i32 m0, s51, 0x2000
	s_nop 0
	global_load_lds_dwordx4 v229, s[44:45]
	s_add_i32 m0, s51, 0x2400
	s_nop 0
	global_load_lds_dwordx4 v231, s[44:45]
	s_add_i32 m0, s51, 0x4000
	s_nop 0
	global_load_lds_dwordx4 v228, s[46:47]
	s_add_i32 m0, s51, 0x4400
	s_nop 0
	global_load_lds_dwordx4 v230, s[46:47]
	s_waitcnt lgkmcnt(11)
	s_setprio 1
	v_mfma_f32_16x16x32_bf16 v[2:5], v[136:139], v[188:191], v[2:5]
	v_mfma_f32_16x16x32_bf16 v[6:9], v[136:139], v[196:199], v[6:9]
	v_mfma_f32_16x16x32_bf16 v[10:13], v[136:139], v[200:203], v[10:13]
	v_mfma_f32_16x16x32_bf16 v[14:17], v[136:139], v[204:207], v[14:17]
	s_waitcnt lgkmcnt(10)
	v_mfma_f32_16x16x32_bf16 v[18:21], v[140:143], v[188:191], v[18:21]
	v_mfma_f32_16x16x32_bf16 v[22:25], v[140:143], v[196:199], v[22:25]
	v_mfma_f32_16x16x32_bf16 v[26:29], v[140:143], v[200:203], v[26:29]
	v_mfma_f32_16x16x32_bf16 v[30:33], v[140:143], v[204:207], v[30:33]
	s_waitcnt lgkmcnt(9)
	v_mfma_f32_16x16x32_bf16 v[34:37], v[144:147], v[188:191], v[34:37]
	v_mfma_f32_16x16x32_bf16 v[38:41], v[144:147], v[196:199], v[38:41]
	v_mfma_f32_16x16x32_bf16 v[42:45], v[144:147], v[200:203], v[42:45]
	v_mfma_f32_16x16x32_bf16 v[46:49], v[144:147], v[204:207], v[46:49]
	s_waitcnt lgkmcnt(8)
	v_mfma_f32_16x16x32_bf16 v[50:53], v[148:151], v[188:191], v[50:53]
	v_mfma_f32_16x16x32_bf16 v[54:57], v[148:151], v[196:199], v[54:57]
	v_mfma_f32_16x16x32_bf16 v[58:61], v[148:151], v[200:203], v[58:61]
	v_mfma_f32_16x16x32_bf16 v[62:65], v[148:151], v[204:207], v[62:65]
	s_waitcnt lgkmcnt(3)
	v_mfma_f32_16x16x32_bf16 v[2:5], v[172:175], v[212:215], v[2:5]
	v_mfma_f32_16x16x32_bf16 v[6:9], v[172:175], v[216:219], v[6:9]
	v_mfma_f32_16x16x32_bf16 v[10:13], v[172:175], v[220:223], v[10:13]
	v_mfma_f32_16x16x32_bf16 v[14:17], v[172:175], v[224:227], v[14:17]
	s_waitcnt lgkmcnt(2)
	v_mfma_f32_16x16x32_bf16 v[18:21], v[176:179], v[212:215], v[18:21]
	v_mfma_f32_16x16x32_bf16 v[22:25], v[176:179], v[216:219], v[22:25]
	v_mfma_f32_16x16x32_bf16 v[26:29], v[176:179], v[220:223], v[26:29]
	v_mfma_f32_16x16x32_bf16 v[30:33], v[176:179], v[224:227], v[30:33]
	s_waitcnt lgkmcnt(1)
	v_mfma_f32_16x16x32_bf16 v[34:37], v[180:183], v[212:215], v[34:37]
	v_mfma_f32_16x16x32_bf16 v[38:41], v[180:183], v[216:219], v[38:41]
	v_mfma_f32_16x16x32_bf16 v[42:45], v[180:183], v[220:223], v[42:45]
	v_mfma_f32_16x16x32_bf16 v[46:49], v[180:183], v[224:227], v[46:49]
	s_waitcnt lgkmcnt(0)
	v_mfma_f32_16x16x32_bf16 v[50:53], v[184:187], v[212:215], v[50:53]
	v_mfma_f32_16x16x32_bf16 v[54:57], v[184:187], v[216:219], v[54:57]
	v_mfma_f32_16x16x32_bf16 v[58:61], v[184:187], v[220:223], v[58:61]
	v_mfma_f32_16x16x32_bf16 v[62:65], v[184:187], v[224:227], v[62:65]
	s_setprio 0
	s_waitcnt vmcnt(6)
	s_barrier
	s_setprio 3
	v_add_u32_e32 v236, s42, v232
	v_add_u32_e32 v237, s42, v233
	ds_read_b128 v[188:191], v236
	ds_read_b128 v[196:199], v236 offset:2048
	ds_read_b128 v[200:203], v236 offset:4096
	ds_read_b128 v[204:207], v236 offset:6144
	ds_read_b128 v[212:215], v237
	ds_read_b128 v[216:219], v237 offset:2048
	ds_read_b128 v[220:223], v237 offset:4096
	ds_read_b128 v[224:227], v237 offset:6144
	s_add_i32 m0, s51, 0x6000
	s_nop 0
	global_load_lds_dwordx4 v229, s[46:47]
	s_add_i32 m0, s51, 0x6400
	s_nop 0
	global_load_lds_dwordx4 v231, s[46:47]
	s_add_i32 m0, s51, 0x8000
	s_nop 0
	global_load_lds_dwordx4 v228, s[48:49]
	s_add_i32 m0, s51, 0x8400
	s_nop 0
	global_load_lds_dwordx4 v230, s[48:49]
	s_add_i32 m0, s51, 0xa000
	s_nop 0
	global_load_lds_dwordx4 v229, s[48:49]
	s_add_i32 m0, s51, 0xa400
	s_nop 0
	global_load_lds_dwordx4 v231, s[48:49]
	s_waitcnt lgkmcnt(7)
	s_setprio 1
	v_mfma_f32_16x16x32_bf16 v[66:69], v[136:139], v[188:191], v[66:69]
	v_mfma_f32_16x16x32_bf16 v[82:85], v[140:143], v[188:191], v[82:85]
	v_mfma_f32_16x16x32_bf16 v[98:101], v[144:147], v[188:191], v[98:101]
	v_mfma_f32_16x16x32_bf16 v[114:117], v[148:151], v[188:191], v[114:117]
	s_waitcnt lgkmcnt(6)
	v_mfma_f32_16x16x32_bf16 v[70:73], v[136:139], v[196:199], v[70:73]
	v_mfma_f32_16x16x32_bf16 v[86:89], v[140:143], v[196:199], v[86:89]
	v_mfma_f32_16x16x32_bf16 v[102:105], v[144:147], v[196:199], v[102:105]
	v_mfma_f32_16x16x32_bf16 v[118:121], v[148:151], v[196:199], v[118:121]
	s_waitcnt lgkmcnt(5)
	v_mfma_f32_16x16x32_bf16 v[74:77], v[136:139], v[200:203], v[74:77]
	v_mfma_f32_16x16x32_bf16 v[90:93], v[140:143], v[200:203], v[90:93]
	v_mfma_f32_16x16x32_bf16 v[106:109], v[144:147], v[200:203], v[106:109]
	v_mfma_f32_16x16x32_bf16 v[122:125], v[148:151], v[200:203], v[122:125]
	s_waitcnt lgkmcnt(4)
	v_mfma_f32_16x16x32_bf16 v[78:81], v[136:139], v[204:207], v[78:81]
	v_mfma_f32_16x16x32_bf16 v[94:97], v[140:143], v[204:207], v[94:97]
	v_mfma_f32_16x16x32_bf16 v[110:113], v[144:147], v[204:207], v[110:113]
	v_mfma_f32_16x16x32_bf16 v[126:129], v[148:151], v[204:207], v[126:129]
	s_waitcnt lgkmcnt(3)
	v_mfma_f32_16x16x32_bf16 v[66:69], v[172:175], v[212:215], v[66:69]
	v_mfma_f32_16x16x32_bf16 v[82:85], v[176:179], v[212:215], v[82:85]
	v_mfma_f32_16x16x32_bf16 v[98:101], v[180:183], v[212:215], v[98:101]
	v_mfma_f32_16x16x32_bf16 v[114:117], v[184:187], v[212:215], v[114:117]
	s_waitcnt lgkmcnt(2)
	v_mfma_f32_16x16x32_bf16 v[70:73], v[172:175], v[216:219], v[70:73]
	v_mfma_f32_16x16x32_bf16 v[86:89], v[176:179], v[216:219], v[86:89]
	v_mfma_f32_16x16x32_bf16 v[102:105], v[180:183], v[216:219], v[102:105]
	v_mfma_f32_16x16x32_bf16 v[118:121], v[184:187], v[216:219], v[118:121]
	s_waitcnt lgkmcnt(1)
	v_mfma_f32_16x16x32_bf16 v[74:77], v[172:175], v[220:223], v[74:77]
	v_mfma_f32_16x16x32_bf16 v[90:93], v[176:179], v[220:223], v[90:93]
	v_mfma_f32_16x16x32_bf16 v[106:109], v[180:183], v[220:223], v[106:109]
	v_mfma_f32_16x16x32_bf16 v[122:125], v[184:187], v[220:223], v[122:125]
	s_waitcnt lgkmcnt(0)
	v_mfma_f32_16x16x32_bf16 v[78:81], v[172:175], v[224:227], v[78:81]
	v_mfma_f32_16x16x32_bf16 v[94:97], v[176:179], v[224:227], v[94:97]
	v_mfma_f32_16x16x32_bf16 v[110:113], v[180:183], v[224:227], v[110:113]
	v_mfma_f32_16x16x32_bf16 v[126:129], v[184:187], v[224:227], v[126:129]
	s_setprio 0
	v_add_u32_e32 v228, 0x80, v228
	v_add_u32_e32 v229, 0x80, v229
	v_add_u32_e32 v230, 0x80, v230
	v_add_u32_e32 v231, 0x80, v231
	s_waitcnt vmcnt(4)
	s_barrier
	s_add_i32 s52, s52, 1
	s_cmp_lt_u32 s52, 10
	s_cbranch_scc1 .Lres1_loop
	s_setprio 3
	v_add_u32_e32 v234, s22, v232
	v_add_u32_e32 v236, s28, v232
	v_add_u32_e32 v235, s22, v233
	v_add_u32_e32 v237, s28, v233
	ds_read_b128 v[136:139], v234
	ds_read_b128 v[188:191], v236
	ds_read_b128 v[196:199], v236 offset:2048
	ds_read_b128 v[200:203], v236 offset:4096
	ds_read_b128 v[204:207], v236 offset:6144
	ds_read_b128 v[140:143], v234 offset:2048
	ds_read_b128 v[144:147], v234 offset:4096
	ds_read_b128 v[148:151], v234 offset:6144
	ds_read_b128 v[172:175], v235
	ds_read_b128 v[212:215], v237
	ds_read_b128 v[216:219], v237 offset:2048
	ds_read_b128 v[220:223], v237 offset:4096
	ds_read_b128 v[224:227], v237 offset:6144
	ds_read_b128 v[176:179], v235 offset:2048
	ds_read_b128 v[180:183], v235 offset:4096
	ds_read_b128 v[184:187], v235 offset:6144
	s_add_i32 m0, s51, 0xc000
	s_nop 0
	global_load_lds_dwordx4 v228, s[44:45]
	s_add_i32 m0, s51, 0xc400
	s_nop 0
	global_load_lds_dwordx4 v230, s[44:45]
	s_add_i32 m0, s51, 0xe000
	s_nop 0
	global_load_lds_dwordx4 v229, s[44:45]
	s_add_i32 m0, s51, 0xe400
	s_nop 0
	global_load_lds_dwordx4 v231, s[44:45]
	s_add_i32 m0, s51, 0x10000
	s_nop 0
	global_load_lds_dwordx4 v228, s[46:47]
	s_add_i32 m0, s51, 0x10400
	s_nop 0
	global_load_lds_dwordx4 v230, s[46:47]
	s_waitcnt lgkmcnt(11)
	s_setprio 1
	v_mfma_f32_16x16x32_bf16 v[2:5], v[136:139], v[188:191], v[2:5]
	v_mfma_f32_16x16x32_bf16 v[6:9], v[136:139], v[196:199], v[6:9]
	v_mfma_f32_16x16x32_bf16 v[10:13], v[136:139], v[200:203], v[10:13]
	v_mfma_f32_16x16x32_bf16 v[14:17], v[136:139], v[204:207], v[14:17]
	s_waitcnt lgkmcnt(10)
	v_mfma_f32_16x16x32_bf16 v[18:21], v[140:143], v[188:191], v[18:21]
	v_mfma_f32_16x16x32_bf16 v[22:25], v[140:143], v[196:199], v[22:25]
	v_mfma_f32_16x16x32_bf16 v[26:29], v[140:143], v[200:203], v[26:29]
	v_mfma_f32_16x16x32_bf16 v[30:33], v[140:143], v[204:207], v[30:33]
	s_waitcnt lgkmcnt(9)
	v_mfma_f32_16x16x32_bf16 v[34:37], v[144:147], v[188:191], v[34:37]
	v_mfma_f32_16x16x32_bf16 v[38:41], v[144:147], v[196:199], v[38:41]
	v_mfma_f32_16x16x32_bf16 v[42:45], v[144:147], v[200:203], v[42:45]
	v_mfma_f32_16x16x32_bf16 v[46:49], v[144:147], v[204:207], v[46:49]
	s_waitcnt lgkmcnt(8)
	v_mfma_f32_16x16x32_bf16 v[50:53], v[148:151], v[188:191], v[50:53]
	v_mfma_f32_16x16x32_bf16 v[54:57], v[148:151], v[196:199], v[54:57]
	v_mfma_f32_16x16x32_bf16 v[58:61], v[148:151], v[200:203], v[58:61]
	v_mfma_f32_16x16x32_bf16 v[62:65], v[148:151], v[204:207], v[62:65]
	s_waitcnt lgkmcnt(3)
	v_mfma_f32_16x16x32_bf16 v[2:5], v[172:175], v[212:215], v[2:5]
	v_mfma_f32_16x16x32_bf16 v[6:9], v[172:175], v[216:219], v[6:9]
	v_mfma_f32_16x16x32_bf16 v[10:13], v[172:175], v[220:223], v[10:13]
	v_mfma_f32_16x16x32_bf16 v[14:17], v[172:175], v[224:227], v[14:17]
	s_waitcnt lgkmcnt(2)
	v_mfma_f32_16x16x32_bf16 v[18:21], v[176:179], v[212:215], v[18:21]
	v_mfma_f32_16x16x32_bf16 v[22:25], v[176:179], v[216:219], v[22:25]
	v_mfma_f32_16x16x32_bf16 v[26:29], v[176:179], v[220:223], v[26:29]
	v_mfma_f32_16x16x32_bf16 v[30:33], v[176:179], v[224:227], v[30:33]
	s_waitcnt lgkmcnt(1)
	v_mfma_f32_16x16x32_bf16 v[34:37], v[180:183], v[212:215], v[34:37]
	v_mfma_f32_16x16x32_bf16 v[38:41], v[180:183], v[216:219], v[38:41]
	v_mfma_f32_16x16x32_bf16 v[42:45], v[180:183], v[220:223], v[42:45]
	v_mfma_f32_16x16x32_bf16 v[46:49], v[180:183], v[224:227], v[46:49]
	s_waitcnt lgkmcnt(0)
	v_mfma_f32_16x16x32_bf16 v[50:53], v[184:187], v[212:215], v[50:53]
	v_mfma_f32_16x16x32_bf16 v[54:57], v[184:187], v[216:219], v[54:57]
	v_mfma_f32_16x16x32_bf16 v[58:61], v[184:187], v[220:223], v[58:61]
	v_mfma_f32_16x16x32_bf16 v[62:65], v[184:187], v[224:227], v[62:65]
	s_setprio 0
	s_waitcnt vmcnt(6)
	s_barrier
	s_setprio 3
	v_add_u32_e32 v236, s40, v232
	v_add_u32_e32 v237, s40, v233
	ds_read_b128 v[188:191], v236
	ds_read_b128 v[196:199], v236 offset:2048
	ds_read_b128 v[200:203], v236 offset:4096
	ds_read_b128 v[204:207], v236 offset:6144
	ds_read_b128 v[212:215], v237
	ds_read_b128 v[216:219], v237 offset:2048
	ds_read_b128 v[220:223], v237 offset:4096
	ds_read_b128 v[224:227], v237 offset:6144
	s_mov_b32 m0, s51
	s_nop 0
	global_load_lds_dwordx4 v229, s[46:47]
	s_add_i32 m0, s51, 0x400
	s_nop 0
	global_load_lds_dwordx4 v231, s[46:47]
	s_add_i32 m0, s51, 0x2000
	s_nop 0
	global_load_lds_dwordx4 v228, s[48:49]
	s_add_i32 m0, s51, 0x2400
	s_nop 0
	global_load_lds_dwordx4 v230, s[48:49]
	s_add_i32 m0, s51, 0x4000
	s_nop 0
	global_load_lds_dwordx4 v229, s[48:49]
	s_add_i32 m0, s51, 0x4400
	s_nop 0
	global_load_lds_dwordx4 v231, s[48:49]
	s_waitcnt lgkmcnt(7)
	s_setprio 1
	v_mfma_f32_16x16x32_bf16 v[66:69], v[136:139], v[188:191], v[66:69]
	v_mfma_f32_16x16x32_bf16 v[82:85], v[140:143], v[188:191], v[82:85]
	v_mfma_f32_16x16x32_bf16 v[98:101], v[144:147], v[188:191], v[98:101]
	v_mfma_f32_16x16x32_bf16 v[114:117], v[148:151], v[188:191], v[114:117]
	s_waitcnt lgkmcnt(6)
	v_mfma_f32_16x16x32_bf16 v[70:73], v[136:139], v[196:199], v[70:73]
	v_mfma_f32_16x16x32_bf16 v[86:89], v[140:143], v[196:199], v[86:89]
	v_mfma_f32_16x16x32_bf16 v[102:105], v[144:147], v[196:199], v[102:105]
	v_mfma_f32_16x16x32_bf16 v[118:121], v[148:151], v[196:199], v[118:121]
	s_waitcnt lgkmcnt(5)
	v_mfma_f32_16x16x32_bf16 v[74:77], v[136:139], v[200:203], v[74:77]
	v_mfma_f32_16x16x32_bf16 v[90:93], v[140:143], v[200:203], v[90:93]
	v_mfma_f32_16x16x32_bf16 v[106:109], v[144:147], v[200:203], v[106:109]
	v_mfma_f32_16x16x32_bf16 v[122:125], v[148:151], v[200:203], v[122:125]
	s_waitcnt lgkmcnt(4)
	v_mfma_f32_16x16x32_bf16 v[78:81], v[136:139], v[204:207], v[78:81]
	v_mfma_f32_16x16x32_bf16 v[94:97], v[140:143], v[204:207], v[94:97]
	v_mfma_f32_16x16x32_bf16 v[110:113], v[144:147], v[204:207], v[110:113]
	v_mfma_f32_16x16x32_bf16 v[126:129], v[148:151], v[204:207], v[126:129]
	s_waitcnt lgkmcnt(3)
	v_mfma_f32_16x16x32_bf16 v[66:69], v[172:175], v[212:215], v[66:69]
	v_mfma_f32_16x16x32_bf16 v[82:85], v[176:179], v[212:215], v[82:85]
	v_mfma_f32_16x16x32_bf16 v[98:101], v[180:183], v[212:215], v[98:101]
	v_mfma_f32_16x16x32_bf16 v[114:117], v[184:187], v[212:215], v[114:117]
	s_waitcnt lgkmcnt(2)
	v_mfma_f32_16x16x32_bf16 v[70:73], v[172:175], v[216:219], v[70:73]
	v_mfma_f32_16x16x32_bf16 v[86:89], v[176:179], v[216:219], v[86:89]
	v_mfma_f32_16x16x32_bf16 v[102:105], v[180:183], v[216:219], v[102:105]
	v_mfma_f32_16x16x32_bf16 v[118:121], v[184:187], v[216:219], v[118:121]
	s_waitcnt lgkmcnt(1)
	v_mfma_f32_16x16x32_bf16 v[74:77], v[172:175], v[220:223], v[74:77]
	v_mfma_f32_16x16x32_bf16 v[90:93], v[176:179], v[220:223], v[90:93]
	v_mfma_f32_16x16x32_bf16 v[106:109], v[180:183], v[220:223], v[106:109]
	v_mfma_f32_16x16x32_bf16 v[122:125], v[184:187], v[220:223], v[122:125]
	s_waitcnt lgkmcnt(0)
	v_mfma_f32_16x16x32_bf16 v[78:81], v[172:175], v[224:227], v[78:81]
	v_mfma_f32_16x16x32_bf16 v[94:97], v[176:179], v[224:227], v[94:97]
	v_mfma_f32_16x16x32_bf16 v[110:113], v[180:183], v[224:227], v[110:113]
	v_mfma_f32_16x16x32_bf16 v[126:129], v[184:187], v[224:227], v[126:129]
	s_setprio 0
	v_add_u32_e32 v228, 0x80, v228
	v_add_u32_e32 v229, 0x80, v229
	v_add_u32_e32 v230, 0x80, v230
	v_add_u32_e32 v231, 0x80, v231
	s_waitcnt vmcnt(4)
	s_barrier
	s_setprio 3
	v_add_u32_e32 v234, s23, v232
	v_add_u32_e32 v236, s29, v232
	v_add_u32_e32 v235, s23, v233
	v_add_u32_e32 v237, s29, v233
	ds_read_b128 v[136:139], v234
	ds_read_b128 v[188:191], v236
	ds_read_b128 v[196:199], v236 offset:2048
	ds_read_b128 v[200:203], v236 offset:4096
	ds_read_b128 v[204:207], v236 offset:6144
	ds_read_b128 v[140:143], v234 offset:2048
	ds_read_b128 v[144:147], v234 offset:4096
	ds_read_b128 v[148:151], v234 offset:6144
	ds_read_b128 v[172:175], v235
	ds_read_b128 v[212:215], v237
	ds_read_b128 v[216:219], v237 offset:2048
	ds_read_b128 v[220:223], v237 offset:4096
	ds_read_b128 v[224:227], v237 offset:6144
	ds_read_b128 v[176:179], v235 offset:2048
	ds_read_b128 v[180:183], v235 offset:4096
	ds_read_b128 v[184:187], v235 offset:6144
	s_waitcnt lgkmcnt(11)
	s_setprio 1
	v_mfma_f32_16x16x32_bf16 v[2:5], v[136:139], v[188:191], v[2:5]
	v_mfma_f32_16x16x32_bf16 v[6:9], v[136:139], v[196:199], v[6:9]
	v_mfma_f32_16x16x32_bf16 v[10:13], v[136:139], v[200:203], v[10:13]
	v_mfma_f32_16x16x32_bf16 v[14:17], v[136:139], v[204:207], v[14:17]
	s_waitcnt lgkmcnt(10)
	v_mfma_f32_16x16x32_bf16 v[18:21], v[140:143], v[188:191], v[18:21]
	v_mfma_f32_16x16x32_bf16 v[22:25], v[140:143], v[196:199], v[22:25]
	v_mfma_f32_16x16x32_bf16 v[26:29], v[140:143], v[200:203], v[26:29]
	v_mfma_f32_16x16x32_bf16 v[30:33], v[140:143], v[204:207], v[30:33]
	s_waitcnt lgkmcnt(9)
	v_mfma_f32_16x16x32_bf16 v[34:37], v[144:147], v[188:191], v[34:37]
	v_mfma_f32_16x16x32_bf16 v[38:41], v[144:147], v[196:199], v[38:41]
	v_mfma_f32_16x16x32_bf16 v[42:45], v[144:147], v[200:203], v[42:45]
	v_mfma_f32_16x16x32_bf16 v[46:49], v[144:147], v[204:207], v[46:49]
	s_waitcnt lgkmcnt(8)
	v_mfma_f32_16x16x32_bf16 v[50:53], v[148:151], v[188:191], v[50:53]
	v_mfma_f32_16x16x32_bf16 v[54:57], v[148:151], v[196:199], v[54:57]
	v_mfma_f32_16x16x32_bf16 v[58:61], v[148:151], v[200:203], v[58:61]
	v_mfma_f32_16x16x32_bf16 v[62:65], v[148:151], v[204:207], v[62:65]
	s_waitcnt lgkmcnt(3)
	v_mfma_f32_16x16x32_bf16 v[2:5], v[172:175], v[212:215], v[2:5]
	v_mfma_f32_16x16x32_bf16 v[6:9], v[172:175], v[216:219], v[6:9]
	v_mfma_f32_16x16x32_bf16 v[10:13], v[172:175], v[220:223], v[10:13]
	v_mfma_f32_16x16x32_bf16 v[14:17], v[172:175], v[224:227], v[14:17]
	s_waitcnt lgkmcnt(2)
	v_mfma_f32_16x16x32_bf16 v[18:21], v[176:179], v[212:215], v[18:21]
	v_mfma_f32_16x16x32_bf16 v[22:25], v[176:179], v[216:219], v[22:25]
	v_mfma_f32_16x16x32_bf16 v[26:29], v[176:179], v[220:223], v[26:29]
	v_mfma_f32_16x16x32_bf16 v[30:33], v[176:179], v[224:227], v[30:33]
	s_waitcnt lgkmcnt(1)
	v_mfma_f32_16x16x32_bf16 v[34:37], v[180:183], v[212:215], v[34:37]
	v_mfma_f32_16x16x32_bf16 v[38:41], v[180:183], v[216:219], v[38:41]
	v_mfma_f32_16x16x32_bf16 v[42:45], v[180:183], v[220:223], v[42:45]
	v_mfma_f32_16x16x32_bf16 v[46:49], v[180:183], v[224:227], v[46:49]
	s_waitcnt lgkmcnt(0)
	v_mfma_f32_16x16x32_bf16 v[50:53], v[184:187], v[212:215], v[50:53]
	v_mfma_f32_16x16x32_bf16 v[54:57], v[184:187], v[216:219], v[54:57]
	v_mfma_f32_16x16x32_bf16 v[58:61], v[184:187], v[220:223], v[58:61]
	v_mfma_f32_16x16x32_bf16 v[62:65], v[184:187], v[224:227], v[62:65]
	s_setprio 0
	s_waitcnt vmcnt(0)
	s_barrier
	s_setprio 3
	v_add_u32_e32 v236, s41, v232
	v_add_u32_e32 v237, s41, v233
	ds_read_b128 v[188:191], v236
	ds_read_b128 v[196:199], v236 offset:2048
	ds_read_b128 v[200:203], v236 offset:4096
	ds_read_b128 v[204:207], v236 offset:6144
	ds_read_b128 v[212:215], v237
	ds_read_b128 v[216:219], v237 offset:2048
	ds_read_b128 v[220:223], v237 offset:4096
	ds_read_b128 v[224:227], v237 offset:6144
	s_waitcnt lgkmcnt(7)
	s_setprio 1
	v_mfma_f32_16x16x32_bf16 v[66:69], v[136:139], v[188:191], v[66:69]
	v_mfma_f32_16x16x32_bf16 v[82:85], v[140:143], v[188:191], v[82:85]
	v_mfma_f32_16x16x32_bf16 v[98:101], v[144:147], v[188:191], v[98:101]
	v_mfma_f32_16x16x32_bf16 v[114:117], v[148:151], v[188:191], v[114:117]
	s_waitcnt lgkmcnt(6)
	v_mfma_f32_16x16x32_bf16 v[70:73], v[136:139], v[196:199], v[70:73]
	v_mfma_f32_16x16x32_bf16 v[86:89], v[140:143], v[196:199], v[86:89]
	v_mfma_f32_16x16x32_bf16 v[102:105], v[144:147], v[196:199], v[102:105]
	v_mfma_f32_16x16x32_bf16 v[118:121], v[148:151], v[196:199], v[118:121]
	s_waitcnt lgkmcnt(5)
	v_mfma_f32_16x16x32_bf16 v[74:77], v[136:139], v[200:203], v[74:77]
	v_mfma_f32_16x16x32_bf16 v[90:93], v[140:143], v[200:203], v[90:93]
	v_mfma_f32_16x16x32_bf16 v[106:109], v[144:147], v[200:203], v[106:109]
	v_mfma_f32_16x16x32_bf16 v[122:125], v[148:151], v[200:203], v[122:125]
	s_waitcnt lgkmcnt(4)
	v_mfma_f32_16x16x32_bf16 v[78:81], v[136:139], v[204:207], v[78:81]
	v_mfma_f32_16x16x32_bf16 v[94:97], v[140:143], v[204:207], v[94:97]
	v_mfma_f32_16x16x32_bf16 v[110:113], v[144:147], v[204:207], v[110:113]
	v_mfma_f32_16x16x32_bf16 v[126:129], v[148:151], v[204:207], v[126:129]
	s_waitcnt lgkmcnt(3)
	v_mfma_f32_16x16x32_bf16 v[66:69], v[172:175], v[212:215], v[66:69]
	v_mfma_f32_16x16x32_bf16 v[82:85], v[176:179], v[212:215], v[82:85]
	v_mfma_f32_16x16x32_bf16 v[98:101], v[180:183], v[212:215], v[98:101]
	v_mfma_f32_16x16x32_bf16 v[114:117], v[184:187], v[212:215], v[114:117]
	s_waitcnt lgkmcnt(2)
	v_mfma_f32_16x16x32_bf16 v[70:73], v[172:175], v[216:219], v[70:73]
	v_mfma_f32_16x16x32_bf16 v[86:89], v[176:179], v[216:219], v[86:89]
	v_mfma_f32_16x16x32_bf16 v[102:105], v[180:183], v[216:219], v[102:105]
	v_mfma_f32_16x16x32_bf16 v[118:121], v[184:187], v[216:219], v[118:121]
	s_waitcnt lgkmcnt(1)
	v_mfma_f32_16x16x32_bf16 v[74:77], v[172:175], v[220:223], v[74:77]
	v_mfma_f32_16x16x32_bf16 v[90:93], v[176:179], v[220:223], v[90:93]
	v_mfma_f32_16x16x32_bf16 v[106:109], v[180:183], v[220:223], v[106:109]
	v_mfma_f32_16x16x32_bf16 v[122:125], v[184:187], v[220:223], v[122:125]
	s_waitcnt lgkmcnt(0)
	v_mfma_f32_16x16x32_bf16 v[78:81], v[172:175], v[224:227], v[78:81]
	v_mfma_f32_16x16x32_bf16 v[94:97], v[176:179], v[224:227], v[94:97]
	v_mfma_f32_16x16x32_bf16 v[110:113], v[180:183], v[224:227], v[110:113]
	v_mfma_f32_16x16x32_bf16 v[126:129], v[184:187], v[224:227], v[126:129]
	s_setprio 0
	s_nop 7
	s_barrier
	s_load_dwordx2 s[44:45], s[12:13], 0x0
	s_load_dwordx2 s[58:59], s[12:13], 0x100
	s_load_dwordx2 s[46:47], s[12:13], 0x160
	s_load_dwordx2 s[48:49], s[12:13], 0x1c8
	v_lshrrev_b32_e32 v241, 5, v131
	v_and_b32_e32 v242, 31, v131
	v_lshlrev_b32_e32 v243, 4, v242
	s_movk_i32 s56, 0x210
	v_mad_u32_u24 v239, v241, s56, v243
	v_add_u32_e32 v239, 16, v239
	v_lshlrev_b32_e32 v240, 13, v241
	v_or_b32_e32 v240, v240, v243
	v_lshlrev_b32_e32 v244, 3, v242
	v_mad_u32_u24 v244, v241, s81, v244
	v_lshlrev_b32_e32 v245, 2, v241
	s_lshl_b32 s56, s53, 13
	s_lshl_b32 s57, s54, 2
	s_add_i32 s56, s56, s57
	s_mul_i32 s57, s53, s81
	s_lshl_b32 s0, s54, 1
	s_add_i32 s57, s57, s0
	s_lshl_b32 s0, s53, 2
	s_waitcnt lgkmcnt(0)
	s_add_u32 s44, s44, s56
	s_addc_u32 s45, s45, 0
	s_add_u32 s58, s58, s56
	s_addc_u32 s59, s59, 0
	s_add_u32 s46, s46, s57
	s_addc_u32 s47, s47, 0
	s_add_u32 s48, s48, s0
	s_addc_u32 s49, s49, 0
	s_mov_b32 s56, s44
	s_mov_b32 s57, s45
	global_load_dwordx4 v[136:139], v240, s[56:57]
	s_add_u32 s56, s56, 0x10000
	s_addc_u32 s57, s57, 0
	global_load_dwordx4 v[140:143], v240, s[56:57]
	s_add_u32 s56, s56, 0x10000
	s_addc_u32 s57, s57, 0
	global_load_dwordx4 v[144:147], v240, s[56:57]
	s_add_u32 s56, s56, 0x10000
	s_addc_u32 s57, s57, 0
	global_load_dwordx4 v[148:151], v240, s[56:57]
	s_add_u32 s56, s56, 0x10000
	s_addc_u32 s57, s57, 0
	global_load_dwordx4 v[172:175], v240, s[56:57]
	s_add_u32 s56, s56, 0x10000
	s_addc_u32 s57, s57, 0
	global_load_dwordx4 v[176:179], v240, s[56:57]
	s_add_u32 s56, s56, 0x10000
	s_addc_u32 s57, s57, 0
	global_load_dwordx4 v[180:183], v240, s[56:57]
	s_add_u32 s56, s56, 0x10000
	s_addc_u32 s57, s57, 0
	global_load_dwordx4 v[184:187], v240, s[56:57]
	s_add_u32 s56, s56, 0x10000
	s_addc_u32 s57, s57, 0
	global_load_dwordx4 v[188:191], v240, s[56:57]
	s_add_u32 s56, s56, 0x10000
	s_addc_u32 s57, s57, 0
	global_load_dwordx4 v[196:199], v240, s[56:57]
	s_add_u32 s56, s56, 0x10000
	s_addc_u32 s57, s57, 0
	global_load_dwordx4 v[200:203], v240, s[56:57]
	s_add_u32 s56, s56, 0x10000
	s_addc_u32 s57, s57, 0
	global_load_dwordx4 v[204:207], v240, s[56:57]
	s_add_u32 s56, s56, 0x10000
	s_addc_u32 s57, s57, 0
	global_load_dwordx4 v[212:215], v240, s[56:57]
	s_add_u32 s56, s56, 0x10000
	s_addc_u32 s57, s57, 0
	global_load_dwordx4 v[216:219], v240, s[56:57]
	s_add_u32 s56, s56, 0x10000
	s_addc_u32 s57, s57, 0
	global_load_dwordx4 v[220:223], v240, s[56:57]
	s_add_u32 s56, s56, 0x10000
	s_addc_u32 s57, s57, 0
	global_load_dwordx4 v[224:227], v240, s[56:57]
	ds_write_b32 v238, v2
	ds_write_b32 v238, v3 offset:528
	ds_write_b32 v238, v4 offset:1056
	ds_write_b32 v238, v5 offset:1584
	ds_write_b32 v238, v6 offset:64
	ds_write_b32 v238, v7 offset:592
	ds_write_b32 v238, v8 offset:1120
	ds_write_b32 v238, v9 offset:1648
	ds_write_b32 v238, v10 offset:128
	ds_write_b32 v238, v11 offset:656
	ds_write_b32 v238, v12 offset:1184
	ds_write_b32 v238, v13 offset:1712
	ds_write_b32 v238, v14 offset:192
	ds_write_b32 v238, v15 offset:720
	ds_write_b32 v238, v16 offset:1248
	ds_write_b32 v238, v17 offset:1776
	ds_write_b32 v238, v18 offset:8448
	ds_write_b32 v238, v19 offset:8976
	ds_write_b32 v238, v20 offset:9504
	ds_write_b32 v238, v21 offset:10032
	ds_write_b32 v238, v22 offset:8512
	ds_write_b32 v238, v23 offset:9040
	ds_write_b32 v238, v24 offset:9568
	ds_write_b32 v238, v25 offset:10096
	ds_write_b32 v238, v26 offset:8576
	ds_write_b32 v238, v27 offset:9104
	ds_write_b32 v238, v28 offset:9632
	ds_write_b32 v238, v29 offset:10160
	ds_write_b32 v238, v30 offset:8640
	ds_write_b32 v238, v31 offset:9168
	ds_write_b32 v238, v32 offset:9696
	ds_write_b32 v238, v33 offset:10224
	ds_write_b32 v238, v34 offset:16896
	ds_write_b32 v238, v35 offset:17424
	ds_write_b32 v238, v36 offset:17952
	ds_write_b32 v238, v37 offset:18480
	ds_write_b32 v238, v38 offset:16960
	ds_write_b32 v238, v39 offset:17488
	ds_write_b32 v238, v40 offset:18016
	ds_write_b32 v238, v41 offset:18544
	ds_write_b32 v238, v42 offset:17024
	ds_write_b32 v238, v43 offset:17552
	ds_write_b32 v238, v44 offset:18080
	ds_write_b32 v238, v45 offset:18608
	ds_write_b32 v238, v46 offset:17088
	ds_write_b32 v238, v47 offset:17616
	ds_write_b32 v238, v48 offset:18144
	ds_write_b32 v238, v49 offset:18672
	ds_write_b32 v238, v50 offset:25344
	ds_write_b32 v238, v51 offset:25872
	ds_write_b32 v238, v52 offset:26400
	ds_write_b32 v238, v53 offset:26928
	ds_write_b32 v238, v54 offset:25408
	ds_write_b32 v238, v55 offset:25936
	ds_write_b32 v238, v56 offset:26464
	ds_write_b32 v238, v57 offset:26992
	ds_write_b32 v238, v58 offset:25472
	ds_write_b32 v238, v59 offset:26000
	ds_write_b32 v238, v60 offset:26528
	ds_write_b32 v238, v61 offset:27056
	ds_write_b32 v238, v62 offset:25536
	ds_write_b32 v238, v63 offset:26064
	ds_write_b32 v238, v64 offset:26592
	ds_write_b32 v238, v65 offset:27120
	s_waitcnt lgkmcnt(0)
	s_barrier
	ds_read_b128 v[2:5], v239
	ds_read_b128 v[6:9], v239 offset:4224
	ds_read_b128 v[10:13], v239 offset:8448
	ds_read_b128 v[14:17], v239 offset:12672
	ds_read_b128 v[18:21], v239 offset:16896
	ds_read_b128 v[22:25], v239 offset:21120
	ds_read_b128 v[26:29], v239 offset:25344
	ds_read_b128 v[30:33], v239 offset:29568
	ds_read_b128 v[34:37], v239 offset:33792
	ds_read_b128 v[38:41], v239 offset:38016
	ds_read_b128 v[42:45], v239 offset:42240
	ds_read_b128 v[46:49], v239 offset:46464
	ds_read_b128 v[50:53], v239 offset:50688
	ds_read_b128 v[54:57], v239 offset:54912
	ds_read_b128 v[58:61], v239 offset:59136
	ds_read_b128 v[62:65], v239 offset:63360
	s_waitcnt vmcnt(15) lgkmcnt(15)
	v_pk_add_f32 v[2:3], v[2:3], v[136:137]
	v_pk_add_f32 v[4:5], v[4:5], v[138:139]
	v_cvt_pk_bf16_f32 v136, v2, v3
	v_cvt_pk_bf16_f32 v137, v4, v5
	v_mul_f32_e32 v138, v2, v2
	v_fmac_f32_e32 v138, v3, v3
	v_fmac_f32_e32 v138, v4, v4
	v_fmac_f32_e32 v138, v5, v5
	s_waitcnt vmcnt(14) lgkmcnt(14)
	v_pk_add_f32 v[6:7], v[6:7], v[140:141]
	v_pk_add_f32 v[8:9], v[8:9], v[142:143]
	v_cvt_pk_bf16_f32 v140, v6, v7
	v_cvt_pk_bf16_f32 v141, v8, v9
	v_mul_f32_e32 v142, v6, v6
	v_fmac_f32_e32 v142, v7, v7
	v_fmac_f32_e32 v142, v8, v8
	v_fmac_f32_e32 v142, v9, v9
	s_waitcnt vmcnt(13) lgkmcnt(13)
	v_pk_add_f32 v[10:11], v[10:11], v[144:145]
	v_pk_add_f32 v[12:13], v[12:13], v[146:147]
	v_cvt_pk_bf16_f32 v144, v10, v11
	v_cvt_pk_bf16_f32 v145, v12, v13
	v_mul_f32_e32 v146, v10, v10
	v_fmac_f32_e32 v146, v11, v11
	v_fmac_f32_e32 v146, v12, v12
	v_fmac_f32_e32 v146, v13, v13
	s_waitcnt vmcnt(12) lgkmcnt(12)
	v_pk_add_f32 v[14:15], v[14:15], v[148:149]
	v_pk_add_f32 v[16:17], v[16:17], v[150:151]
	v_cvt_pk_bf16_f32 v148, v14, v15
	v_cvt_pk_bf16_f32 v149, v16, v17
	v_mul_f32_e32 v150, v14, v14
	v_fmac_f32_e32 v150, v15, v15
	v_fmac_f32_e32 v150, v16, v16
	v_fmac_f32_e32 v150, v17, v17
	s_waitcnt vmcnt(11) lgkmcnt(11)
	v_pk_add_f32 v[18:19], v[18:19], v[172:173]
	v_pk_add_f32 v[20:21], v[20:21], v[174:175]
	v_cvt_pk_bf16_f32 v172, v18, v19
	v_cvt_pk_bf16_f32 v173, v20, v21
	v_mul_f32_e32 v174, v18, v18
	v_fmac_f32_e32 v174, v19, v19
	v_fmac_f32_e32 v174, v20, v20
	v_fmac_f32_e32 v174, v21, v21
	s_waitcnt vmcnt(10) lgkmcnt(10)
	v_pk_add_f32 v[22:23], v[22:23], v[176:177]
	v_pk_add_f32 v[24:25], v[24:25], v[178:179]
	v_cvt_pk_bf16_f32 v176, v22, v23
	v_cvt_pk_bf16_f32 v177, v24, v25
	v_mul_f32_e32 v178, v22, v22
	v_fmac_f32_e32 v178, v23, v23
	v_fmac_f32_e32 v178, v24, v24
	v_fmac_f32_e32 v178, v25, v25
	s_waitcnt vmcnt(9) lgkmcnt(9)
	v_pk_add_f32 v[26:27], v[26:27], v[180:181]
	v_pk_add_f32 v[28:29], v[28:29], v[182:183]
	v_cvt_pk_bf16_f32 v180, v26, v27
	v_cvt_pk_bf16_f32 v181, v28, v29
	v_mul_f32_e32 v182, v26, v26
	v_fmac_f32_e32 v182, v27, v27
	v_fmac_f32_e32 v182, v28, v28
	v_fmac_f32_e32 v182, v29, v29
	s_waitcnt vmcnt(8) lgkmcnt(8)
	v_pk_add_f32 v[30:31], v[30:31], v[184:185]
	v_pk_add_f32 v[32:33], v[32:33], v[186:187]
	v_cvt_pk_bf16_f32 v184, v30, v31
	v_cvt_pk_bf16_f32 v185, v32, v33
	v_mul_f32_e32 v186, v30, v30
	v_fmac_f32_e32 v186, v31, v31
	v_fmac_f32_e32 v186, v32, v32
	v_fmac_f32_e32 v186, v33, v33
	s_waitcnt vmcnt(7) lgkmcnt(7)
	v_pk_add_f32 v[34:35], v[34:35], v[188:189]
	v_pk_add_f32 v[36:37], v[36:37], v[190:191]
	v_cvt_pk_bf16_f32 v188, v34, v35
	v_cvt_pk_bf16_f32 v189, v36, v37
	v_mul_f32_e32 v190, v34, v34
	v_fmac_f32_e32 v190, v35, v35
	v_fmac_f32_e32 v190, v36, v36
	v_fmac_f32_e32 v190, v37, v37
	s_waitcnt vmcnt(6) lgkmcnt(6)
	v_pk_add_f32 v[38:39], v[38:39], v[196:197]
	v_pk_add_f32 v[40:41], v[40:41], v[198:199]
	v_cvt_pk_bf16_f32 v196, v38, v39
	v_cvt_pk_bf16_f32 v197, v40, v41
	v_mul_f32_e32 v198, v38, v38
	v_fmac_f32_e32 v198, v39, v39
	v_fmac_f32_e32 v198, v40, v40
	v_fmac_f32_e32 v198, v41, v41
	s_waitcnt vmcnt(5) lgkmcnt(5)
	v_pk_add_f32 v[42:43], v[42:43], v[200:201]
	v_pk_add_f32 v[44:45], v[44:45], v[202:203]
	v_cvt_pk_bf16_f32 v200, v42, v43
	v_cvt_pk_bf16_f32 v201, v44, v45
	v_mul_f32_e32 v202, v42, v42
	v_fmac_f32_e32 v202, v43, v43
	v_fmac_f32_e32 v202, v44, v44
	v_fmac_f32_e32 v202, v45, v45
	s_waitcnt vmcnt(4) lgkmcnt(4)
	v_pk_add_f32 v[46:47], v[46:47], v[204:205]
	v_pk_add_f32 v[48:49], v[48:49], v[206:207]
	v_cvt_pk_bf16_f32 v204, v46, v47
	v_cvt_pk_bf16_f32 v205, v48, v49
	v_mul_f32_e32 v206, v46, v46
	v_fmac_f32_e32 v206, v47, v47
	v_fmac_f32_e32 v206, v48, v48
	v_fmac_f32_e32 v206, v49, v49
	s_waitcnt vmcnt(3) lgkmcnt(3)
	v_pk_add_f32 v[50:51], v[50:51], v[212:213]
	v_pk_add_f32 v[52:53], v[52:53], v[214:215]
	v_cvt_pk_bf16_f32 v212, v50, v51
	v_cvt_pk_bf16_f32 v213, v52, v53
	v_mul_f32_e32 v214, v50, v50
	v_fmac_f32_e32 v214, v51, v51
	v_fmac_f32_e32 v214, v52, v52
	v_fmac_f32_e32 v214, v53, v53
	s_waitcnt vmcnt(2) lgkmcnt(2)
	v_pk_add_f32 v[54:55], v[54:55], v[216:217]
	v_pk_add_f32 v[56:57], v[56:57], v[218:219]
	v_cvt_pk_bf16_f32 v216, v54, v55
	v_cvt_pk_bf16_f32 v217, v56, v57
	v_mul_f32_e32 v218, v54, v54
	v_fmac_f32_e32 v218, v55, v55
	v_fmac_f32_e32 v218, v56, v56
	v_fmac_f32_e32 v218, v57, v57
	s_waitcnt vmcnt(1) lgkmcnt(1)
	v_pk_add_f32 v[58:59], v[58:59], v[220:221]
	v_pk_add_f32 v[60:61], v[60:61], v[222:223]
	v_cvt_pk_bf16_f32 v220, v58, v59
	v_cvt_pk_bf16_f32 v221, v60, v61
	v_mul_f32_e32 v222, v58, v58
	v_fmac_f32_e32 v222, v59, v59
	v_fmac_f32_e32 v222, v60, v60
	v_fmac_f32_e32 v222, v61, v61
	s_waitcnt vmcnt(0) lgkmcnt(0)
	v_pk_add_f32 v[62:63], v[62:63], v[224:225]
	v_pk_add_f32 v[64:65], v[64:65], v[226:227]
	v_cvt_pk_bf16_f32 v224, v62, v63
	v_cvt_pk_bf16_f32 v225, v64, v65
	v_mul_f32_e32 v226, v62, v62
	v_fmac_f32_e32 v226, v63, v63
	v_fmac_f32_e32 v226, v64, v64
	v_fmac_f32_e32 v226, v65, v65
	s_mov_b32 s56, s58
	s_mov_b32 s57, s59
	s_mov_b32 s40, s46
	s_mov_b32 s41, s47
	global_store_dwordx4 v240, v[2:5], s[56:57]
	global_store_dwordx2 v244, v[136:137], s[40:41]
	s_add_u32 s56, s56, 0x10000
	s_addc_u32 s57, s57, 0
	s_add_u32 s40, s40, 0x8400
	s_addc_u32 s41, s41, 0
	global_store_dwordx4 v240, v[6:9], s[56:57]
	global_store_dwordx2 v244, v[140:141], s[40:41]
	s_add_u32 s56, s56, 0x10000
	s_addc_u32 s57, s57, 0
	s_add_u32 s40, s40, 0x8400
	s_addc_u32 s41, s41, 0
	global_store_dwordx4 v240, v[10:13], s[56:57]
	global_store_dwordx2 v244, v[144:145], s[40:41]
	s_add_u32 s56, s56, 0x10000
	s_addc_u32 s57, s57, 0
	s_add_u32 s40, s40, 0x8400
	s_addc_u32 s41, s41, 0
	global_store_dwordx4 v240, v[14:17], s[56:57]
	global_store_dwordx2 v244, v[148:149], s[40:41]
	s_add_u32 s56, s56, 0x10000
	s_addc_u32 s57, s57, 0
	s_add_u32 s40, s40, 0x8400
	s_addc_u32 s41, s41, 0
	global_store_dwordx4 v240, v[18:21], s[56:57]
	global_store_dwordx2 v244, v[172:173], s[40:41]
	s_add_u32 s56, s56, 0x10000
	s_addc_u32 s57, s57, 0
	s_add_u32 s40, s40, 0x8400
	s_addc_u32 s41, s41, 0
	global_store_dwordx4 v240, v[22:25], s[56:57]
	global_store_dwordx2 v244, v[176:177], s[40:41]
	s_add_u32 s56, s56, 0x10000
	s_addc_u32 s57, s57, 0
	s_add_u32 s40, s40, 0x8400
	s_addc_u32 s41, s41, 0
	global_store_dwordx4 v240, v[26:29], s[56:57]
	global_store_dwordx2 v244, v[180:181], s[40:41]
	s_add_u32 s56, s56, 0x10000
	s_addc_u32 s57, s57, 0
	s_add_u32 s40, s40, 0x8400
	s_addc_u32 s41, s41, 0
	global_store_dwordx4 v240, v[30:33], s[56:57]
	global_store_dwordx2 v244, v[184:185], s[40:41]
	s_add_u32 s56, s56, 0x10000
	s_addc_u32 s57, s57, 0
	s_add_u32 s40, s40, 0x8400
	s_addc_u32 s41, s41, 0
	global_store_dwordx4 v240, v[34:37], s[56:57]
	global_store_dwordx2 v244, v[188:189], s[40:41]
	s_add_u32 s56, s56, 0x10000
	s_addc_u32 s57, s57, 0
	s_add_u32 s40, s40, 0x8400
	s_addc_u32 s41, s41, 0
	global_store_dwordx4 v240, v[38:41], s[56:57]
	global_store_dwordx2 v244, v[196:197], s[40:41]
	s_add_u32 s56, s56, 0x10000
	s_addc_u32 s57, s57, 0
	s_add_u32 s40, s40, 0x8400
	s_addc_u32 s41, s41, 0
	global_store_dwordx4 v240, v[42:45], s[56:57]
	global_store_dwordx2 v244, v[200:201], s[40:41]
	s_add_u32 s56, s56, 0x10000
	s_addc_u32 s57, s57, 0
	s_add_u32 s40, s40, 0x8400
	s_addc_u32 s41, s41, 0
	global_store_dwordx4 v240, v[46:49], s[56:57]
	global_store_dwordx2 v244, v[204:205], s[40:41]
	s_add_u32 s56, s56, 0x10000
	s_addc_u32 s57, s57, 0
	s_add_u32 s40, s40, 0x8400
	s_addc_u32 s41, s41, 0
	global_store_dwordx4 v240, v[50:53], s[56:57]
	global_store_dwordx2 v244, v[212:213], s[40:41]
	s_add_u32 s56, s56, 0x10000
	s_addc_u32 s57, s57, 0
	s_add_u32 s40, s40, 0x8400
	s_addc_u32 s41, s41, 0
	global_store_dwordx4 v240, v[54:57], s[56:57]
	global_store_dwordx2 v244, v[216:217], s[40:41]
	s_add_u32 s56, s56, 0x10000
	s_addc_u32 s57, s57, 0
	s_add_u32 s40, s40, 0x8400
	s_addc_u32 s41, s41, 0
	global_store_dwordx4 v240, v[58:61], s[56:57]
	global_store_dwordx2 v244, v[220:221], s[40:41]
	s_add_u32 s56, s56, 0x10000
	s_addc_u32 s57, s57, 0
	s_add_u32 s40, s40, 0x8400
	s_addc_u32 s41, s41, 0
	global_store_dwordx4 v240, v[62:65], s[56:57]
	global_store_dwordx2 v244, v[224:225], s[40:41]
	v_add_f32_dpp v138, v138, v138 quad_perm:[1,0,3,2] row_mask:0xf bank_mask:0xf
	v_add_f32_dpp v142, v142, v142 quad_perm:[1,0,3,2] row_mask:0xf bank_mask:0xf
	v_add_f32_dpp v146, v146, v146 quad_perm:[1,0,3,2] row_mask:0xf bank_mask:0xf
	v_add_f32_dpp v150, v150, v150 quad_perm:[1,0,3,2] row_mask:0xf bank_mask:0xf
	v_add_f32_dpp v174, v174, v174 quad_perm:[1,0,3,2] row_mask:0xf bank_mask:0xf
	v_add_f32_dpp v178, v178, v178 quad_perm:[1,0,3,2] row_mask:0xf bank_mask:0xf
	v_add_f32_dpp v182, v182, v182 quad_perm:[1,0,3,2] row_mask:0xf bank_mask:0xf
	v_add_f32_dpp v186, v186, v186 quad_perm:[1,0,3,2] row_mask:0xf bank_mask:0xf
	v_add_f32_dpp v190, v190, v190 quad_perm:[1,0,3,2] row_mask:0xf bank_mask:0xf
	v_add_f32_dpp v198, v198, v198 quad_perm:[1,0,3,2] row_mask:0xf bank_mask:0xf
	v_add_f32_dpp v202, v202, v202 quad_perm:[1,0,3,2] row_mask:0xf bank_mask:0xf
	v_add_f32_dpp v206, v206, v206 quad_perm:[1,0,3,2] row_mask:0xf bank_mask:0xf
	v_add_f32_dpp v214, v214, v214 quad_perm:[1,0,3,2] row_mask:0xf bank_mask:0xf
	v_add_f32_dpp v218, v218, v218 quad_perm:[1,0,3,2] row_mask:0xf bank_mask:0xf
	v_add_f32_dpp v222, v222, v222 quad_perm:[1,0,3,2] row_mask:0xf bank_mask:0xf
	v_add_f32_dpp v226, v226, v226 quad_perm:[1,0,3,2] row_mask:0xf bank_mask:0xf
	v_add_f32_dpp v138, v138, v138 quad_perm:[2,3,0,1] row_mask:0xf bank_mask:0xf
	v_add_f32_dpp v142, v142, v142 quad_perm:[2,3,0,1] row_mask:0xf bank_mask:0xf
	v_add_f32_dpp v146, v146, v146 quad_perm:[2,3,0,1] row_mask:0xf bank_mask:0xf
	v_add_f32_dpp v150, v150, v150 quad_perm:[2,3,0,1] row_mask:0xf bank_mask:0xf
	v_add_f32_dpp v174, v174, v174 quad_perm:[2,3,0,1] row_mask:0xf bank_mask:0xf
	v_add_f32_dpp v178, v178, v178 quad_perm:[2,3,0,1] row_mask:0xf bank_mask:0xf
	v_add_f32_dpp v182, v182, v182 quad_perm:[2,3,0,1] row_mask:0xf bank_mask:0xf
	v_add_f32_dpp v186, v186, v186 quad_perm:[2,3,0,1] row_mask:0xf bank_mask:0xf
	v_add_f32_dpp v190, v190, v190 quad_perm:[2,3,0,1] row_mask:0xf bank_mask:0xf
	v_add_f32_dpp v198, v198, v198 quad_perm:[2,3,0,1] row_mask:0xf bank_mask:0xf
	v_add_f32_dpp v202, v202, v202 quad_perm:[2,3,0,1] row_mask:0xf bank_mask:0xf
	v_add_f32_dpp v206, v206, v206 quad_perm:[2,3,0,1] row_mask:0xf bank_mask:0xf
	v_add_f32_dpp v214, v214, v214 quad_perm:[2,3,0,1] row_mask:0xf bank_mask:0xf
	v_add_f32_dpp v218, v218, v218 quad_perm:[2,3,0,1] row_mask:0xf bank_mask:0xf
	v_add_f32_dpp v222, v222, v222 quad_perm:[2,3,0,1] row_mask:0xf bank_mask:0xf
	v_add_f32_dpp v226, v226, v226 quad_perm:[2,3,0,1] row_mask:0xf bank_mask:0xf
	v_add_f32_dpp v138, v138, v138 row_half_mirror row_mask:0xf bank_mask:0xf
	v_add_f32_dpp v142, v142, v142 row_half_mirror row_mask:0xf bank_mask:0xf
	v_add_f32_dpp v146, v146, v146 row_half_mirror row_mask:0xf bank_mask:0xf
	v_add_f32_dpp v150, v150, v150 row_half_mirror row_mask:0xf bank_mask:0xf
	v_add_f32_dpp v174, v174, v174 row_half_mirror row_mask:0xf bank_mask:0xf
	v_add_f32_dpp v178, v178, v178 row_half_mirror row_mask:0xf bank_mask:0xf
	v_add_f32_dpp v182, v182, v182 row_half_mirror row_mask:0xf bank_mask:0xf
	v_add_f32_dpp v186, v186, v186 row_half_mirror row_mask:0xf bank_mask:0xf
	v_add_f32_dpp v190, v190, v190 row_half_mirror row_mask:0xf bank_mask:0xf
	v_add_f32_dpp v198, v198, v198 row_half_mirror row_mask:0xf bank_mask:0xf
	v_add_f32_dpp v202, v202, v202 row_half_mirror row_mask:0xf bank_mask:0xf
	v_add_f32_dpp v206, v206, v206 row_half_mirror row_mask:0xf bank_mask:0xf
	v_add_f32_dpp v214, v214, v214 row_half_mirror row_mask:0xf bank_mask:0xf
	v_add_f32_dpp v218, v218, v218 row_half_mirror row_mask:0xf bank_mask:0xf
	v_add_f32_dpp v222, v222, v222 row_half_mirror row_mask:0xf bank_mask:0xf
	v_add_f32_dpp v226, v226, v226 row_half_mirror row_mask:0xf bank_mask:0xf
	v_add_f32_dpp v138, v138, v138 row_mirror row_mask:0xf bank_mask:0xf
	v_add_f32_dpp v142, v142, v142 row_mirror row_mask:0xf bank_mask:0xf
	v_add_f32_dpp v146, v146, v146 row_mirror row_mask:0xf bank_mask:0xf
	v_add_f32_dpp v150, v150, v150 row_mirror row_mask:0xf bank_mask:0xf
	v_add_f32_dpp v174, v174, v174 row_mirror row_mask:0xf bank_mask:0xf
	v_add_f32_dpp v178, v178, v178 row_mirror row_mask:0xf bank_mask:0xf
	v_add_f32_dpp v182, v182, v182 row_mirror row_mask:0xf bank_mask:0xf
	v_add_f32_dpp v186, v186, v186 row_mirror row_mask:0xf bank_mask:0xf
	v_add_f32_dpp v190, v190, v190 row_mirror row_mask:0xf bank_mask:0xf
	v_add_f32_dpp v198, v198, v198 row_mirror row_mask:0xf bank_mask:0xf
	v_add_f32_dpp v202, v202, v202 row_mirror row_mask:0xf bank_mask:0xf
	v_add_f32_dpp v206, v206, v206 row_mirror row_mask:0xf bank_mask:0xf
	v_add_f32_dpp v214, v214, v214 row_mirror row_mask:0xf bank_mask:0xf
	v_add_f32_dpp v218, v218, v218 row_mirror row_mask:0xf bank_mask:0xf
	v_add_f32_dpp v222, v222, v222 row_mirror row_mask:0xf bank_mask:0xf
	v_add_f32_dpp v226, v226, v226 row_mirror row_mask:0xf bank_mask:0xf
	v_add_f32_dpp v138, v138, v138 row_bcast:15 row_mask:0xa bank_mask:0xf
	v_add_f32_dpp v142, v142, v142 row_bcast:15 row_mask:0xa bank_mask:0xf
	v_add_f32_dpp v146, v146, v146 row_bcast:15 row_mask:0xa bank_mask:0xf
	v_add_f32_dpp v150, v150, v150 row_bcast:15 row_mask:0xa bank_mask:0xf
	v_add_f32_dpp v174, v174, v174 row_bcast:15 row_mask:0xa bank_mask:0xf
	v_add_f32_dpp v178, v178, v178 row_bcast:15 row_mask:0xa bank_mask:0xf
	v_add_f32_dpp v182, v182, v182 row_bcast:15 row_mask:0xa bank_mask:0xf
	v_add_f32_dpp v186, v186, v186 row_bcast:15 row_mask:0xa bank_mask:0xf
	v_add_f32_dpp v190, v190, v190 row_bcast:15 row_mask:0xa bank_mask:0xf
	v_add_f32_dpp v198, v198, v198 row_bcast:15 row_mask:0xa bank_mask:0xf
	v_add_f32_dpp v202, v202, v202 row_bcast:15 row_mask:0xa bank_mask:0xf
	v_add_f32_dpp v206, v206, v206 row_bcast:15 row_mask:0xa bank_mask:0xf
	v_add_f32_dpp v214, v214, v214 row_bcast:15 row_mask:0xa bank_mask:0xf
	v_add_f32_dpp v218, v218, v218 row_bcast:15 row_mask:0xa bank_mask:0xf
	v_add_f32_dpp v222, v222, v222 row_bcast:15 row_mask:0xa bank_mask:0xf
	v_add_f32_dpp v226, v226, v226 row_bcast:15 row_mask:0xa bank_mask:0xf
	s_mov_b32 exec_lo, 0x10000
	s_mov_b32 exec_hi, 0x10000
	global_atomic_add_f32 v245, v138, s[48:49]
	global_atomic_add_f32 v245, v142, s[48:49] offset:32
	global_atomic_add_f32 v245, v146, s[48:49] offset:64
	global_atomic_add_f32 v245, v150, s[48:49] offset:96
	global_atomic_add_f32 v245, v174, s[48:49] offset:128
	global_atomic_add_f32 v245, v178, s[48:49] offset:160
	global_atomic_add_f32 v245, v182, s[48:49] offset:192
	global_atomic_add_f32 v245, v186, s[48:49] offset:224
	global_atomic_add_f32 v245, v190, s[48:49] offset:256
	global_atomic_add_f32 v245, v198, s[48:49] offset:288
	global_atomic_add_f32 v245, v202, s[48:49] offset:320
	global_atomic_add_f32 v245, v206, s[48:49] offset:352
	global_atomic_add_f32 v245, v214, s[48:49] offset:384
	global_atomic_add_f32 v245, v218, s[48:49] offset:416
	global_atomic_add_f32 v245, v222, s[48:49] offset:448
	global_atomic_add_f32 v245, v226, s[48:49] offset:480
	s_mov_b64 exec, -1
	s_add_u32 s44, s44, 0x1000
	s_addc_u32 s45, s45, 0
	s_add_u32 s58, s58, 0x1000
	s_addc_u32 s59, s59, 0
	s_add_u32 s46, s46, 0x800
	s_addc_u32 s47, s47, 0
	s_waitcnt lgkmcnt(0)
	s_barrier
	s_mov_b32 s56, s44
	s_mov_b32 s57, s45
	global_load_dwordx4 v[136:139], v240, s[56:57]
	s_add_u32 s56, s56, 0x10000
	s_addc_u32 s57, s57, 0
	global_load_dwordx4 v[140:143], v240, s[56:57]
	s_add_u32 s56, s56, 0x10000
	s_addc_u32 s57, s57, 0
	global_load_dwordx4 v[144:147], v240, s[56:57]
	s_add_u32 s56, s56, 0x10000
	s_addc_u32 s57, s57, 0
	global_load_dwordx4 v[148:151], v240, s[56:57]
	s_add_u32 s56, s56, 0x10000
	s_addc_u32 s57, s57, 0
	global_load_dwordx4 v[172:175], v240, s[56:57]
	s_add_u32 s56, s56, 0x10000
	s_addc_u32 s57, s57, 0
	global_load_dwordx4 v[176:179], v240, s[56:57]
	s_add_u32 s56, s56, 0x10000
	s_addc_u32 s57, s57, 0
	global_load_dwordx4 v[180:183], v240, s[56:57]
	s_add_u32 s56, s56, 0x10000
	s_addc_u32 s57, s57, 0
	global_load_dwordx4 v[184:187], v240, s[56:57]
	s_add_u32 s56, s56, 0x10000
	s_addc_u32 s57, s57, 0
	global_load_dwordx4 v[188:191], v240, s[56:57]
	s_add_u32 s56, s56, 0x10000
	s_addc_u32 s57, s57, 0
	global_load_dwordx4 v[196:199], v240, s[56:57]
	s_add_u32 s56, s56, 0x10000
	s_addc_u32 s57, s57, 0
	global_load_dwordx4 v[200:203], v240, s[56:57]
	s_add_u32 s56, s56, 0x10000
	s_addc_u32 s57, s57, 0
	global_load_dwordx4 v[204:207], v240, s[56:57]
	s_add_u32 s56, s56, 0x10000
	s_addc_u32 s57, s57, 0
	global_load_dwordx4 v[212:215], v240, s[56:57]
	s_add_u32 s56, s56, 0x10000
	s_addc_u32 s57, s57, 0
	global_load_dwordx4 v[216:219], v240, s[56:57]
	s_add_u32 s56, s56, 0x10000
	s_addc_u32 s57, s57, 0
	global_load_dwordx4 v[220:223], v240, s[56:57]
	s_add_u32 s56, s56, 0x10000
	s_addc_u32 s57, s57, 0
	global_load_dwordx4 v[224:227], v240, s[56:57]
	ds_write_b32 v238, v66
	ds_write_b32 v238, v67 offset:528
	ds_write_b32 v238, v68 offset:1056
	ds_write_b32 v238, v69 offset:1584
	ds_write_b32 v238, v70 offset:64
	ds_write_b32 v238, v71 offset:592
	ds_write_b32 v238, v72 offset:1120
	ds_write_b32 v238, v73 offset:1648
	ds_write_b32 v238, v74 offset:128
	ds_write_b32 v238, v75 offset:656
	ds_write_b32 v238, v76 offset:1184
	ds_write_b32 v238, v77 offset:1712
	ds_write_b32 v238, v78 offset:192
	ds_write_b32 v238, v79 offset:720
	ds_write_b32 v238, v80 offset:1248
	ds_write_b32 v238, v81 offset:1776
	ds_write_b32 v238, v82 offset:8448
	ds_write_b32 v238, v83 offset:8976
	ds_write_b32 v238, v84 offset:9504
	ds_write_b32 v238, v85 offset:10032
	ds_write_b32 v238, v86 offset:8512
	ds_write_b32 v238, v87 offset:9040
	ds_write_b32 v238, v88 offset:9568
	ds_write_b32 v238, v89 offset:10096
	ds_write_b32 v238, v90 offset:8576
	ds_write_b32 v238, v91 offset:9104
	ds_write_b32 v238, v92 offset:9632
	ds_write_b32 v238, v93 offset:10160
	ds_write_b32 v238, v94 offset:8640
	ds_write_b32 v238, v95 offset:9168
	ds_write_b32 v238, v96 offset:9696
	ds_write_b32 v238, v97 offset:10224
	ds_write_b32 v238, v98 offset:16896
	ds_write_b32 v238, v99 offset:17424
	ds_write_b32 v238, v100 offset:17952
	ds_write_b32 v238, v101 offset:18480
	ds_write_b32 v238, v102 offset:16960
	ds_write_b32 v238, v103 offset:17488
	ds_write_b32 v238, v104 offset:18016
	ds_write_b32 v238, v105 offset:18544
	ds_write_b32 v238, v106 offset:17024
	ds_write_b32 v238, v107 offset:17552
	ds_write_b32 v238, v108 offset:18080
	ds_write_b32 v238, v109 offset:18608
	ds_write_b32 v238, v110 offset:17088
	ds_write_b32 v238, v111 offset:17616
	ds_write_b32 v238, v112 offset:18144
	ds_write_b32 v238, v113 offset:18672
	ds_write_b32 v238, v114 offset:25344
	ds_write_b32 v238, v115 offset:25872
	ds_write_b32 v238, v116 offset:26400
	ds_write_b32 v238, v117 offset:26928
	ds_write_b32 v238, v118 offset:25408
	ds_write_b32 v238, v119 offset:25936
	ds_write_b32 v238, v120 offset:26464
	ds_write_b32 v238, v121 offset:26992
	ds_write_b32 v238, v122 offset:25472
	ds_write_b32 v238, v123 offset:26000
	ds_write_b32 v238, v124 offset:26528
	ds_write_b32 v238, v125 offset:27056
	ds_write_b32 v238, v126 offset:25536
	ds_write_b32 v238, v127 offset:26064
	ds_write_b32 v238, v128 offset:26592
	ds_write_b32 v238, v129 offset:27120
	s_waitcnt lgkmcnt(0)
	s_barrier
	ds_read_b128 v[66:69], v239
	ds_read_b128 v[70:73], v239 offset:4224
	ds_read_b128 v[74:77], v239 offset:8448
	ds_read_b128 v[78:81], v239 offset:12672
	ds_read_b128 v[82:85], v239 offset:16896
	ds_read_b128 v[86:89], v239 offset:21120
	ds_read_b128 v[90:93], v239 offset:25344
	ds_read_b128 v[94:97], v239 offset:29568
	ds_read_b128 v[98:101], v239 offset:33792
	ds_read_b128 v[102:105], v239 offset:38016
	ds_read_b128 v[106:109], v239 offset:42240
	ds_read_b128 v[110:113], v239 offset:46464
	ds_read_b128 v[114:117], v239 offset:50688
	ds_read_b128 v[118:121], v239 offset:54912
	ds_read_b128 v[122:125], v239 offset:59136
	ds_read_b128 v[126:129], v239 offset:63360
	s_waitcnt vmcnt(15) lgkmcnt(15)
	v_pk_add_f32 v[66:67], v[66:67], v[136:137]
	v_pk_add_f32 v[68:69], v[68:69], v[138:139]
	v_cvt_pk_bf16_f32 v136, v66, v67
	v_cvt_pk_bf16_f32 v137, v68, v69
	v_mul_f32_e32 v138, v66, v66
	v_fmac_f32_e32 v138, v67, v67
	v_fmac_f32_e32 v138, v68, v68
	v_fmac_f32_e32 v138, v69, v69
	s_waitcnt vmcnt(14) lgkmcnt(14)
	v_pk_add_f32 v[70:71], v[70:71], v[140:141]
	v_pk_add_f32 v[72:73], v[72:73], v[142:143]
	v_cvt_pk_bf16_f32 v140, v70, v71
	v_cvt_pk_bf16_f32 v141, v72, v73
	v_mul_f32_e32 v142, v70, v70
	v_fmac_f32_e32 v142, v71, v71
	v_fmac_f32_e32 v142, v72, v72
	v_fmac_f32_e32 v142, v73, v73
	s_waitcnt vmcnt(13) lgkmcnt(13)
	v_pk_add_f32 v[74:75], v[74:75], v[144:145]
	v_pk_add_f32 v[76:77], v[76:77], v[146:147]
	v_cvt_pk_bf16_f32 v144, v74, v75
	v_cvt_pk_bf16_f32 v145, v76, v77
	v_mul_f32_e32 v146, v74, v74
	v_fmac_f32_e32 v146, v75, v75
	v_fmac_f32_e32 v146, v76, v76
	v_fmac_f32_e32 v146, v77, v77
	s_waitcnt vmcnt(12) lgkmcnt(12)
	v_pk_add_f32 v[78:79], v[78:79], v[148:149]
	v_pk_add_f32 v[80:81], v[80:81], v[150:151]
	v_cvt_pk_bf16_f32 v148, v78, v79
	v_cvt_pk_bf16_f32 v149, v80, v81
	v_mul_f32_e32 v150, v78, v78
	v_fmac_f32_e32 v150, v79, v79
	v_fmac_f32_e32 v150, v80, v80
	v_fmac_f32_e32 v150, v81, v81
	s_waitcnt vmcnt(11) lgkmcnt(11)
	v_pk_add_f32 v[82:83], v[82:83], v[172:173]
	v_pk_add_f32 v[84:85], v[84:85], v[174:175]
	v_cvt_pk_bf16_f32 v172, v82, v83
	v_cvt_pk_bf16_f32 v173, v84, v85
	v_mul_f32_e32 v174, v82, v82
	v_fmac_f32_e32 v174, v83, v83
	v_fmac_f32_e32 v174, v84, v84
	v_fmac_f32_e32 v174, v85, v85
	s_waitcnt vmcnt(10) lgkmcnt(10)
	v_pk_add_f32 v[86:87], v[86:87], v[176:177]
	v_pk_add_f32 v[88:89], v[88:89], v[178:179]
	v_cvt_pk_bf16_f32 v176, v86, v87
	v_cvt_pk_bf16_f32 v177, v88, v89
	v_mul_f32_e32 v178, v86, v86
	v_fmac_f32_e32 v178, v87, v87
	v_fmac_f32_e32 v178, v88, v88
	v_fmac_f32_e32 v178, v89, v89
	s_waitcnt vmcnt(9) lgkmcnt(9)
	v_pk_add_f32 v[90:91], v[90:91], v[180:181]
	v_pk_add_f32 v[92:93], v[92:93], v[182:183]
	v_cvt_pk_bf16_f32 v180, v90, v91
	v_cvt_pk_bf16_f32 v181, v92, v93
	v_mul_f32_e32 v182, v90, v90
	v_fmac_f32_e32 v182, v91, v91
	v_fmac_f32_e32 v182, v92, v92
	v_fmac_f32_e32 v182, v93, v93
	s_waitcnt vmcnt(8) lgkmcnt(8)
	v_pk_add_f32 v[94:95], v[94:95], v[184:185]
	v_pk_add_f32 v[96:97], v[96:97], v[186:187]
	v_cvt_pk_bf16_f32 v184, v94, v95
	v_cvt_pk_bf16_f32 v185, v96, v97
	v_mul_f32_e32 v186, v94, v94
	v_fmac_f32_e32 v186, v95, v95
	v_fmac_f32_e32 v186, v96, v96
	v_fmac_f32_e32 v186, v97, v97
	s_waitcnt vmcnt(7) lgkmcnt(7)
	v_pk_add_f32 v[98:99], v[98:99], v[188:189]
	v_pk_add_f32 v[100:101], v[100:101], v[190:191]
	v_cvt_pk_bf16_f32 v188, v98, v99
	v_cvt_pk_bf16_f32 v189, v100, v101
	v_mul_f32_e32 v190, v98, v98
	v_fmac_f32_e32 v190, v99, v99
	v_fmac_f32_e32 v190, v100, v100
	v_fmac_f32_e32 v190, v101, v101
	s_waitcnt vmcnt(6) lgkmcnt(6)
	v_pk_add_f32 v[102:103], v[102:103], v[196:197]
	v_pk_add_f32 v[104:105], v[104:105], v[198:199]
	v_cvt_pk_bf16_f32 v196, v102, v103
	v_cvt_pk_bf16_f32 v197, v104, v105
	v_mul_f32_e32 v198, v102, v102
	v_fmac_f32_e32 v198, v103, v103
	v_fmac_f32_e32 v198, v104, v104
	v_fmac_f32_e32 v198, v105, v105
	s_waitcnt vmcnt(5) lgkmcnt(5)
	v_pk_add_f32 v[106:107], v[106:107], v[200:201]
	v_pk_add_f32 v[108:109], v[108:109], v[202:203]
	v_cvt_pk_bf16_f32 v200, v106, v107
	v_cvt_pk_bf16_f32 v201, v108, v109
	v_mul_f32_e32 v202, v106, v106
	v_fmac_f32_e32 v202, v107, v107
	v_fmac_f32_e32 v202, v108, v108
	v_fmac_f32_e32 v202, v109, v109
	s_waitcnt vmcnt(4) lgkmcnt(4)
	v_pk_add_f32 v[110:111], v[110:111], v[204:205]
	v_pk_add_f32 v[112:113], v[112:113], v[206:207]
	v_cvt_pk_bf16_f32 v204, v110, v111
	v_cvt_pk_bf16_f32 v205, v112, v113
	v_mul_f32_e32 v206, v110, v110
	v_fmac_f32_e32 v206, v111, v111
	v_fmac_f32_e32 v206, v112, v112
	v_fmac_f32_e32 v206, v113, v113
	s_waitcnt vmcnt(3) lgkmcnt(3)
	v_pk_add_f32 v[114:115], v[114:115], v[212:213]
	v_pk_add_f32 v[116:117], v[116:117], v[214:215]
	v_cvt_pk_bf16_f32 v212, v114, v115
	v_cvt_pk_bf16_f32 v213, v116, v117
	v_mul_f32_e32 v214, v114, v114
	v_fmac_f32_e32 v214, v115, v115
	v_fmac_f32_e32 v214, v116, v116
	v_fmac_f32_e32 v214, v117, v117
	s_waitcnt vmcnt(2) lgkmcnt(2)
	v_pk_add_f32 v[118:119], v[118:119], v[216:217]
	v_pk_add_f32 v[120:121], v[120:121], v[218:219]
	v_cvt_pk_bf16_f32 v216, v118, v119
	v_cvt_pk_bf16_f32 v217, v120, v121
	v_mul_f32_e32 v218, v118, v118
	v_fmac_f32_e32 v218, v119, v119
	v_fmac_f32_e32 v218, v120, v120
	v_fmac_f32_e32 v218, v121, v121
	s_waitcnt vmcnt(1) lgkmcnt(1)
	v_pk_add_f32 v[122:123], v[122:123], v[220:221]
	v_pk_add_f32 v[124:125], v[124:125], v[222:223]
	v_cvt_pk_bf16_f32 v220, v122, v123
	v_cvt_pk_bf16_f32 v221, v124, v125
	v_mul_f32_e32 v222, v122, v122
	v_fmac_f32_e32 v222, v123, v123
	v_fmac_f32_e32 v222, v124, v124
	v_fmac_f32_e32 v222, v125, v125
	s_waitcnt vmcnt(0) lgkmcnt(0)
	v_pk_add_f32 v[126:127], v[126:127], v[224:225]
	v_pk_add_f32 v[128:129], v[128:129], v[226:227]
	v_cvt_pk_bf16_f32 v224, v126, v127
	v_cvt_pk_bf16_f32 v225, v128, v129
	v_mul_f32_e32 v226, v126, v126
	v_fmac_f32_e32 v226, v127, v127
	v_fmac_f32_e32 v226, v128, v128
	v_fmac_f32_e32 v226, v129, v129
	s_mov_b32 s56, s58
	s_mov_b32 s57, s59
	s_mov_b32 s40, s46
	s_mov_b32 s41, s47
	global_store_dwordx4 v240, v[66:69], s[56:57]
	global_store_dwordx2 v244, v[136:137], s[40:41]
	s_add_u32 s56, s56, 0x10000
	s_addc_u32 s57, s57, 0
	s_add_u32 s40, s40, 0x8400
	s_addc_u32 s41, s41, 0
	global_store_dwordx4 v240, v[70:73], s[56:57]
	global_store_dwordx2 v244, v[140:141], s[40:41]
	s_add_u32 s56, s56, 0x10000
	s_addc_u32 s57, s57, 0
	s_add_u32 s40, s40, 0x8400
	s_addc_u32 s41, s41, 0
	global_store_dwordx4 v240, v[74:77], s[56:57]
	global_store_dwordx2 v244, v[144:145], s[40:41]
	s_add_u32 s56, s56, 0x10000
	s_addc_u32 s57, s57, 0
	s_add_u32 s40, s40, 0x8400
	s_addc_u32 s41, s41, 0
	global_store_dwordx4 v240, v[78:81], s[56:57]
	global_store_dwordx2 v244, v[148:149], s[40:41]
	s_add_u32 s56, s56, 0x10000
	s_addc_u32 s57, s57, 0
	s_add_u32 s40, s40, 0x8400
	s_addc_u32 s41, s41, 0
	global_store_dwordx4 v240, v[82:85], s[56:57]
	global_store_dwordx2 v244, v[172:173], s[40:41]
	s_add_u32 s56, s56, 0x10000
	s_addc_u32 s57, s57, 0
	s_add_u32 s40, s40, 0x8400
	s_addc_u32 s41, s41, 0
	global_store_dwordx4 v240, v[86:89], s[56:57]
	global_store_dwordx2 v244, v[176:177], s[40:41]
	s_add_u32 s56, s56, 0x10000
	s_addc_u32 s57, s57, 0
	s_add_u32 s40, s40, 0x8400
	s_addc_u32 s41, s41, 0
	global_store_dwordx4 v240, v[90:93], s[56:57]
	global_store_dwordx2 v244, v[180:181], s[40:41]
	s_add_u32 s56, s56, 0x10000
	s_addc_u32 s57, s57, 0
	s_add_u32 s40, s40, 0x8400
	s_addc_u32 s41, s41, 0
	global_store_dwordx4 v240, v[94:97], s[56:57]
	global_store_dwordx2 v244, v[184:185], s[40:41]
	s_add_u32 s56, s56, 0x10000
	s_addc_u32 s57, s57, 0
	s_add_u32 s40, s40, 0x8400
	s_addc_u32 s41, s41, 0
	global_store_dwordx4 v240, v[98:101], s[56:57]
	global_store_dwordx2 v244, v[188:189], s[40:41]
	s_add_u32 s56, s56, 0x10000
	s_addc_u32 s57, s57, 0
	s_add_u32 s40, s40, 0x8400
	s_addc_u32 s41, s41, 0
	global_store_dwordx4 v240, v[102:105], s[56:57]
	global_store_dwordx2 v244, v[196:197], s[40:41]
	s_add_u32 s56, s56, 0x10000
	s_addc_u32 s57, s57, 0
	s_add_u32 s40, s40, 0x8400
	s_addc_u32 s41, s41, 0
	global_store_dwordx4 v240, v[106:109], s[56:57]
	global_store_dwordx2 v244, v[200:201], s[40:41]
	s_add_u32 s56, s56, 0x10000
	s_addc_u32 s57, s57, 0
	s_add_u32 s40, s40, 0x8400
	s_addc_u32 s41, s41, 0
	global_store_dwordx4 v240, v[110:113], s[56:57]
	global_store_dwordx2 v244, v[204:205], s[40:41]
	s_add_u32 s56, s56, 0x10000
	s_addc_u32 s57, s57, 0
	s_add_u32 s40, s40, 0x8400
	s_addc_u32 s41, s41, 0
	global_store_dwordx4 v240, v[114:117], s[56:57]
	global_store_dwordx2 v244, v[212:213], s[40:41]
	s_add_u32 s56, s56, 0x10000
	s_addc_u32 s57, s57, 0
	s_add_u32 s40, s40, 0x8400
	s_addc_u32 s41, s41, 0
	global_store_dwordx4 v240, v[118:121], s[56:57]
	global_store_dwordx2 v244, v[216:217], s[40:41]
	s_add_u32 s56, s56, 0x10000
	s_addc_u32 s57, s57, 0
	s_add_u32 s40, s40, 0x8400
	s_addc_u32 s41, s41, 0
	global_store_dwordx4 v240, v[122:125], s[56:57]
	global_store_dwordx2 v244, v[220:221], s[40:41]
	s_add_u32 s56, s56, 0x10000
	s_addc_u32 s57, s57, 0
	s_add_u32 s40, s40, 0x8400
	s_addc_u32 s41, s41, 0
	global_store_dwordx4 v240, v[126:129], s[56:57]
	global_store_dwordx2 v244, v[224:225], s[40:41]
	v_add_f32_dpp v138, v138, v138 quad_perm:[1,0,3,2] row_mask:0xf bank_mask:0xf
	v_add_f32_dpp v142, v142, v142 quad_perm:[1,0,3,2] row_mask:0xf bank_mask:0xf
	v_add_f32_dpp v146, v146, v146 quad_perm:[1,0,3,2] row_mask:0xf bank_mask:0xf
	v_add_f32_dpp v150, v150, v150 quad_perm:[1,0,3,2] row_mask:0xf bank_mask:0xf
	v_add_f32_dpp v174, v174, v174 quad_perm:[1,0,3,2] row_mask:0xf bank_mask:0xf
	v_add_f32_dpp v178, v178, v178 quad_perm:[1,0,3,2] row_mask:0xf bank_mask:0xf
	v_add_f32_dpp v182, v182, v182 quad_perm:[1,0,3,2] row_mask:0xf bank_mask:0xf
	v_add_f32_dpp v186, v186, v186 quad_perm:[1,0,3,2] row_mask:0xf bank_mask:0xf
	v_add_f32_dpp v190, v190, v190 quad_perm:[1,0,3,2] row_mask:0xf bank_mask:0xf
	v_add_f32_dpp v198, v198, v198 quad_perm:[1,0,3,2] row_mask:0xf bank_mask:0xf
	v_add_f32_dpp v202, v202, v202 quad_perm:[1,0,3,2] row_mask:0xf bank_mask:0xf
	v_add_f32_dpp v206, v206, v206 quad_perm:[1,0,3,2] row_mask:0xf bank_mask:0xf
	v_add_f32_dpp v214, v214, v214 quad_perm:[1,0,3,2] row_mask:0xf bank_mask:0xf
	v_add_f32_dpp v218, v218, v218 quad_perm:[1,0,3,2] row_mask:0xf bank_mask:0xf
	v_add_f32_dpp v222, v222, v222 quad_perm:[1,0,3,2] row_mask:0xf bank_mask:0xf
	v_add_f32_dpp v226, v226, v226 quad_perm:[1,0,3,2] row_mask:0xf bank_mask:0xf
	v_add_f32_dpp v138, v138, v138 quad_perm:[2,3,0,1] row_mask:0xf bank_mask:0xf
	v_add_f32_dpp v142, v142, v142 quad_perm:[2,3,0,1] row_mask:0xf bank_mask:0xf
	v_add_f32_dpp v146, v146, v146 quad_perm:[2,3,0,1] row_mask:0xf bank_mask:0xf
	v_add_f32_dpp v150, v150, v150 quad_perm:[2,3,0,1] row_mask:0xf bank_mask:0xf
	v_add_f32_dpp v174, v174, v174 quad_perm:[2,3,0,1] row_mask:0xf bank_mask:0xf
	v_add_f32_dpp v178, v178, v178 quad_perm:[2,3,0,1] row_mask:0xf bank_mask:0xf
	v_add_f32_dpp v182, v182, v182 quad_perm:[2,3,0,1] row_mask:0xf bank_mask:0xf
	v_add_f32_dpp v186, v186, v186 quad_perm:[2,3,0,1] row_mask:0xf bank_mask:0xf
	v_add_f32_dpp v190, v190, v190 quad_perm:[2,3,0,1] row_mask:0xf bank_mask:0xf
	v_add_f32_dpp v198, v198, v198 quad_perm:[2,3,0,1] row_mask:0xf bank_mask:0xf
	v_add_f32_dpp v202, v202, v202 quad_perm:[2,3,0,1] row_mask:0xf bank_mask:0xf
	v_add_f32_dpp v206, v206, v206 quad_perm:[2,3,0,1] row_mask:0xf bank_mask:0xf
	v_add_f32_dpp v214, v214, v214 quad_perm:[2,3,0,1] row_mask:0xf bank_mask:0xf
	v_add_f32_dpp v218, v218, v218 quad_perm:[2,3,0,1] row_mask:0xf bank_mask:0xf
	v_add_f32_dpp v222, v222, v222 quad_perm:[2,3,0,1] row_mask:0xf bank_mask:0xf
	v_add_f32_dpp v226, v226, v226 quad_perm:[2,3,0,1] row_mask:0xf bank_mask:0xf
	v_add_f32_dpp v138, v138, v138 row_half_mirror row_mask:0xf bank_mask:0xf
	v_add_f32_dpp v142, v142, v142 row_half_mirror row_mask:0xf bank_mask:0xf
	v_add_f32_dpp v146, v146, v146 row_half_mirror row_mask:0xf bank_mask:0xf
	v_add_f32_dpp v150, v150, v150 row_half_mirror row_mask:0xf bank_mask:0xf
	v_add_f32_dpp v174, v174, v174 row_half_mirror row_mask:0xf bank_mask:0xf
	v_add_f32_dpp v178, v178, v178 row_half_mirror row_mask:0xf bank_mask:0xf
	v_add_f32_dpp v182, v182, v182 row_half_mirror row_mask:0xf bank_mask:0xf
	v_add_f32_dpp v186, v186, v186 row_half_mirror row_mask:0xf bank_mask:0xf
	v_add_f32_dpp v190, v190, v190 row_half_mirror row_mask:0xf bank_mask:0xf
	v_add_f32_dpp v198, v198, v198 row_half_mirror row_mask:0xf bank_mask:0xf
	v_add_f32_dpp v202, v202, v202 row_half_mirror row_mask:0xf bank_mask:0xf
	v_add_f32_dpp v206, v206, v206 row_half_mirror row_mask:0xf bank_mask:0xf
	v_add_f32_dpp v214, v214, v214 row_half_mirror row_mask:0xf bank_mask:0xf
	v_add_f32_dpp v218, v218, v218 row_half_mirror row_mask:0xf bank_mask:0xf
	v_add_f32_dpp v222, v222, v222 row_half_mirror row_mask:0xf bank_mask:0xf
	v_add_f32_dpp v226, v226, v226 row_half_mirror row_mask:0xf bank_mask:0xf
	v_add_f32_dpp v138, v138, v138 row_mirror row_mask:0xf bank_mask:0xf
	v_add_f32_dpp v142, v142, v142 row_mirror row_mask:0xf bank_mask:0xf
	v_add_f32_dpp v146, v146, v146 row_mirror row_mask:0xf bank_mask:0xf
	v_add_f32_dpp v150, v150, v150 row_mirror row_mask:0xf bank_mask:0xf
	v_add_f32_dpp v174, v174, v174 row_mirror row_mask:0xf bank_mask:0xf
	v_add_f32_dpp v178, v178, v178 row_mirror row_mask:0xf bank_mask:0xf
	v_add_f32_dpp v182, v182, v182 row_mirror row_mask:0xf bank_mask:0xf
	v_add_f32_dpp v186, v186, v186 row_mirror row_mask:0xf bank_mask:0xf
	v_add_f32_dpp v190, v190, v190 row_mirror row_mask:0xf bank_mask:0xf
	v_add_f32_dpp v198, v198, v198 row_mirror row_mask:0xf bank_mask:0xf
	v_add_f32_dpp v202, v202, v202 row_mirror row_mask:0xf bank_mask:0xf
	v_add_f32_dpp v206, v206, v206 row_mirror row_mask:0xf bank_mask:0xf
	v_add_f32_dpp v214, v214, v214 row_mirror row_mask:0xf bank_mask:0xf
	v_add_f32_dpp v218, v218, v218 row_mirror row_mask:0xf bank_mask:0xf
	v_add_f32_dpp v222, v222, v222 row_mirror row_mask:0xf bank_mask:0xf
	v_add_f32_dpp v226, v226, v226 row_mirror row_mask:0xf bank_mask:0xf
	v_add_f32_dpp v138, v138, v138 row_bcast:15 row_mask:0xa bank_mask:0xf
	v_add_f32_dpp v142, v142, v142 row_bcast:15 row_mask:0xa bank_mask:0xf
	v_add_f32_dpp v146, v146, v146 row_bcast:15 row_mask:0xa bank_mask:0xf
	v_add_f32_dpp v150, v150, v150 row_bcast:15 row_mask:0xa bank_mask:0xf
	v_add_f32_dpp v174, v174, v174 row_bcast:15 row_mask:0xa bank_mask:0xf
	v_add_f32_dpp v178, v178, v178 row_bcast:15 row_mask:0xa bank_mask:0xf
	v_add_f32_dpp v182, v182, v182 row_bcast:15 row_mask:0xa bank_mask:0xf
	v_add_f32_dpp v186, v186, v186 row_bcast:15 row_mask:0xa bank_mask:0xf
	v_add_f32_dpp v190, v190, v190 row_bcast:15 row_mask:0xa bank_mask:0xf
	v_add_f32_dpp v198, v198, v198 row_bcast:15 row_mask:0xa bank_mask:0xf
	v_add_f32_dpp v202, v202, v202 row_bcast:15 row_mask:0xa bank_mask:0xf
	v_add_f32_dpp v206, v206, v206 row_bcast:15 row_mask:0xa bank_mask:0xf
	v_add_f32_dpp v214, v214, v214 row_bcast:15 row_mask:0xa bank_mask:0xf
	v_add_f32_dpp v218, v218, v218 row_bcast:15 row_mask:0xa bank_mask:0xf
	v_add_f32_dpp v222, v222, v222 row_bcast:15 row_mask:0xa bank_mask:0xf
	v_add_f32_dpp v226, v226, v226 row_bcast:15 row_mask:0xa bank_mask:0xf
	s_mov_b32 exec_lo, 0x10000
	s_mov_b32 exec_hi, 0x10000
	global_atomic_add_f32 v245, v138, s[48:49]
	global_atomic_add_f32 v245, v142, s[48:49] offset:32
	global_atomic_add_f32 v245, v146, s[48:49] offset:64
	global_atomic_add_f32 v245, v150, s[48:49] offset:96
	global_atomic_add_f32 v245, v174, s[48:49] offset:128
	global_atomic_add_f32 v245, v178, s[48:49] offset:160
	global_atomic_add_f32 v245, v182, s[48:49] offset:192
	global_atomic_add_f32 v245, v186, s[48:49] offset:224
	global_atomic_add_f32 v245, v190, s[48:49] offset:256
	global_atomic_add_f32 v245, v198, s[48:49] offset:288
	global_atomic_add_f32 v245, v202, s[48:49] offset:320
	global_atomic_add_f32 v245, v206, s[48:49] offset:352
	global_atomic_add_f32 v245, v214, s[48:49] offset:384
	global_atomic_add_f32 v245, v218, s[48:49] offset:416
	global_atomic_add_f32 v245, v222, s[48:49] offset:448
	global_atomic_add_f32 v245, v226, s[48:49] offset:480
	s_mov_b64 exec, -1
	s_add_i32 s21, s21, s72
	s_cmpk_lt_i32 s21, 0x200
	s_waitcnt lgkmcnt(0)
	s_barrier
	s_cbranch_scc1 .Lres1_tile

.Lin2_loop:
	s_setprio 3
	v_add_u32_e32 v234, s22, v232
	v_add_u32_e32 v236, s28, v232
	v_add_u32_e32 v235, s22, v233
	v_add_u32_e32 v237, s28, v233
	ds_read_b128 v[136:139], v234
	ds_read_b128 v[188:191], v236
	ds_read_b128 v[196:199], v236 offset:2048
	ds_read_b128 v[200:203], v236 offset:4096
	ds_read_b128 v[204:207], v236 offset:6144
	ds_read_b128 v[140:143], v234 offset:2048
	ds_read_b128 v[144:147], v234 offset:4096
	ds_read_b128 v[148:151], v234 offset:6144
	ds_read_b128 v[172:175], v235
	ds_read_b128 v[212:215], v237
	ds_read_b128 v[216:219], v237 offset:2048
	ds_read_b128 v[220:223], v237 offset:4096
	ds_read_b128 v[224:227], v237 offset:6144
	ds_read_b128 v[176:179], v235 offset:2048
	ds_read_b128 v[180:183], v235 offset:4096
	ds_read_b128 v[184:187], v235 offset:6144
	s_add_i32 m0, s51, 0xc000
	s_nop 0
	global_load_lds_dwordx4 v228, s[44:45]
	s_add_i32 m0, s51, 0xc400
	s_nop 0
	global_load_lds_dwordx4 v230, s[44:45]
	s_add_i32 m0, s51, 0xe000
	s_nop 0
	global_load_lds_dwordx4 v229, s[44:45]
	s_add_i32 m0, s51, 0xe400
	s_nop 0
	global_load_lds_dwordx4 v231, s[44:45]
	s_add_i32 m0, s51, 0x10000
	s_nop 0
	global_load_lds_dwordx4 v228, s[46:47]
	s_add_i32 m0, s51, 0x10400
	s_nop 0
	global_load_lds_dwordx4 v230, s[46:47]
	s_waitcnt lgkmcnt(11)
	s_setprio 1
	v_mfma_f32_16x16x32_bf16 v[2:5], v[136:139], v[188:191], v[2:5]
	v_mfma_f32_16x16x32_bf16 v[6:9], v[136:139], v[196:199], v[6:9]
	v_mfma_f32_16x16x32_bf16 v[10:13], v[136:139], v[200:203], v[10:13]
	v_mfma_f32_16x16x32_bf16 v[14:17], v[136:139], v[204:207], v[14:17]
	s_waitcnt lgkmcnt(10)
	v_mfma_f32_16x16x32_bf16 v[18:21], v[140:143], v[188:191], v[18:21]
	v_mfma_f32_16x16x32_bf16 v[22:25], v[140:143], v[196:199], v[22:25]
	v_mfma_f32_16x16x32_bf16 v[26:29], v[140:143], v[200:203], v[26:29]
	v_mfma_f32_16x16x32_bf16 v[30:33], v[140:143], v[204:207], v[30:33]
	s_waitcnt lgkmcnt(9)
	v_mfma_f32_16x16x32_bf16 v[34:37], v[144:147], v[188:191], v[34:37]
	v_mfma_f32_16x16x32_bf16 v[38:41], v[144:147], v[196:199], v[38:41]
	v_mfma_f32_16x16x32_bf16 v[42:45], v[144:147], v[200:203], v[42:45]
	v_mfma_f32_16x16x32_bf16 v[46:49], v[144:147], v[204:207], v[46:49]
	s_waitcnt lgkmcnt(8)
	v_mfma_f32_16x16x32_bf16 v[50:53], v[148:151], v[188:191], v[50:53]
	v_mfma_f32_16x16x32_bf16 v[54:57], v[148:151], v[196:199], v[54:57]
	v_mfma_f32_16x16x32_bf16 v[58:61], v[148:151], v[200:203], v[58:61]
	v_mfma_f32_16x16x32_bf16 v[62:65], v[148:151], v[204:207], v[62:65]
	s_waitcnt lgkmcnt(3)
	v_mfma_f32_16x16x32_bf16 v[2:5], v[172:175], v[212:215], v[2:5]
	v_mfma_f32_16x16x32_bf16 v[6:9], v[172:175], v[216:219], v[6:9]
	v_mfma_f32_16x16x32_bf16 v[10:13], v[172:175], v[220:223], v[10:13]
	v_mfma_f32_16x16x32_bf16 v[14:17], v[172:175], v[224:227], v[14:17]
	s_waitcnt lgkmcnt(2)
	v_mfma_f32_16x16x32_bf16 v[18:21], v[176:179], v[212:215], v[18:21]
	v_mfma_f32_16x16x32_bf16 v[22:25], v[176:179], v[216:219], v[22:25]
	v_mfma_f32_16x16x32_bf16 v[26:29], v[176:179], v[220:223], v[26:29]
	v_mfma_f32_16x16x32_bf16 v[30:33], v[176:179], v[224:227], v[30:33]
	s_waitcnt lgkmcnt(1)
	v_mfma_f32_16x16x32_bf16 v[34:37], v[180:183], v[212:215], v[34:37]
	v_mfma_f32_16x16x32_bf16 v[38:41], v[180:183], v[216:219], v[38:41]
	v_mfma_f32_16x16x32_bf16 v[42:45], v[180:183], v[220:223], v[42:45]
	v_mfma_f32_16x16x32_bf16 v[46:49], v[180:183], v[224:227], v[46:49]
	s_waitcnt lgkmcnt(0)
	v_mfma_f32_16x16x32_bf16 v[50:53], v[184:187], v[212:215], v[50:53]
	v_mfma_f32_16x16x32_bf16 v[54:57], v[184:187], v[216:219], v[54:57]
	v_mfma_f32_16x16x32_bf16 v[58:61], v[184:187], v[220:223], v[58:61]
	v_mfma_f32_16x16x32_bf16 v[62:65], v[184:187], v[224:227], v[62:65]
	s_setprio 0
	s_waitcnt vmcnt(6)
	s_barrier
	s_setprio 3
	v_add_u32_e32 v236, s40, v232
	v_add_u32_e32 v237, s40, v233
	ds_read_b128 v[188:191], v236
	ds_read_b128 v[196:199], v236 offset:2048
	ds_read_b128 v[200:203], v236 offset:4096
	ds_read_b128 v[204:207], v236 offset:6144
	ds_read_b128 v[212:215], v237
	ds_read_b128 v[216:219], v237 offset:2048
	ds_read_b128 v[220:223], v237 offset:4096
	ds_read_b128 v[224:227], v237 offset:6144
	s_mov_b32 m0, s51
	s_nop 0
	global_load_lds_dwordx4 v229, s[46:47]
	s_add_i32 m0, s51, 0x400
	s_nop 0
	global_load_lds_dwordx4 v231, s[46:47]
	s_add_i32 m0, s51, 0x2000
	s_nop 0
	global_load_lds_dwordx4 v228, s[48:49]
	s_add_i32 m0, s51, 0x2400
	s_nop 0
	global_load_lds_dwordx4 v230, s[48:49]
	s_add_i32 m0, s51, 0x4000
	s_nop 0
	global_load_lds_dwordx4 v229, s[48:49]
	s_add_i32 m0, s51, 0x4400
	s_nop 0
	global_load_lds_dwordx4 v231, s[48:49]
	s_waitcnt lgkmcnt(7)
	s_setprio 1
	v_mfma_f32_16x16x32_bf16 v[66:69], v[136:139], v[188:191], v[66:69]
	v_mfma_f32_16x16x32_bf16 v[82:85], v[140:143], v[188:191], v[82:85]
	v_mfma_f32_16x16x32_bf16 v[98:101], v[144:147], v[188:191], v[98:101]
	v_mfma_f32_16x16x32_bf16 v[114:117], v[148:151], v[188:191], v[114:117]
	s_waitcnt lgkmcnt(6)
	v_mfma_f32_16x16x32_bf16 v[70:73], v[136:139], v[196:199], v[70:73]
	v_mfma_f32_16x16x32_bf16 v[86:89], v[140:143], v[196:199], v[86:89]
	v_mfma_f32_16x16x32_bf16 v[102:105], v[144:147], v[196:199], v[102:105]
	v_mfma_f32_16x16x32_bf16 v[118:121], v[148:151], v[196:199], v[118:121]
	s_waitcnt lgkmcnt(5)
	v_mfma_f32_16x16x32_bf16 v[74:77], v[136:139], v[200:203], v[74:77]
	v_mfma_f32_16x16x32_bf16 v[90:93], v[140:143], v[200:203], v[90:93]
	v_mfma_f32_16x16x32_bf16 v[106:109], v[144:147], v[200:203], v[106:109]
	v_mfma_f32_16x16x32_bf16 v[122:125], v[148:151], v[200:203], v[122:125]
	s_waitcnt lgkmcnt(4)
	v_mfma_f32_16x16x32_bf16 v[78:81], v[136:139], v[204:207], v[78:81]
	v_mfma_f32_16x16x32_bf16 v[94:97], v[140:143], v[204:207], v[94:97]
	v_mfma_f32_16x16x32_bf16 v[110:113], v[144:147], v[204:207], v[110:113]
	v_mfma_f32_16x16x32_bf16 v[126:129], v[148:151], v[204:207], v[126:129]
	s_waitcnt lgkmcnt(3)
	v_mfma_f32_16x16x32_bf16 v[66:69], v[172:175], v[212:215], v[66:69]
	v_mfma_f32_16x16x32_bf16 v[82:85], v[176:179], v[212:215], v[82:85]
	v_mfma_f32_16x16x32_bf16 v[98:101], v[180:183], v[212:215], v[98:101]
	v_mfma_f32_16x16x32_bf16 v[114:117], v[184:187], v[212:215], v[114:117]
	s_waitcnt lgkmcnt(2)
	v_mfma_f32_16x16x32_bf16 v[70:73], v[172:175], v[216:219], v[70:73]
	v_mfma_f32_16x16x32_bf16 v[86:89], v[176:179], v[216:219], v[86:89]
	v_mfma_f32_16x16x32_bf16 v[102:105], v[180:183], v[216:219], v[102:105]
	v_mfma_f32_16x16x32_bf16 v[118:121], v[184:187], v[216:219], v[118:121]
	s_waitcnt lgkmcnt(1)
	v_mfma_f32_16x16x32_bf16 v[74:77], v[172:175], v[220:223], v[74:77]
	v_mfma_f32_16x16x32_bf16 v[90:93], v[176:179], v[220:223], v[90:93]
	v_mfma_f32_16x16x32_bf16 v[106:109], v[180:183], v[220:223], v[106:109]
	v_mfma_f32_16x16x32_bf16 v[122:125], v[184:187], v[220:223], v[122:125]
	s_waitcnt lgkmcnt(0)
	v_mfma_f32_16x16x32_bf16 v[78:81], v[172:175], v[224:227], v[78:81]
	v_mfma_f32_16x16x32_bf16 v[94:97], v[176:179], v[224:227], v[94:97]
	v_mfma_f32_16x16x32_bf16 v[110:113], v[180:183], v[224:227], v[110:113]
	v_mfma_f32_16x16x32_bf16 v[126:129], v[184:187], v[224:227], v[126:129]
	s_setprio 0
	v_add_u32_e32 v228, 0x80, v228
	v_add_u32_e32 v229, 0x80, v229
	v_add_u32_e32 v230, 0x80, v230
	v_add_u32_e32 v231, 0x80, v231
	s_waitcnt vmcnt(4)
	s_barrier
	s_setprio 3
	v_add_u32_e32 v234, s23, v232
	v_add_u32_e32 v236, s29, v232
	v_add_u32_e32 v235, s23, v233
	v_add_u32_e32 v237, s29, v233
	ds_read_b128 v[136:139], v234
	ds_read_b128 v[188:191], v236
	ds_read_b128 v[196:199], v236 offset:2048
	ds_read_b128 v[200:203], v236 offset:4096
	ds_read_b128 v[204:207], v236 offset:6144
	ds_read_b128 v[140:143], v234 offset:2048
	ds_read_b128 v[144:147], v234 offset:4096
	ds_read_b128 v[148:151], v234 offset:6144
	ds_read_b128 v[172:175], v235
	ds_read_b128 v[212:215], v237
	ds_read_b128 v[216:219], v237 offset:2048
	ds_read_b128 v[220:223], v237 offset:4096
	ds_read_b128 v[224:227], v237 offset:6144
	ds_read_b128 v[176:179], v235 offset:2048
	ds_read_b128 v[180:183], v235 offset:4096
	ds_read_b128 v[184:187], v235 offset:6144
	s_add_i32 m0, s51, 0x6000
	s_nop 0
	global_load_lds_dwordx4 v228, s[44:45]
	s_add_i32 m0, s51, 0x6400
	s_nop 0
	global_load_lds_dwordx4 v230, s[44:45]
	s_add_i32 m0, s51, 0x8000
	s_nop 0
	global_load_lds_dwordx4 v229, s[44:45]
	s_add_i32 m0, s51, 0x8400
	s_nop 0
	global_load_lds_dwordx4 v231, s[44:45]
	s_add_i32 m0, s51, 0xa000
	s_nop 0
	global_load_lds_dwordx4 v228, s[46:47]
	s_add_i32 m0, s51, 0xa400
	s_nop 0
	global_load_lds_dwordx4 v230, s[46:47]
	s_waitcnt lgkmcnt(11)
	s_setprio 1
	v_mfma_f32_16x16x32_bf16 v[2:5], v[136:139], v[188:191], v[2:5]
	v_mfma_f32_16x16x32_bf16 v[6:9], v[136:139], v[196:199], v[6:9]
	v_mfma_f32_16x16x32_bf16 v[10:13], v[136:139], v[200:203], v[10:13]
	v_mfma_f32_16x16x32_bf16 v[14:17], v[136:139], v[204:207], v[14:17]
	s_waitcnt lgkmcnt(10)
	v_mfma_f32_16x16x32_bf16 v[18:21], v[140:143], v[188:191], v[18:21]
	v_mfma_f32_16x16x32_bf16 v[22:25], v[140:143], v[196:199], v[22:25]
	v_mfma_f32_16x16x32_bf16 v[26:29], v[140:143], v[200:203], v[26:29]
	v_mfma_f32_16x16x32_bf16 v[30:33], v[140:143], v[204:207], v[30:33]
	s_waitcnt lgkmcnt(9)
	v_mfma_f32_16x16x32_bf16 v[34:37], v[144:147], v[188:191], v[34:37]
	v_mfma_f32_16x16x32_bf16 v[38:41], v[144:147], v[196:199], v[38:41]
	v_mfma_f32_16x16x32_bf16 v[42:45], v[144:147], v[200:203], v[42:45]
	v_mfma_f32_16x16x32_bf16 v[46:49], v[144:147], v[204:207], v[46:49]
	s_waitcnt lgkmcnt(8)
	v_mfma_f32_16x16x32_bf16 v[50:53], v[148:151], v[188:191], v[50:53]
	v_mfma_f32_16x16x32_bf16 v[54:57], v[148:151], v[196:199], v[54:57]
	v_mfma_f32_16x16x32_bf16 v[58:61], v[148:151], v[200:203], v[58:61]
	v_mfma_f32_16x16x32_bf16 v[62:65], v[148:151], v[204:207], v[62:65]
	s_waitcnt lgkmcnt(3)
	v_mfma_f32_16x16x32_bf16 v[2:5], v[172:175], v[212:215], v[2:5]
	v_mfma_f32_16x16x32_bf16 v[6:9], v[172:175], v[216:219], v[6:9]
	v_mfma_f32_16x16x32_bf16 v[10:13], v[172:175], v[220:223], v[10:13]
	v_mfma_f32_16x16x32_bf16 v[14:17], v[172:175], v[224:227], v[14:17]
	s_waitcnt lgkmcnt(2)
	v_mfma_f32_16x16x32_bf16 v[18:21], v[176:179], v[212:215], v[18:21]
	v_mfma_f32_16x16x32_bf16 v[22:25], v[176:179], v[216:219], v[22:25]
	v_mfma_f32_16x16x32_bf16 v[26:29], v[176:179], v[220:223], v[26:29]
	v_mfma_f32_16x16x32_bf16 v[30:33], v[176:179], v[224:227], v[30:33]
	s_waitcnt lgkmcnt(1)
	v_mfma_f32_16x16x32_bf16 v[34:37], v[180:183], v[212:215], v[34:37]
	v_mfma_f32_16x16x32_bf16 v[38:41], v[180:183], v[216:219], v[38:41]
	v_mfma_f32_16x16x32_bf16 v[42:45], v[180:183], v[220:223], v[42:45]
	v_mfma_f32_16x16x32_bf16 v[46:49], v[180:183], v[224:227], v[46:49]
	s_waitcnt lgkmcnt(0)
	v_mfma_f32_16x16x32_bf16 v[50:53], v[184:187], v[212:215], v[50:53]
	v_mfma_f32_16x16x32_bf16 v[54:57], v[184:187], v[216:219], v[54:57]
	v_mfma_f32_16x16x32_bf16 v[58:61], v[184:187], v[220:223], v[58:61]
	v_mfma_f32_16x16x32_bf16 v[62:65], v[184:187], v[224:227], v[62:65]
	s_setprio 0
	s_waitcnt vmcnt(6)
	s_barrier
	s_setprio 3
	v_add_u32_e32 v236, s41, v232
	v_add_u32_e32 v237, s41, v233
	ds_read_b128 v[188:191], v236
	ds_read_b128 v[196:199], v236 offset:2048
	ds_read_b128 v[200:203], v236 offset:4096
	ds_read_b128 v[204:207], v236 offset:6144
	ds_read_b128 v[212:215], v237
	ds_read_b128 v[216:219], v237 offset:2048
	ds_read_b128 v[220:223], v237 offset:4096
	ds_read_b128 v[224:227], v237 offset:6144
	s_add_i32 m0, s51, 0xc000
	s_nop 0
	global_load_lds_dwordx4 v229, s[46:47]
	s_add_i32 m0, s51, 0xc400
	s_nop 0
	global_load_lds_dwordx4 v231, s[46:47]
	s_add_i32 m0, s51, 0xe000
	s_nop 0
	global_load_lds_dwordx4 v228, s[48:49]
	s_add_i32 m0, s51, 0xe400
	s_nop 0
	global_load_lds_dwordx4 v230, s[48:49]
	s_add_i32 m0, s51, 0x10000
	s_nop 0
	global_load_lds_dwordx4 v229, s[48:49]
	s_add_i32 m0, s51, 0x10400
	s_nop 0
	global_load_lds_dwordx4 v231, s[48:49]
	s_waitcnt lgkmcnt(7)
	s_setprio 1
	v_mfma_f32_16x16x32_bf16 v[66:69], v[136:139], v[188:191], v[66:69]
	v_mfma_f32_16x16x32_bf16 v[82:85], v[140:143], v[188:191], v[82:85]
	v_mfma_f32_16x16x32_bf16 v[98:101], v[144:147], v[188:191], v[98:101]
	v_mfma_f32_16x16x32_bf16 v[114:117], v[148:151], v[188:191], v[114:117]
	s_waitcnt lgkmcnt(6)
	v_mfma_f32_16x16x32_bf16 v[70:73], v[136:139], v[196:199], v[70:73]
	v_mfma_f32_16x16x32_bf16 v[86:89], v[140:143], v[196:199], v[86:89]
	v_mfma_f32_16x16x32_bf16 v[102:105], v[144:147], v[196:199], v[102:105]
	v_mfma_f32_16x16x32_bf16 v[118:121], v[148:151], v[196:199], v[118:121]
	s_waitcnt lgkmcnt(5)
	v_mfma_f32_16x16x32_bf16 v[74:77], v[136:139], v[200:203], v[74:77]
	v_mfma_f32_16x16x32_bf16 v[90:93], v[140:143], v[200:203], v[90:93]
	v_mfma_f32_16x16x32_bf16 v[106:109], v[144:147], v[200:203], v[106:109]
	v_mfma_f32_16x16x32_bf16 v[122:125], v[148:151], v[200:203], v[122:125]
	s_waitcnt lgkmcnt(4)
	v_mfma_f32_16x16x32_bf16 v[78:81], v[136:139], v[204:207], v[78:81]
	v_mfma_f32_16x16x32_bf16 v[94:97], v[140:143], v[204:207], v[94:97]
	v_mfma_f32_16x16x32_bf16 v[110:113], v[144:147], v[204:207], v[110:113]
	v_mfma_f32_16x16x32_bf16 v[126:129], v[148:151], v[204:207], v[126:129]
	s_waitcnt lgkmcnt(3)
	v_mfma_f32_16x16x32_bf16 v[66:69], v[172:175], v[212:215], v[66:69]
	v_mfma_f32_16x16x32_bf16 v[82:85], v[176:179], v[212:215], v[82:85]
	v_mfma_f32_16x16x32_bf16 v[98:101], v[180:183], v[212:215], v[98:101]
	v_mfma_f32_16x16x32_bf16 v[114:117], v[184:187], v[212:215], v[114:117]
	s_waitcnt lgkmcnt(2)
	v_mfma_f32_16x16x32_bf16 v[70:73], v[172:175], v[216:219], v[70:73]
	v_mfma_f32_16x16x32_bf16 v[86:89], v[176:179], v[216:219], v[86:89]
	v_mfma_f32_16x16x32_bf16 v[102:105], v[180:183], v[216:219], v[102:105]
	v_mfma_f32_16x16x32_bf16 v[118:121], v[184:187], v[216:219], v[118:121]
	s_waitcnt lgkmcnt(1)
	v_mfma_f32_16x16x32_bf16 v[74:77], v[172:175], v[220:223], v[74:77]
	v_mfma_f32_16x16x32_bf16 v[90:93], v[176:179], v[220:223], v[90:93]
	v_mfma_f32_16x16x32_bf16 v[106:109], v[180:183], v[220:223], v[106:109]
	v_mfma_f32_16x16x32_bf16 v[122:125], v[184:187], v[220:223], v[122:125]
	s_waitcnt lgkmcnt(0)
	v_mfma_f32_16x16x32_bf16 v[78:81], v[172:175], v[224:227], v[78:81]
	v_mfma_f32_16x16x32_bf16 v[94:97], v[176:179], v[224:227], v[94:97]
	v_mfma_f32_16x16x32_bf16 v[110:113], v[180:183], v[224:227], v[110:113]
	v_mfma_f32_16x16x32_bf16 v[126:129], v[184:187], v[224:227], v[126:129]
	s_setprio 0
	v_add_u32_e32 v228, 0x80, v228
	v_add_u32_e32 v229, 0x80, v229
	v_add_u32_e32 v230, 0x80, v230
	v_add_u32_e32 v231, 0x80, v231
	s_waitcnt vmcnt(4)
	s_barrier
	s_setprio 3
	v_add_u32_e32 v234, s24, v232
	v_add_u32_e32 v236, s30, v232
	v_add_u32_e32 v235, s24, v233
	v_add_u32_e32 v237, s30, v233
	ds_read_b128 v[136:139], v234
	ds_read_b128 v[188:191], v236
	ds_read_b128 v[196:199], v236 offset:2048
	ds_read_b128 v[200:203], v236 offset:4096
	ds_read_b128 v[204:207], v236 offset:6144
	ds_read_b128 v[140:143], v234 offset:2048
	ds_read_b128 v[144:147], v234 offset:4096
	ds_read_b128 v[148:151], v234 offset:6144
	ds_read_b128 v[172:175], v235
	ds_read_b128 v[212:215], v237
	ds_read_b128 v[216:219], v237 offset:2048
	ds_read_b128 v[220:223], v237 offset:4096
	ds_read_b128 v[224:227], v237 offset:6144
	ds_read_b128 v[176:179], v235 offset:2048
	ds_read_b128 v[180:183], v235 offset:4096
	ds_read_b128 v[184:187], v235 offset:6144
	s_mov_b32 m0, s51
	s_nop 0
	global_load_lds_dwordx4 v228, s[44:45]
	s_add_i32 m0, s51, 0x400
	s_nop 0
	global_load_lds_dwordx4 v230, s[44:45]
	s_add_i32 m0, s51, 0x2000
	s_nop 0
	global_load_lds_dwordx4 v229, s[44:45]
	s_add_i32 m0, s51, 0x2400
	s_nop 0
	global_load_lds_dwordx4 v231, s[44:45]
	s_add_i32 m0, s51, 0x4000
	s_nop 0
	global_load_lds_dwordx4 v228, s[46:47]
	s_add_i32 m0, s51, 0x4400
	s_nop 0
	global_load_lds_dwordx4 v230, s[46:47]
	s_waitcnt lgkmcnt(11)
	s_setprio 1
	v_mfma_f32_16x16x32_bf16 v[2:5], v[136:139], v[188:191], v[2:5]
	v_mfma_f32_16x16x32_bf16 v[6:9], v[136:139], v[196:199], v[6:9]
	v_mfma_f32_16x16x32_bf16 v[10:13], v[136:139], v[200:203], v[10:13]
	v_mfma_f32_16x16x32_bf16 v[14:17], v[136:139], v[204:207], v[14:17]
	s_waitcnt lgkmcnt(10)
	v_mfma_f32_16x16x32_bf16 v[18:21], v[140:143], v[188:191], v[18:21]
	v_mfma_f32_16x16x32_bf16 v[22:25], v[140:143], v[196:199], v[22:25]
	v_mfma_f32_16x16x32_bf16 v[26:29], v[140:143], v[200:203], v[26:29]
	v_mfma_f32_16x16x32_bf16 v[30:33], v[140:143], v[204:207], v[30:33]
	s_waitcnt lgkmcnt(9)
	v_mfma_f32_16x16x32_bf16 v[34:37], v[144:147], v[188:191], v[34:37]
	v_mfma_f32_16x16x32_bf16 v[38:41], v[144:147], v[196:199], v[38:41]
	v_mfma_f32_16x16x32_bf16 v[42:45], v[144:147], v[200:203], v[42:45]
	v_mfma_f32_16x16x32_bf16 v[46:49], v[144:147], v[204:207], v[46:49]
	s_waitcnt lgkmcnt(8)
	v_mfma_f32_16x16x32_bf16 v[50:53], v[148:151], v[188:191], v[50:53]
	v_mfma_f32_16x16x32_bf16 v[54:57], v[148:151], v[196:199], v[54:57]
	v_mfma_f32_16x16x32_bf16 v[58:61], v[148:151], v[200:203], v[58:61]
	v_mfma_f32_16x16x32_bf16 v[62:65], v[148:151], v[204:207], v[62:65]
	s_waitcnt lgkmcnt(3)
	v_mfma_f32_16x16x32_bf16 v[2:5], v[172:175], v[212:215], v[2:5]
	v_mfma_f32_16x16x32_bf16 v[6:9], v[172:175], v[216:219], v[6:9]
	v_mfma_f32_16x16x32_bf16 v[10:13], v[172:175], v[220:223], v[10:13]
	v_mfma_f32_16x16x32_bf16 v[14:17], v[172:175], v[224:227], v[14:17]
	s_waitcnt lgkmcnt(2)
	v_mfma_f32_16x16x32_bf16 v[18:21], v[176:179], v[212:215], v[18:21]
	v_mfma_f32_16x16x32_bf16 v[22:25], v[176:179], v[216:219], v[22:25]
	v_mfma_f32_16x16x32_bf16 v[26:29], v[176:179], v[220:223], v[26:29]
	v_mfma_f32_16x16x32_bf16 v[30:33], v[176:179], v[224:227], v[30:33]
	s_waitcnt lgkmcnt(1)
	v_mfma_f32_16x16x32_bf16 v[34:37], v[180:183], v[212:215], v[34:37]
	v_mfma_f32_16x16x32_bf16 v[38:41], v[180:183], v[216:219], v[38:41]
	v_mfma_f32_16x16x32_bf16 v[42:45], v[180:183], v[220:223], v[42:45]
	v_mfma_f32_16x16x32_bf16 v[46:49], v[180:183], v[224:227], v[46:49]
	s_waitcnt lgkmcnt(0)
	v_mfma_f32_16x16x32_bf16 v[50:53], v[184:187], v[212:215], v[50:53]
	v_mfma_f32_16x16x32_bf16 v[54:57], v[184:187], v[216:219], v[54:57]
	v_mfma_f32_16x16x32_bf16 v[58:61], v[184:187], v[220:223], v[58:61]
	v_mfma_f32_16x16x32_bf16 v[62:65], v[184:187], v[224:227], v[62:65]
	s_setprio 0
	s_waitcnt vmcnt(6)
	s_barrier
	s_setprio 3
	v_add_u32_e32 v236, s42, v232
	v_add_u32_e32 v237, s42, v233
	ds_read_b128 v[188:191], v236
	ds_read_b128 v[196:199], v236 offset:2048
	ds_read_b128 v[200:203], v236 offset:4096
	ds_read_b128 v[204:207], v236 offset:6144
	ds_read_b128 v[212:215], v237
	ds_read_b128 v[216:219], v237 offset:2048
	ds_read_b128 v[220:223], v237 offset:4096
	ds_read_b128 v[224:227], v237 offset:6144
	s_add_i32 m0, s51, 0x6000
	s_nop 0
	global_load_lds_dwordx4 v229, s[46:47]
	s_add_i32 m0, s51, 0x6400
	s_nop 0
	global_load_lds_dwordx4 v231, s[46:47]
	s_add_i32 m0, s51, 0x8000
	s_nop 0
	global_load_lds_dwordx4 v228, s[48:49]
	s_add_i32 m0, s51, 0x8400
	s_nop 0
	global_load_lds_dwordx4 v230, s[48:49]
	s_add_i32 m0, s51, 0xa000
	s_nop 0
	global_load_lds_dwordx4 v229, s[48:49]
	s_add_i32 m0, s51, 0xa400
	s_nop 0
	global_load_lds_dwordx4 v231, s[48:49]
	s_waitcnt lgkmcnt(7)
	s_setprio 1
	v_mfma_f32_16x16x32_bf16 v[66:69], v[136:139], v[188:191], v[66:69]
	v_mfma_f32_16x16x32_bf16 v[82:85], v[140:143], v[188:191], v[82:85]
	v_mfma_f32_16x16x32_bf16 v[98:101], v[144:147], v[188:191], v[98:101]
	v_mfma_f32_16x16x32_bf16 v[114:117], v[148:151], v[188:191], v[114:117]
	s_waitcnt lgkmcnt(6)
	v_mfma_f32_16x16x32_bf16 v[70:73], v[136:139], v[196:199], v[70:73]
	v_mfma_f32_16x16x32_bf16 v[86:89], v[140:143], v[196:199], v[86:89]
	v_mfma_f32_16x16x32_bf16 v[102:105], v[144:147], v[196:199], v[102:105]
	v_mfma_f32_16x16x32_bf16 v[118:121], v[148:151], v[196:199], v[118:121]
	s_waitcnt lgkmcnt(5)
	v_mfma_f32_16x16x32_bf16 v[74:77], v[136:139], v[200:203], v[74:77]
	v_mfma_f32_16x16x32_bf16 v[90:93], v[140:143], v[200:203], v[90:93]
	v_mfma_f32_16x16x32_bf16 v[106:109], v[144:147], v[200:203], v[106:109]
	v_mfma_f32_16x16x32_bf16 v[122:125], v[148:151], v[200:203], v[122:125]
	s_waitcnt lgkmcnt(4)
	v_mfma_f32_16x16x32_bf16 v[78:81], v[136:139], v[204:207], v[78:81]
	v_mfma_f32_16x16x32_bf16 v[94:97], v[140:143], v[204:207], v[94:97]
	v_mfma_f32_16x16x32_bf16 v[110:113], v[144:147], v[204:207], v[110:113]
	v_mfma_f32_16x16x32_bf16 v[126:129], v[148:151], v[204:207], v[126:129]
	s_waitcnt lgkmcnt(3)
	v_mfma_f32_16x16x32_bf16 v[66:69], v[172:175], v[212:215], v[66:69]
	v_mfma_f32_16x16x32_bf16 v[82:85], v[176:179], v[212:215], v[82:85]
	v_mfma_f32_16x16x32_bf16 v[98:101], v[180:183], v[212:215], v[98:101]
	v_mfma_f32_16x16x32_bf16 v[114:117], v[184:187], v[212:215], v[114:117]
	s_waitcnt lgkmcnt(2)
	v_mfma_f32_16x16x32_bf16 v[70:73], v[172:175], v[216:219], v[70:73]
	v_mfma_f32_16x16x32_bf16 v[86:89], v[176:179], v[216:219], v[86:89]
	v_mfma_f32_16x16x32_bf16 v[102:105], v[180:183], v[216:219], v[102:105]
	v_mfma_f32_16x16x32_bf16 v[118:121], v[184:187], v[216:219], v[118:121]
	s_waitcnt lgkmcnt(1)
	v_mfma_f32_16x16x32_bf16 v[74:77], v[172:175], v[220:223], v[74:77]
	v_mfma_f32_16x16x32_bf16 v[90:93], v[176:179], v[220:223], v[90:93]
	v_mfma_f32_16x16x32_bf16 v[106:109], v[180:183], v[220:223], v[106:109]
	v_mfma_f32_16x16x32_bf16 v[122:125], v[184:187], v[220:223], v[122:125]
	s_waitcnt lgkmcnt(0)
	v_mfma_f32_16x16x32_bf16 v[78:81], v[172:175], v[224:227], v[78:81]
	v_mfma_f32_16x16x32_bf16 v[94:97], v[176:179], v[224:227], v[94:97]
	v_mfma_f32_16x16x32_bf16 v[110:113], v[180:183], v[224:227], v[110:113]
	v_mfma_f32_16x16x32_bf16 v[126:129], v[184:187], v[224:227], v[126:129]
	s_setprio 0
	v_add_u32_e32 v228, 0x80, v228
	v_add_u32_e32 v229, 0x80, v229
	v_add_u32_e32 v230, 0x80, v230
	v_add_u32_e32 v231, 0x80, v231
	s_waitcnt vmcnt(4)
	s_barrier
	s_add_i32 s52, s52, 1
	s_cmp_lt_u32 s52, 10
	s_cbranch_scc1 .Lin2_loop
	s_setprio 3
	v_add_u32_e32 v234, s22, v232
	v_add_u32_e32 v236, s28, v232
	v_add_u32_e32 v235, s22, v233
	v_add_u32_e32 v237, s28, v233
	ds_read_b128 v[136:139], v234
	ds_read_b128 v[188:191], v236
	ds_read_b128 v[196:199], v236 offset:2048
	ds_read_b128 v[200:203], v236 offset:4096
	ds_read_b128 v[204:207], v236 offset:6144
	ds_read_b128 v[140:143], v234 offset:2048
	ds_read_b128 v[144:147], v234 offset:4096
	ds_read_b128 v[148:151], v234 offset:6144
	ds_read_b128 v[172:175], v235
	ds_read_b128 v[212:215], v237
	ds_read_b128 v[216:219], v237 offset:2048
	ds_read_b128 v[220:223], v237 offset:4096
	ds_read_b128 v[224:227], v237 offset:6144
	ds_read_b128 v[176:179], v235 offset:2048
	ds_read_b128 v[180:183], v235 offset:4096
	ds_read_b128 v[184:187], v235 offset:6144
	s_add_i32 m0, s51, 0xc000
	s_nop 0
	global_load_lds_dwordx4 v228, s[44:45]
	s_add_i32 m0, s51, 0xc400
	s_nop 0
	global_load_lds_dwordx4 v230, s[44:45]
	s_add_i32 m0, s51, 0xe000
	s_nop 0
	global_load_lds_dwordx4 v229, s[44:45]
	s_add_i32 m0, s51, 0xe400
	s_nop 0
	global_load_lds_dwordx4 v231, s[44:45]
	s_add_i32 m0, s51, 0x10000
	s_nop 0
	global_load_lds_dwordx4 v228, s[46:47]
	s_add_i32 m0, s51, 0x10400
	s_nop 0
	global_load_lds_dwordx4 v230, s[46:47]
	s_waitcnt lgkmcnt(11)
	s_setprio 1
	v_mfma_f32_16x16x32_bf16 v[2:5], v[136:139], v[188:191], v[2:5]
	v_mfma_f32_16x16x32_bf16 v[6:9], v[136:139], v[196:199], v[6:9]
	v_mfma_f32_16x16x32_bf16 v[10:13], v[136:139], v[200:203], v[10:13]
	v_mfma_f32_16x16x32_bf16 v[14:17], v[136:139], v[204:207], v[14:17]
	s_waitcnt lgkmcnt(10)
	v_mfma_f32_16x16x32_bf16 v[18:21], v[140:143], v[188:191], v[18:21]
	v_mfma_f32_16x16x32_bf16 v[22:25], v[140:143], v[196:199], v[22:25]
	v_mfma_f32_16x16x32_bf16 v[26:29], v[140:143], v[200:203], v[26:29]
	v_mfma_f32_16x16x32_bf16 v[30:33], v[140:143], v[204:207], v[30:33]
	s_waitcnt lgkmcnt(9)
	v_mfma_f32_16x16x32_bf16 v[34:37], v[144:147], v[188:191], v[34:37]
	v_mfma_f32_16x16x32_bf16 v[38:41], v[144:147], v[196:199], v[38:41]
	v_mfma_f32_16x16x32_bf16 v[42:45], v[144:147], v[200:203], v[42:45]
	v_mfma_f32_16x16x32_bf16 v[46:49], v[144:147], v[204:207], v[46:49]
	s_waitcnt lgkmcnt(8)
	v_mfma_f32_16x16x32_bf16 v[50:53], v[148:151], v[188:191], v[50:53]
	v_mfma_f32_16x16x32_bf16 v[54:57], v[148:151], v[196:199], v[54:57]
	v_mfma_f32_16x16x32_bf16 v[58:61], v[148:151], v[200:203], v[58:61]
	v_mfma_f32_16x16x32_bf16 v[62:65], v[148:151], v[204:207], v[62:65]
	s_waitcnt lgkmcnt(3)
	v_mfma_f32_16x16x32_bf16 v[2:5], v[172:175], v[212:215], v[2:5]
	v_mfma_f32_16x16x32_bf16 v[6:9], v[172:175], v[216:219], v[6:9]
	v_mfma_f32_16x16x32_bf16 v[10:13], v[172:175], v[220:223], v[10:13]
	v_mfma_f32_16x16x32_bf16 v[14:17], v[172:175], v[224:227], v[14:17]
	s_waitcnt lgkmcnt(2)
	v_mfma_f32_16x16x32_bf16 v[18:21], v[176:179], v[212:215], v[18:21]
	v_mfma_f32_16x16x32_bf16 v[22:25], v[176:179], v[216:219], v[22:25]
	v_mfma_f32_16x16x32_bf16 v[26:29], v[176:179], v[220:223], v[26:29]
	v_mfma_f32_16x16x32_bf16 v[30:33], v[176:179], v[224:227], v[30:33]
	s_waitcnt lgkmcnt(1)
	v_mfma_f32_16x16x32_bf16 v[34:37], v[180:183], v[212:215], v[34:37]
	v_mfma_f32_16x16x32_bf16 v[38:41], v[180:183], v[216:219], v[38:41]
	v_mfma_f32_16x16x32_bf16 v[42:45], v[180:183], v[220:223], v[42:45]
	v_mfma_f32_16x16x32_bf16 v[46:49], v[180:183], v[224:227], v[46:49]
	s_waitcnt lgkmcnt(0)
	v_mfma_f32_16x16x32_bf16 v[50:53], v[184:187], v[212:215], v[50:53]
	v_mfma_f32_16x16x32_bf16 v[54:57], v[184:187], v[216:219], v[54:57]
	v_mfma_f32_16x16x32_bf16 v[58:61], v[184:187], v[220:223], v[58:61]
	v_mfma_f32_16x16x32_bf16 v[62:65], v[184:187], v[224:227], v[62:65]
	s_setprio 0
	s_waitcnt vmcnt(6)
	s_barrier
	s_setprio 3
	v_add_u32_e32 v236, s40, v232
	v_add_u32_e32 v237, s40, v233
	ds_read_b128 v[188:191], v236
	ds_read_b128 v[196:199], v236 offset:2048
	ds_read_b128 v[200:203], v236 offset:4096
	ds_read_b128 v[204:207], v236 offset:6144
	ds_read_b128 v[212:215], v237
	ds_read_b128 v[216:219], v237 offset:2048
	ds_read_b128 v[220:223], v237 offset:4096
	ds_read_b128 v[224:227], v237 offset:6144
	s_mov_b32 m0, s51
	s_nop 0
	global_load_lds_dwordx4 v229, s[46:47]
	s_add_i32 m0, s51, 0x400
	s_nop 0
	global_load_lds_dwordx4 v231, s[46:47]
	s_add_i32 m0, s51, 0x2000
	s_nop 0
	global_load_lds_dwordx4 v228, s[48:49]
	s_add_i32 m0, s51, 0x2400
	s_nop 0
	global_load_lds_dwordx4 v230, s[48:49]
	s_add_i32 m0, s51, 0x4000
	s_nop 0
	global_load_lds_dwordx4 v229, s[48:49]
	s_add_i32 m0, s51, 0x4400
	s_nop 0
	global_load_lds_dwordx4 v231, s[48:49]
	s_waitcnt lgkmcnt(7)
	s_setprio 1
	v_mfma_f32_16x16x32_bf16 v[66:69], v[136:139], v[188:191], v[66:69]
	v_mfma_f32_16x16x32_bf16 v[82:85], v[140:143], v[188:191], v[82:85]
	v_mfma_f32_16x16x32_bf16 v[98:101], v[144:147], v[188:191], v[98:101]
	v_mfma_f32_16x16x32_bf16 v[114:117], v[148:151], v[188:191], v[114:117]
	s_waitcnt lgkmcnt(6)
	v_mfma_f32_16x16x32_bf16 v[70:73], v[136:139], v[196:199], v[70:73]
	v_mfma_f32_16x16x32_bf16 v[86:89], v[140:143], v[196:199], v[86:89]
	v_mfma_f32_16x16x32_bf16 v[102:105], v[144:147], v[196:199], v[102:105]
	v_mfma_f32_16x16x32_bf16 v[118:121], v[148:151], v[196:199], v[118:121]
	s_waitcnt lgkmcnt(5)
	v_mfma_f32_16x16x32_bf16 v[74:77], v[136:139], v[200:203], v[74:77]
	v_mfma_f32_16x16x32_bf16 v[90:93], v[140:143], v[200:203], v[90:93]
	v_mfma_f32_16x16x32_bf16 v[106:109], v[144:147], v[200:203], v[106:109]
	v_mfma_f32_16x16x32_bf16 v[122:125], v[148:151], v[200:203], v[122:125]
	s_waitcnt lgkmcnt(4)
	v_mfma_f32_16x16x32_bf16 v[78:81], v[136:139], v[204:207], v[78:81]
	v_mfma_f32_16x16x32_bf16 v[94:97], v[140:143], v[204:207], v[94:97]
	v_mfma_f32_16x16x32_bf16 v[110:113], v[144:147], v[204:207], v[110:113]
	v_mfma_f32_16x16x32_bf16 v[126:129], v[148:151], v[204:207], v[126:129]
	s_waitcnt lgkmcnt(3)
	v_mfma_f32_16x16x32_bf16 v[66:69], v[172:175], v[212:215], v[66:69]
	v_mfma_f32_16x16x32_bf16 v[82:85], v[176:179], v[212:215], v[82:85]
	v_mfma_f32_16x16x32_bf16 v[98:101], v[180:183], v[212:215], v[98:101]
	v_mfma_f32_16x16x32_bf16 v[114:117], v[184:187], v[212:215], v[114:117]
	s_waitcnt lgkmcnt(2)
	v_mfma_f32_16x16x32_bf16 v[70:73], v[172:175], v[216:219], v[70:73]
	v_mfma_f32_16x16x32_bf16 v[86:89], v[176:179], v[216:219], v[86:89]
	v_mfma_f32_16x16x32_bf16 v[102:105], v[180:183], v[216:219], v[102:105]
	v_mfma_f32_16x16x32_bf16 v[118:121], v[184:187], v[216:219], v[118:121]
	s_waitcnt lgkmcnt(1)
	v_mfma_f32_16x16x32_bf16 v[74:77], v[172:175], v[220:223], v[74:77]
	v_mfma_f32_16x16x32_bf16 v[90:93], v[176:179], v[220:223], v[90:93]
	v_mfma_f32_16x16x32_bf16 v[106:109], v[180:183], v[220:223], v[106:109]
	v_mfma_f32_16x16x32_bf16 v[122:125], v[184:187], v[220:223], v[122:125]
	s_waitcnt lgkmcnt(0)
	v_mfma_f32_16x16x32_bf16 v[78:81], v[172:175], v[224:227], v[78:81]
	v_mfma_f32_16x16x32_bf16 v[94:97], v[176:179], v[224:227], v[94:97]
	v_mfma_f32_16x16x32_bf16 v[110:113], v[180:183], v[224:227], v[110:113]
	v_mfma_f32_16x16x32_bf16 v[126:129], v[184:187], v[224:227], v[126:129]
	s_setprio 0
	v_add_u32_e32 v228, 0x80, v228
	v_add_u32_e32 v229, 0x80, v229
	v_add_u32_e32 v230, 0x80, v230
	v_add_u32_e32 v231, 0x80, v231
	s_waitcnt vmcnt(4)
	s_barrier
	s_setprio 3
	v_add_u32_e32 v234, s23, v232
	v_add_u32_e32 v236, s29, v232
	v_add_u32_e32 v235, s23, v233
	v_add_u32_e32 v237, s29, v233
	ds_read_b128 v[136:139], v234
	ds_read_b128 v[188:191], v236
	ds_read_b128 v[196:199], v236 offset:2048
	ds_read_b128 v[200:203], v236 offset:4096
	ds_read_b128 v[204:207], v236 offset:6144
	ds_read_b128 v[140:143], v234 offset:2048
	ds_read_b128 v[144:147], v234 offset:4096
	ds_read_b128 v[148:151], v234 offset:6144
	ds_read_b128 v[172:175], v235
	ds_read_b128 v[212:215], v237
	ds_read_b128 v[216:219], v237 offset:2048
	ds_read_b128 v[220:223], v237 offset:4096
	ds_read_b128 v[224:227], v237 offset:6144
	ds_read_b128 v[176:179], v235 offset:2048
	ds_read_b128 v[180:183], v235 offset:4096
	ds_read_b128 v[184:187], v235 offset:6144
	s_waitcnt lgkmcnt(11)
	s_setprio 1
	v_mfma_f32_16x16x32_bf16 v[2:5], v[136:139], v[188:191], v[2:5]
	v_mfma_f32_16x16x32_bf16 v[6:9], v[136:139], v[196:199], v[6:9]
	v_mfma_f32_16x16x32_bf16 v[10:13], v[136:139], v[200:203], v[10:13]
	v_mfma_f32_16x16x32_bf16 v[14:17], v[136:139], v[204:207], v[14:17]
	s_waitcnt lgkmcnt(10)
	v_mfma_f32_16x16x32_bf16 v[18:21], v[140:143], v[188:191], v[18:21]
	v_mfma_f32_16x16x32_bf16 v[22:25], v[140:143], v[196:199], v[22:25]
	v_mfma_f32_16x16x32_bf16 v[26:29], v[140:143], v[200:203], v[26:29]
	v_mfma_f32_16x16x32_bf16 v[30:33], v[140:143], v[204:207], v[30:33]
	s_waitcnt lgkmcnt(9)
	v_mfma_f32_16x16x32_bf16 v[34:37], v[144:147], v[188:191], v[34:37]
	v_mfma_f32_16x16x32_bf16 v[38:41], v[144:147], v[196:199], v[38:41]
	v_mfma_f32_16x16x32_bf16 v[42:45], v[144:147], v[200:203], v[42:45]
	v_mfma_f32_16x16x32_bf16 v[46:49], v[144:147], v[204:207], v[46:49]
	s_waitcnt lgkmcnt(8)
	v_mfma_f32_16x16x32_bf16 v[50:53], v[148:151], v[188:191], v[50:53]
	v_mfma_f32_16x16x32_bf16 v[54:57], v[148:151], v[196:199], v[54:57]
	v_mfma_f32_16x16x32_bf16 v[58:61], v[148:151], v[200:203], v[58:61]
	v_mfma_f32_16x16x32_bf16 v[62:65], v[148:151], v[204:207], v[62:65]
	s_waitcnt lgkmcnt(3)
	v_mfma_f32_16x16x32_bf16 v[2:5], v[172:175], v[212:215], v[2:5]
	v_mfma_f32_16x16x32_bf16 v[6:9], v[172:175], v[216:219], v[6:9]
	v_mfma_f32_16x16x32_bf16 v[10:13], v[172:175], v[220:223], v[10:13]
	v_mfma_f32_16x16x32_bf16 v[14:17], v[172:175], v[224:227], v[14:17]
	s_waitcnt lgkmcnt(2)
	v_mfma_f32_16x16x32_bf16 v[18:21], v[176:179], v[212:215], v[18:21]
	v_mfma_f32_16x16x32_bf16 v[22:25], v[176:179], v[216:219], v[22:25]
	v_mfma_f32_16x16x32_bf16 v[26:29], v[176:179], v[220:223], v[26:29]
	v_mfma_f32_16x16x32_bf16 v[30:33], v[176:179], v[224:227], v[30:33]
	s_waitcnt lgkmcnt(1)
	v_mfma_f32_16x16x32_bf16 v[34:37], v[180:183], v[212:215], v[34:37]
	v_mfma_f32_16x16x32_bf16 v[38:41], v[180:183], v[216:219], v[38:41]
	v_mfma_f32_16x16x32_bf16 v[42:45], v[180:183], v[220:223], v[42:45]
	v_mfma_f32_16x16x32_bf16 v[46:49], v[180:183], v[224:227], v[46:49]
	s_waitcnt lgkmcnt(0)
	v_mfma_f32_16x16x32_bf16 v[50:53], v[184:187], v[212:215], v[50:53]
	v_mfma_f32_16x16x32_bf16 v[54:57], v[184:187], v[216:219], v[54:57]
	v_mfma_f32_16x16x32_bf16 v[58:61], v[184:187], v[220:223], v[58:61]
	v_mfma_f32_16x16x32_bf16 v[62:65], v[184:187], v[224:227], v[62:65]
	s_setprio 0
	s_waitcnt vmcnt(0)
	s_barrier
	s_setprio 3
	v_add_u32_e32 v236, s41, v232
	v_add_u32_e32 v237, s41, v233
	ds_read_b128 v[188:191], v236
	ds_read_b128 v[196:199], v236 offset:2048
	ds_read_b128 v[200:203], v236 offset:4096
	ds_read_b128 v[204:207], v236 offset:6144
	ds_read_b128 v[212:215], v237
	ds_read_b128 v[216:219], v237 offset:2048
	ds_read_b128 v[220:223], v237 offset:4096
	ds_read_b128 v[224:227], v237 offset:6144
	s_waitcnt lgkmcnt(7)
	s_setprio 1
	v_mfma_f32_16x16x32_bf16 v[66:69], v[136:139], v[188:191], v[66:69]
	v_mfma_f32_16x16x32_bf16 v[82:85], v[140:143], v[188:191], v[82:85]
	v_mfma_f32_16x16x32_bf16 v[98:101], v[144:147], v[188:191], v[98:101]
	v_mfma_f32_16x16x32_bf16 v[114:117], v[148:151], v[188:191], v[114:117]
	s_waitcnt lgkmcnt(6)
	v_mfma_f32_16x16x32_bf16 v[70:73], v[136:139], v[196:199], v[70:73]
	v_mfma_f32_16x16x32_bf16 v[86:89], v[140:143], v[196:199], v[86:89]
	v_mfma_f32_16x16x32_bf16 v[102:105], v[144:147], v[196:199], v[102:105]
	v_mfma_f32_16x16x32_bf16 v[118:121], v[148:151], v[196:199], v[118:121]
	s_waitcnt lgkmcnt(5)
	v_mfma_f32_16x16x32_bf16 v[74:77], v[136:139], v[200:203], v[74:77]
	v_mfma_f32_16x16x32_bf16 v[90:93], v[140:143], v[200:203], v[90:93]
	v_mfma_f32_16x16x32_bf16 v[106:109], v[144:147], v[200:203], v[106:109]
	v_mfma_f32_16x16x32_bf16 v[122:125], v[148:151], v[200:203], v[122:125]
	s_waitcnt lgkmcnt(4)
	v_mfma_f32_16x16x32_bf16 v[78:81], v[136:139], v[204:207], v[78:81]
	v_mfma_f32_16x16x32_bf16 v[94:97], v[140:143], v[204:207], v[94:97]
	v_mfma_f32_16x16x32_bf16 v[110:113], v[144:147], v[204:207], v[110:113]
	v_mfma_f32_16x16x32_bf16 v[126:129], v[148:151], v[204:207], v[126:129]
	s_waitcnt lgkmcnt(3)
	v_mfma_f32_16x16x32_bf16 v[66:69], v[172:175], v[212:215], v[66:69]
	v_mfma_f32_16x16x32_bf16 v[82:85], v[176:179], v[212:215], v[82:85]
	v_mfma_f32_16x16x32_bf16 v[98:101], v[180:183], v[212:215], v[98:101]
	v_mfma_f32_16x16x32_bf16 v[114:117], v[184:187], v[212:215], v[114:117]
	s_waitcnt lgkmcnt(2)
	v_mfma_f32_16x16x32_bf16 v[70:73], v[172:175], v[216:219], v[70:73]
	v_mfma_f32_16x16x32_bf16 v[86:89], v[176:179], v[216:219], v[86:89]
	v_mfma_f32_16x16x32_bf16 v[102:105], v[180:183], v[216:219], v[102:105]
	v_mfma_f32_16x16x32_bf16 v[118:121], v[184:187], v[216:219], v[118:121]
	s_waitcnt lgkmcnt(1)
	v_mfma_f32_16x16x32_bf16 v[74:77], v[172:175], v[220:223], v[74:77]
	v_mfma_f32_16x16x32_bf16 v[90:93], v[176:179], v[220:223], v[90:93]
	v_mfma_f32_16x16x32_bf16 v[106:109], v[180:183], v[220:223], v[106:109]
	v_mfma_f32_16x16x32_bf16 v[122:125], v[184:187], v[220:223], v[122:125]
	s_waitcnt lgkmcnt(0)
	v_mfma_f32_16x16x32_bf16 v[78:81], v[172:175], v[224:227], v[78:81]
	v_mfma_f32_16x16x32_bf16 v[94:97], v[176:179], v[224:227], v[94:97]
	v_mfma_f32_16x16x32_bf16 v[110:113], v[180:183], v[224:227], v[110:113]
	v_mfma_f32_16x16x32_bf16 v[126:129], v[184:187], v[224:227], v[126:129]
	s_setprio 0
	s_nop 7
	s_barrier
	v_and_b32_e32 v241, 63, v131
	v_and_b32_e32 v242, 15, v241
	v_lshrrev_b32_e32 v243, 4, v241
	s_lshr_b32 s56, s50, 1
	s_and_b32 s57, s50, 1
	s_mul_i32 s0, s56, 64*272
	s_lshl_b32 s52, s57, 7
	s_add_i32 s0, s0, s52
	s_add_i32 s0, s0, 16
	v_mul_u32_u24_e32 v244, 1088, v243
	v_lshl_add_u32 v244, v242, 1, v244
	v_add_u32_e32 v229, s0, v244
	s_mul_i32 s0, s57, 64*272
	s_lshl_b32 s52, s56, 7
	s_add_i32 s0, s0, s52
	s_add_i32 s0, s0, 16
	v_mul_u32_u24_e32 v244, 272, v242
	v_lshl_add_u32 v244, v243, 3, v244
	v_add_u32_e32 v230, s0, v244
	s_lshl_b32 s0, s57, 9
	s_lshl_b32 s52, s56, 8
	s_add_i32 s0, s0, s52
	s_add_i32 s0, s0, 16+34816
	v_lshl_add_u32 v228, v243, 4, s0
	s_lshl_b32 s0, s57, 8
	v_lshl_add_u32 v234, v242, 2, s0
	v_lshrrev_b32_e32 v241, 4, v131
	v_and_b32_e32 v242, 15, v131
	v_lshlrev_b32_e32 v242, 4, v242
	v_mul_u32_u24_e32 v243, 272, v241
	v_add3_u32 v231, v243, v242, 16
	s_movk_i32 s0, 0x2500
	v_mad_u32_u24 v232, v241, s0, v242
	v_lshl_add_u32 v233, v241, 12, v242
	s_lshr_b32 s52, s54, 7
	s_mov_b32 s57, 0
	s_movk_i32 s56, 0x170
	s_cmp_lt_u32 s52, 8
	s_cbranch_scc0 .Lin2_t1_v1
	s_mov_b32 s57, 1
	s_movk_i32 s56, 0x28
	s_branch .Lin2_t1_vd
